# epilogue de-serialisation: the six [rows][1024] tile-store ladders (ffn_down, w_o, branch; MT8 and ctx MT4) read 8 LDS chunks in flight with counted waits instead of read-wait-store one at a time
# baseline (speedup 1.0000x reference)
.LBB0_121:
	v_lshl_add_u32 v83, s24, 14, v80
	v_add_u32_e32 v90, 0x1000, v83
	v_readfirstlane_b32 s26, v83
	s_waitcnt vmcnt(4) lgkmcnt(0)
	s_barrier
	v_add_u32_e32 v89, 0x2000, v83
	s_mov_b32 m0, s26
	v_readfirstlane_b32 s26, v90
	v_lshl_add_u64 v[74:75], v[70:71], 0, s[10:11]
	v_add_u32_e32 v88, 0x3000, v83
	global_load_lds_dwordx4 v[68:69], off
	s_mov_b32 m0, s26
	v_readfirstlane_b32 s26, v89
	v_lshl_add_u64 v[84:85], v[74:75], 0, s[36:37]
	global_load_lds_dwordx4 v[66:67], off
	s_mov_b32 m0, s26
	v_readfirstlane_b32 s26, v88
	global_load_lds_dwordx4 v[84:85], off
	s_mov_b32 m0, s26
	s_lshl_b32 s26, s25, 14
	v_lshl_add_u64 v[86:87], v[74:75], 0, s[40:41]
	s_add_i32 s26, s26, 0
	global_load_lds_dwordx4 v[86:87], off
	v_add3_u32 v83, s26, v82, v0
	ds_read_b128 v[84:87], v83 offset:8192
	ds_read_b128 v[88:91], v83 offset:9216
	ds_read_b128 v[92:95], v83 offset:10240
	ds_read_b128 v[96:99], v83 offset:11264
	v_add3_u32 v83, s26, v81, v0
	s_add_i32 s26, s25, 1
	ds_read_b128 v[100:103], v83
	ds_read_b128 v[104:107], v83 offset:1024
	ds_read_b128 v[108:111], v83 offset:2048
	ds_read_b128 v[112:115], v83 offset:3072
	s_cmp_lg_u32 s25, 2
	s_cselect_b32 s25, s26, 0
	s_add_i32 s26, s24, 1
	s_cmp_lg_u32 s24, 2
	s_cselect_b32 s24, s26, 0
	v_lshl_add_u32 v83, s24, 14, v80
	s_waitcnt lgkmcnt(0)
	s_setprio 1
	v_mfma_f32_16x16x32_bf16 v[62:65], v[84:87], v[100:103], v[62:65]
	v_readfirstlane_b32 s26, v83
	v_lshl_add_u64 v[78:79], v[68:69], 0, 64
	s_setprio 0
	s_waitcnt vmcnt(4) lgkmcnt(0)
	s_setprio 1
	v_mfma_f32_16x16x32_bf16 v[46:49], v[84:87], v[104:107], v[46:49]
	s_setprio 0
	s_barrier
	s_mov_b32 m0, s26
	s_setprio 1
	v_mfma_f32_16x16x32_bf16 v[30:33], v[84:87], v[108:111], v[30:33]
	v_lshl_add_u64 v[76:77], v[66:67], 0, 64
	global_load_lds_dwordx4 v[78:79], off
	v_mfma_f32_16x16x32_bf16 v[14:17], v[84:87], v[112:115], v[14:17]
	v_add_u32_e32 v86, 0x1000, v83
	v_add_u32_e32 v85, 0x2000, v83
	v_readfirstlane_b32 s26, v86
	v_add_u32_e32 v84, 0x3000, v83
	s_mov_b32 m0, s26
	v_readfirstlane_b32 s26, v85
	v_lshl_add_u64 v[72:73], v[74:75], 0, s[58:59]
	v_lshl_add_u64 v[74:75], v[74:75], 0, s[82:83]
	global_load_lds_dwordx4 v[76:77], off
	s_mov_b32 m0, s26
	v_readfirstlane_b32 s26, v84
	global_load_lds_dwordx4 v[74:75], off
	s_mov_b32 m0, s26
	s_lshl_b32 s26, s25, 14
	global_load_lds_dwordx4 v[72:73], off
	s_add_i32 s26, s26, 0
	v_add3_u32 v83, s26, v82, v0
	v_mfma_f32_16x16x32_bf16 v[58:61], v[88:91], v[100:103], v[58:61]
	v_lshl_add_u64 v[68:69], v[68:69], 0, s[78:79]
	v_lshl_add_u64 v[66:67], v[66:67], 0, s[78:79]
	v_mfma_f32_16x16x32_bf16 v[42:45], v[88:91], v[104:107], v[42:45]
	v_mfma_f32_16x16x32_bf16 v[26:29], v[88:91], v[108:111], v[26:29]
	v_mfma_f32_16x16x32_bf16 v[10:13], v[88:91], v[112:115], v[10:13]
	s_setprio 0
	ds_read_b128 v[72:75], v83 offset:8192
	ds_read_b128 v[76:79], v83 offset:9216
	ds_read_b128 v[84:87], v83 offset:10240
	ds_read_b128 v[88:91], v83 offset:11264
	v_add3_u32 v83, s26, v81, v0
	s_add_i32 s26, s25, 1
	s_setprio 1
	v_mfma_f32_16x16x32_bf16 v[54:57], v[92:95], v[100:103], v[54:57]
	s_cmp_lg_u32 s25, 2
	s_cselect_b32 s25, s26, 0
	s_add_i32 s26, s24, 1
	v_mfma_f32_16x16x32_bf16 v[50:53], v[96:99], v[100:103], v[50:53]
	s_cmp_lg_u32 s24, 2
	s_cselect_b32 s24, s26, 0
	s_add_u32 s10, s10, 0x80
	v_mfma_f32_16x16x32_bf16 v[38:41], v[92:95], v[104:107], v[38:41]
	s_addc_u32 s11, s11, 0
	s_cmpk_eq_i32 s10, 0x1580
	v_mfma_f32_16x16x32_bf16 v[34:37], v[96:99], v[104:107], v[34:37]
	v_mfma_f32_16x16x32_bf16 v[22:25], v[92:95], v[108:111], v[22:25]
	v_mfma_f32_16x16x32_bf16 v[18:21], v[96:99], v[108:111], v[18:21]
	v_mfma_f32_16x16x32_bf16 v[6:9], v[92:95], v[112:115], v[6:9]
	v_mfma_f32_16x16x32_bf16 v[2:5], v[96:99], v[112:115], v[2:5]
	s_setprio 0
	ds_read_b128 v[92:95], v83
	ds_read_b128 v[96:99], v83 offset:1024
	ds_read_b128 v[100:103], v83 offset:2048
	ds_read_b128 v[104:107], v83 offset:3072
	s_waitcnt lgkmcnt(0)
	s_setprio 1
	v_mfma_f32_16x16x32_bf16 v[62:65], v[72:75], v[92:95], v[62:65]
	v_mfma_f32_16x16x32_bf16 v[58:61], v[76:79], v[92:95], v[58:61]
	v_mfma_f32_16x16x32_bf16 v[54:57], v[84:87], v[92:95], v[54:57]
	v_mfma_f32_16x16x32_bf16 v[50:53], v[88:91], v[92:95], v[50:53]
	v_mfma_f32_16x16x32_bf16 v[46:49], v[72:75], v[96:99], v[46:49]
	v_mfma_f32_16x16x32_bf16 v[42:45], v[76:79], v[96:99], v[42:45]
	v_mfma_f32_16x16x32_bf16 v[38:41], v[84:87], v[96:99], v[38:41]
	v_mfma_f32_16x16x32_bf16 v[34:37], v[88:91], v[96:99], v[34:37]
	v_mfma_f32_16x16x32_bf16 v[30:33], v[72:75], v[100:103], v[30:33]
	v_mfma_f32_16x16x32_bf16 v[26:29], v[76:79], v[100:103], v[26:29]
	v_mfma_f32_16x16x32_bf16 v[22:25], v[84:87], v[100:103], v[22:25]
	v_mfma_f32_16x16x32_bf16 v[18:21], v[88:91], v[100:103], v[18:21]
	v_mfma_f32_16x16x32_bf16 v[14:17], v[72:75], v[104:107], v[14:17]
	v_mfma_f32_16x16x32_bf16 v[10:13], v[76:79], v[104:107], v[10:13]
	v_mfma_f32_16x16x32_bf16 v[6:9], v[84:87], v[104:107], v[6:9]
	v_mfma_f32_16x16x32_bf16 v[2:5], v[88:91], v[104:107], v[2:5]
	s_setprio 0
	s_cbranch_scc0 .LBB0_121
	s_waitcnt vmcnt(4) lgkmcnt(0)
	s_barrier
	v_add3_u32 v98, 0, v82, v0
	v_add3_u32 v0, 0, v81, v0
	ds_read_b128 v[66:69], v98 offset:40960
	ds_read_b128 v[70:73], v98 offset:41984
	ds_read_b128 v[74:77], v98 offset:43008
	ds_read_b128 v[82:85], v98 offset:44032
	ds_read_b128 v[78:81], v0 offset:32768
	ds_read_b128 v[86:89], v0 offset:33792
	ds_read_b128 v[90:93], v0 offset:34816
	ds_read_b128 v[94:97], v0 offset:35840
	s_waitcnt vmcnt(0) lgkmcnt(0)
	s_barrier
	s_waitcnt lgkmcnt(0)
	v_mfma_f32_16x16x32_bf16 v[62:65], v[66:69], v[78:81], v[62:65]
	s_lshl_b64 s[10:11], s[2:3], 11
	s_add_u32 s2, s19, s10
	s_addc_u32 s11, s20, s11
	v_mfma_f32_16x16x32_bf16 v[58:61], v[70:73], v[78:81], v[58:61]
	s_lshl_b32 s10, s13, 1
	s_add_u32 s10, s2, s10
	s_mov_b32 s2, 0xfffffc0
	v_mfma_f32_16x16x32_bf16 v[54:57], v[74:77], v[78:81], v[54:57]
	s_addc_u32 s11, s11, 0
	s_mov_b64 s[24:25], 0x3000
	v_mfma_f32_16x16x32_bf16 v[50:53], v[82:85], v[78:81], v[50:53]
	v_mfma_f32_16x16x32_bf16 v[46:49], v[66:69], v[86:89], v[46:49]
	v_mfma_f32_16x16x32_bf16 v[42:45], v[70:73], v[86:89], v[42:45]
	v_mfma_f32_16x16x32_bf16 v[38:41], v[74:77], v[86:89], v[38:41]
	v_mfma_f32_16x16x32_bf16 v[34:37], v[82:85], v[86:89], v[34:37]
	v_mfma_f32_16x16x32_bf16 v[30:33], v[66:69], v[90:93], v[30:33]
	v_mfma_f32_16x16x32_bf16 v[26:29], v[70:73], v[90:93], v[26:29]
	v_mfma_f32_16x16x32_bf16 v[22:25], v[74:77], v[90:93], v[22:25]
	v_mfma_f32_16x16x32_bf16 v[18:21], v[82:85], v[90:93], v[18:21]
	v_mfma_f32_16x16x32_bf16 v[14:17], v[66:69], v[94:97], v[14:17]
	v_mfma_f32_16x16x32_bf16 v[10:13], v[70:73], v[94:97], v[10:13]
	v_mfma_f32_16x16x32_bf16 v[6:9], v[74:77], v[94:97], v[6:9]
	v_mfma_f32_16x16x32_bf16 v[2:5], v[82:85], v[94:97], v[2:5]
	ds_read_b128 v[66:69], v98 offset:8192
	ds_read_b128 v[70:73], v98 offset:9216
	ds_read_b128 v[74:77], v98 offset:10240
	ds_read_b128 v[78:81], v98 offset:11264
	ds_read_b128 v[82:85], v0
	ds_read_b128 v[86:89], v0 offset:1024
	ds_read_b128 v[90:93], v0 offset:2048
	ds_read_b128 v[94:97], v0 offset:3072
	s_waitcnt vmcnt(0) lgkmcnt(0)
	s_barrier
	v_mfma_f32_16x16x32_bf16 v[62:65], v[66:69], v[82:85], v[62:65]
	v_mfma_f32_16x16x32_bf16 v[58:61], v[70:73], v[82:85], v[58:61]
	v_mfma_f32_16x16x32_bf16 v[54:57], v[74:77], v[82:85], v[54:57]
	s_nop 5
	v_cvt_pk_bf16_f32 v62, v62, v63
	v_cvt_pk_bf16_f32 v63, v64, v65
	v_cvt_pk_bf16_f32 v58, v58, v59
	v_mfma_f32_16x16x32_bf16 v[50:53], v[78:81], v[82:85], v[50:53]
	v_cvt_pk_bf16_f32 v59, v60, v61
	v_cvt_pk_bf16_f32 v54, v54, v55
	v_cvt_pk_bf16_f32 v55, v56, v57
	v_mfma_f32_16x16x32_bf16 v[46:49], v[66:69], v[86:89], v[46:49]
	v_mfma_f32_16x16x32_bf16 v[30:33], v[66:69], v[90:93], v[30:33]
	s_nop 2
	v_cvt_pk_bf16_f32 v50, v50, v51
	v_cvt_pk_bf16_f32 v51, v52, v53
	s_nop 1
	v_cvt_pk_bf16_f32 v46, v46, v47
	v_mfma_f32_16x16x32_bf16 v[14:17], v[66:69], v[94:97], v[14:17]
	v_mov_b32_e32 v66, v196
	v_cvt_pk_bf16_f32 v47, v48, v49
	v_mfma_f32_16x16x32_bf16 v[42:45], v[70:73], v[86:89], v[42:45]
	v_and_b32_e32 v67, 15, v66
	v_lshrrev_b32_e32 v68, 1, v66
	v_and_b32_e32 v0, 64, v66
	v_mfma_f32_16x16x32_bf16 v[26:29], v[70:73], v[90:93], v[26:29]
	v_and_or_b32 v69, v68, s2, v67
	v_lshl_add_u32 v0, v0, 1, 0
	v_and_b32_e32 v68, 24, v68
	v_mfma_f32_16x16x32_bf16 v[10:13], v[70:73], v[94:97], v[10:13]
	v_mul_lo_u32 v69, v69, s30
	v_add3_u32 v0, v0, v68, v69
	ds_write2_b64 v0, v[62:63], v[58:59] offset1:4
	v_mfma_f32_16x16x32_bf16 v[6:9], v[74:77], v[94:97], v[6:9]
	ds_write2_b64 v0, v[54:55], v[50:51] offset0:8 offset1:12
	v_cvt_pk_bf16_f32 v42, v42, v43
	v_cvt_pk_bf16_f32 v43, v44, v45
	v_mfma_f32_16x16x32_bf16 v[2:5], v[78:81], v[94:97], v[2:5]
	v_add_u32_e32 v44, 0x1000, v0
	v_cvt_pk_bf16_f32 v26, v26, v27
	v_cvt_pk_bf16_f32 v27, v28, v29
	v_mfma_f32_16x16x32_bf16 v[38:41], v[74:77], v[86:89], v[38:41]
	v_add_u32_e32 v28, 0x2000, v0
	v_cvt_pk_bf16_f32 v14, v14, v15
	v_cvt_pk_bf16_f32 v15, v16, v17
	v_mfma_f32_16x16x32_bf16 v[34:37], v[78:81], v[86:89], v[34:37]
	v_cvt_pk_bf16_f32 v10, v10, v11
	v_cvt_pk_bf16_f32 v11, v12, v13
	v_add_u32_e32 v0, 0x3000, v0
	v_mfma_f32_16x16x32_bf16 v[22:25], v[74:77], v[90:93], v[22:25]
	v_cvt_pk_bf16_f32 v6, v6, v7
	v_cvt_pk_bf16_f32 v7, v8, v9
	v_cvt_pk_bf16_f32 v2, v2, v3
	v_mfma_f32_16x16x32_bf16 v[18:21], v[78:81], v[90:93], v[18:21]
	v_cvt_pk_bf16_f32 v3, v4, v5
	ds_write2_b64 v0, v[14:15], v[10:11] offset0:96 offset1:100
	ds_write2_b64 v0, v[6:7], v[2:3] offset0:104 offset1:108
	v_lshlrev_b32_e32 v0, 4, v67
	v_ashrrev_i32_e32 v2, 4, v66
	v_lshl_add_u64 v[6:7], s[10:11], 0, v[0:1]
	v_add_u32_e32 v0, 0, v0
	v_ashrrev_i32_e32 v3, 31, v2
	v_cvt_pk_bf16_f32 v38, v38, v39
	v_cvt_pk_bf16_f32 v39, v40, v41
	v_cvt_pk_bf16_f32 v34, v34, v35
	v_cvt_pk_bf16_f32 v35, v36, v37
	v_cvt_pk_bf16_f32 v30, v30, v31
	v_cvt_pk_bf16_f32 v31, v32, v33
	v_cvt_pk_bf16_f32 v22, v22, v23
	v_cvt_pk_bf16_f32 v23, v24, v25
	v_cvt_pk_bf16_f32 v18, v18, v19
	v_cvt_pk_bf16_f32 v19, v20, v21
	v_mad_u64_u32 v[4:5], s[10:11], v2, s30, v[0:1]
	v_lshlrev_b64 v[2:3], 11, v[2:3]
	ds_write2_b64 v44, v[46:47], v[42:43] offset0:32 offset1:36
	ds_write2_b64 v44, v[38:39], v[34:35] offset0:40 offset1:44
	ds_write2_b64 v28, v[30:31], v[26:27] offset0:64 offset1:68
	ds_write2_b64 v28, v[22:23], v[18:19] offset0:72 offset1:76
	s_waitcnt lgkmcnt(0)
	s_barrier
	v_lshl_add_u64 v[8:9], v[6:7], 0, v[2:3]
	v_mov_b32_e32 v214, 0x8000
	v_mov_b32_e32 v215, 0
	ds_read_b128 v[216:219], v4
	ds_read_b128 v[228:231], v4 offset:4352
	ds_read_b128 v[232:235], v4 offset:8704
	ds_read_b128 v[236:239], v4 offset:13056
	ds_read_b128 v[240:243], v4 offset:17408
	ds_read_b128 v[244:247], v4 offset:21760
	ds_read_b128 v[248:251], v4 offset:26112
	ds_read_b128 v[252:255], v4 offset:30464
	s_waitcnt lgkmcnt(7)
	global_store_dwordx4 v[8:9], v[216:219], off
	v_lshl_add_u64 v[8:9], v[8:9], 0, v[214:215]
	s_waitcnt lgkmcnt(6)
	global_store_dwordx4 v[8:9], v[228:231], off
	v_lshl_add_u64 v[8:9], v[8:9], 0, v[214:215]
	s_waitcnt lgkmcnt(5)
	global_store_dwordx4 v[8:9], v[232:235], off
	v_lshl_add_u64 v[8:9], v[8:9], 0, v[214:215]
	s_waitcnt lgkmcnt(4)
	global_store_dwordx4 v[8:9], v[236:239], off
	v_lshl_add_u64 v[8:9], v[8:9], 0, v[214:215]
	s_waitcnt lgkmcnt(3)
	global_store_dwordx4 v[8:9], v[240:243], off
	v_lshl_add_u64 v[8:9], v[8:9], 0, v[214:215]
	s_waitcnt lgkmcnt(2)
	global_store_dwordx4 v[8:9], v[244:247], off
	v_lshl_add_u64 v[8:9], v[8:9], 0, v[214:215]
	s_waitcnt lgkmcnt(1)
	global_store_dwordx4 v[8:9], v[248:251], off
	v_lshl_add_u64 v[8:9], v[8:9], 0, v[214:215]
	s_waitcnt lgkmcnt(0)
	global_store_dwordx4 v[8:9], v[252:255], off
	s_mov_b64 s[10:11], 0
	s_barrier

.LBB0_125:
	s_mul_i32 s26, s25, 0x6000
	v_add_u32_e32 v144, s26, v156
	v_add_u32_e32 v132, 0x1000, v144
	v_readfirstlane_b32 s26, v144
	s_waitcnt vmcnt(6) lgkmcnt(0)
	s_barrier
	s_mov_b32 m0, s26
	v_readfirstlane_b32 s26, v132
	v_add_u32_e32 v134, 0x2000, v144
	global_load_lds_dwordx4 v[148:149], off
	s_mov_b32 m0, s26
	v_readfirstlane_b32 s26, v134
	v_add_u32_e32 v136, 0x3000, v144
	global_load_lds_dwordx4 v[150:151], off
	s_mov_b32 m0, s26
	v_readfirstlane_b32 s26, v136
	v_add_u32_e32 v145, 0x4000, v144
	v_lshl_add_u64 v[138:139], v[154:155], 0, s[12:13]
	global_load_lds_dwordx4 v[152:153], off
	s_mov_b32 m0, s26
	v_readfirstlane_b32 s26, v145
	v_lshl_add_u64 v[142:143], v[138:139], 0, s[36:37]
	global_load_lds_dwordx4 v[146:147], off
	s_mov_b32 m0, s26
	v_lshl_add_u64 v[140:141], v[138:139], 0, s[40:41]
	global_load_lds_dwordx4 v[142:143], off
	v_add_u32_e32 v142, 0x5000, v144
	v_lshl_add_u64 v[130:131], v[148:149], 0, 64
	v_readfirstlane_b32 s26, v142
	s_mov_b32 m0, s26
	s_mul_i32 s26, s2, 0x6000
	s_add_i32 s26, s26, 0
	global_load_lds_dwordx4 v[140:141], off
	v_add3_u32 v159, s26, v157, v0
	ds_read_b128 v[142:145], v159 offset:16384
	ds_read_b128 v[160:163], v159 offset:17408
	ds_read_b128 v[164:167], v159 offset:18432
	ds_read_b128 v[168:171], v159 offset:19456
	v_add3_u32 v159, s26, v158, v0
	ds_read_b128 v[172:175], v159
	ds_read_b128 v[176:179], v159 offset:1024
	ds_read_b128 v[180:183], v159 offset:2048
	ds_read_b128 v[184:187], v159 offset:3072
	s_add_i32 s26, s2, 1
	s_waitcnt lgkmcnt(0)
	s_setprio 1
	v_mfma_f32_16x16x32_bf16 v[126:129], v[142:145], v[172:175], v[126:129]
	s_cmp_lg_u32 s2, 2
	s_cselect_b32 s2, s26, 0
	s_add_i32 s26, s25, 1
	v_mfma_f32_16x16x32_bf16 v[122:125], v[160:163], v[172:175], v[122:125]
	s_cmp_lg_u32 s25, 2
	s_cselect_b32 s25, s26, 0
	s_mul_i32 s26, s25, 0x6000
	v_mfma_f32_16x16x32_bf16 v[118:121], v[164:167], v[172:175], v[118:121]
	v_lshl_add_u64 v[132:133], v[150:151], 0, 64
	v_lshl_add_u64 v[134:135], v[152:153], 0, 64
	v_lshl_add_u64 v[136:137], v[146:147], 0, 64
	v_mfma_f32_16x16x32_bf16 v[114:117], v[168:171], v[172:175], v[114:117]
	v_lshl_add_u64 v[140:141], v[138:139], 0, s[82:83]
	v_lshl_add_u64 v[138:139], v[138:139], 0, s[58:59]
	v_lshl_add_u64 v[148:149], v[148:149], 0, s[78:79]
	v_mfma_f32_16x16x32_bf16 v[110:113], v[142:145], v[176:179], v[110:113]
	v_lshl_add_u64 v[150:151], v[150:151], 0, s[78:79]
	v_lshl_add_u64 v[152:153], v[152:153], 0, s[78:79]
	v_lshl_add_u64 v[146:147], v[146:147], 0, s[78:79]
	v_mfma_f32_16x16x32_bf16 v[106:109], v[160:163], v[176:179], v[106:109]
	v_mfma_f32_16x16x32_bf16 v[102:105], v[164:167], v[176:179], v[102:105]
	v_mfma_f32_16x16x32_bf16 v[98:101], v[168:171], v[176:179], v[98:101]
	v_mfma_f32_16x16x32_bf16 v[94:97], v[142:145], v[180:183], v[94:97]
	v_mfma_f32_16x16x32_bf16 v[90:93], v[160:163], v[180:183], v[90:93]
	v_mfma_f32_16x16x32_bf16 v[86:89], v[164:167], v[180:183], v[86:89]
	v_mfma_f32_16x16x32_bf16 v[82:85], v[168:171], v[180:183], v[82:85]
	v_mfma_f32_16x16x32_bf16 v[78:81], v[142:145], v[184:187], v[78:81]
	v_mfma_f32_16x16x32_bf16 v[74:77], v[160:163], v[184:187], v[74:77]
	v_mfma_f32_16x16x32_bf16 v[70:73], v[164:167], v[184:187], v[70:73]
	v_mfma_f32_16x16x32_bf16 v[66:69], v[168:171], v[184:187], v[66:69]
	s_setprio 0
	ds_read_b128 v[172:175], v159 offset:4096
	ds_read_b128 v[176:179], v159 offset:5120
	ds_read_b128 v[180:183], v159 offset:6144
	ds_read_b128 v[184:187], v159 offset:7168
	s_waitcnt vmcnt(6) lgkmcnt(0)
	s_barrier
	s_waitcnt lgkmcnt(0)
	s_setprio 1
	v_mfma_f32_16x16x32_bf16 v[62:65], v[142:145], v[172:175], v[62:65]
	s_setprio 0
	s_setprio 1
	v_mfma_f32_16x16x32_bf16 v[46:49], v[142:145], v[176:179], v[46:49]
	v_mfma_f32_16x16x32_bf16 v[30:33], v[142:145], v[180:183], v[30:33]
	v_mfma_f32_16x16x32_bf16 v[14:17], v[142:145], v[184:187], v[14:17]
	v_add_u32_e32 v142, s26, v156
	s_nop 0
	v_readfirstlane_b32 s26, v142
	s_mov_b32 m0, s26
	v_mfma_f32_16x16x32_bf16 v[58:61], v[160:163], v[172:175], v[58:61]
	global_load_lds_dwordx4 v[130:131], off
	v_add_u32_e32 v130, 0x1000, v142
	v_mfma_f32_16x16x32_bf16 v[54:57], v[164:167], v[172:175], v[54:57]
	v_readfirstlane_b32 s26, v130
	v_add_u32_e32 v130, 0x2000, v142
	s_mov_b32 m0, s26
	v_readfirstlane_b32 s26, v130
	v_add_u32_e32 v130, 0x3000, v142
	global_load_lds_dwordx4 v[132:133], off
	s_mov_b32 m0, s26
	v_readfirstlane_b32 s26, v130
	v_add_u32_e32 v130, 0x4000, v142
	global_load_lds_dwordx4 v[134:135], off
	s_mov_b32 m0, s26
	v_readfirstlane_b32 s26, v130
	v_add_u32_e32 v130, 0x5000, v142
	global_load_lds_dwordx4 v[136:137], off
	s_mov_b32 m0, s26
	v_readfirstlane_b32 s26, v130
	global_load_lds_dwordx4 v[140:141], off
	s_mov_b32 m0, s26
	s_mul_i32 s26, s2, 0x6000
	global_load_lds_dwordx4 v[138:139], off
	s_add_i32 s26, s26, 0
	v_add3_u32 v142, s26, v157, v0
	v_add3_u32 v159, s26, v158, v0
	v_mfma_f32_16x16x32_bf16 v[50:53], v[168:171], v[172:175], v[50:53]
	s_setprio 0
	ds_read_b128 v[130:133], v142 offset:16384
	ds_read_b128 v[134:137], v142 offset:17408
	ds_read_b128 v[138:141], v142 offset:18432
	ds_read_b128 v[142:145], v142 offset:19456
	s_add_i32 s26, s2, 1
	s_cmp_lg_u32 s2, 2
	s_setprio 1
	v_mfma_f32_16x16x32_bf16 v[42:45], v[160:163], v[176:179], v[42:45]
	s_cselect_b32 s2, s26, 0
	s_add_i32 s26, s25, 1
	s_cmp_lg_u32 s25, 2
	v_mfma_f32_16x16x32_bf16 v[38:41], v[164:167], v[176:179], v[38:41]
	s_cselect_b32 s25, s26, 0
	s_add_u32 s12, s12, 0x80
	s_addc_u32 s13, s13, 0
	v_mfma_f32_16x16x32_bf16 v[34:37], v[168:171], v[176:179], v[34:37]
	s_cmpk_eq_i32 s12, 0x1580
	v_mfma_f32_16x16x32_bf16 v[26:29], v[160:163], v[180:183], v[26:29]
	v_mfma_f32_16x16x32_bf16 v[22:25], v[164:167], v[180:183], v[22:25]
	v_mfma_f32_16x16x32_bf16 v[18:21], v[168:171], v[180:183], v[18:21]
	v_mfma_f32_16x16x32_bf16 v[10:13], v[160:163], v[184:187], v[10:13]
	v_mfma_f32_16x16x32_bf16 v[6:9], v[164:167], v[184:187], v[6:9]
	v_mfma_f32_16x16x32_bf16 v[2:5], v[168:171], v[184:187], v[2:5]
	s_setprio 0
	ds_read_b128 v[160:163], v159
	ds_read_b128 v[164:167], v159 offset:1024
	ds_read_b128 v[168:171], v159 offset:2048
	ds_read_b128 v[172:175], v159 offset:3072
	s_waitcnt lgkmcnt(0)
	s_setprio 1
	v_mfma_f32_16x16x32_bf16 v[126:129], v[130:133], v[160:163], v[126:129]
	v_mfma_f32_16x16x32_bf16 v[122:125], v[134:137], v[160:163], v[122:125]
	v_mfma_f32_16x16x32_bf16 v[118:121], v[138:141], v[160:163], v[118:121]
	v_mfma_f32_16x16x32_bf16 v[114:117], v[142:145], v[160:163], v[114:117]
	v_mfma_f32_16x16x32_bf16 v[110:113], v[130:133], v[164:167], v[110:113]
	v_mfma_f32_16x16x32_bf16 v[106:109], v[134:137], v[164:167], v[106:109]
	v_mfma_f32_16x16x32_bf16 v[102:105], v[138:141], v[164:167], v[102:105]
	v_mfma_f32_16x16x32_bf16 v[98:101], v[142:145], v[164:167], v[98:101]
	v_mfma_f32_16x16x32_bf16 v[94:97], v[130:133], v[168:171], v[94:97]
	v_mfma_f32_16x16x32_bf16 v[90:93], v[134:137], v[168:171], v[90:93]
	v_mfma_f32_16x16x32_bf16 v[86:89], v[138:141], v[168:171], v[86:89]
	v_mfma_f32_16x16x32_bf16 v[82:85], v[142:145], v[168:171], v[82:85]
	v_mfma_f32_16x16x32_bf16 v[78:81], v[130:133], v[172:175], v[78:81]
	v_mfma_f32_16x16x32_bf16 v[74:77], v[134:137], v[172:175], v[74:77]
	v_mfma_f32_16x16x32_bf16 v[70:73], v[138:141], v[172:175], v[70:73]
	v_mfma_f32_16x16x32_bf16 v[66:69], v[142:145], v[172:175], v[66:69]
	s_setprio 0
	ds_read_b128 v[160:163], v159 offset:4096
	ds_read_b128 v[164:167], v159 offset:5120
	ds_read_b128 v[168:171], v159 offset:6144
	ds_read_b128 v[172:175], v159 offset:7168
	s_waitcnt lgkmcnt(0)
	s_setprio 1
	v_mfma_f32_16x16x32_bf16 v[62:65], v[130:133], v[160:163], v[62:65]
	v_mfma_f32_16x16x32_bf16 v[58:61], v[134:137], v[160:163], v[58:61]
	v_mfma_f32_16x16x32_bf16 v[54:57], v[138:141], v[160:163], v[54:57]
	v_mfma_f32_16x16x32_bf16 v[50:53], v[142:145], v[160:163], v[50:53]
	v_mfma_f32_16x16x32_bf16 v[46:49], v[130:133], v[164:167], v[46:49]
	v_mfma_f32_16x16x32_bf16 v[42:45], v[134:137], v[164:167], v[42:45]
	v_mfma_f32_16x16x32_bf16 v[38:41], v[138:141], v[164:167], v[38:41]
	v_mfma_f32_16x16x32_bf16 v[34:37], v[142:145], v[164:167], v[34:37]
	v_mfma_f32_16x16x32_bf16 v[30:33], v[130:133], v[168:171], v[30:33]
	v_mfma_f32_16x16x32_bf16 v[26:29], v[134:137], v[168:171], v[26:29]
	v_mfma_f32_16x16x32_bf16 v[22:25], v[138:141], v[168:171], v[22:25]
	v_mfma_f32_16x16x32_bf16 v[18:21], v[142:145], v[168:171], v[18:21]
	v_mfma_f32_16x16x32_bf16 v[14:17], v[130:133], v[172:175], v[14:17]
	v_mfma_f32_16x16x32_bf16 v[10:13], v[134:137], v[172:175], v[10:13]
	v_mfma_f32_16x16x32_bf16 v[6:9], v[138:141], v[172:175], v[6:9]
	v_mfma_f32_16x16x32_bf16 v[2:5], v[142:145], v[172:175], v[2:5]
	s_setprio 0
	s_cbranch_scc0 .LBB0_125
	v_add3_u32 v182, 0, v157, v0
	s_waitcnt vmcnt(6) lgkmcnt(0)
	s_barrier
	v_add_u32_e32 v142, 0xc000, v182
	v_add3_u32 v0, 0, v158, v0
	ds_read_b128 v[130:133], v142 offset:16384
	ds_read_b128 v[134:137], v142 offset:17408
	ds_read_b128 v[138:141], v142 offset:18432
	ds_read_b128 v[142:145], v142 offset:19456
	ds_read_b128 v[146:149], v0 offset:49152
	ds_read_b128 v[150:153], v0 offset:50176
	ds_read_b128 v[154:157], v0 offset:51200
	ds_read_b128 v[158:161], v0 offset:52224
	s_waitcnt lgkmcnt(0)
	v_mfma_f32_16x16x32_bf16 v[126:129], v[130:133], v[146:149], v[126:129]
	s_lshl_b64 s[10:11], s[10:11], 11
	s_add_u32 s2, s19, s10
	s_addc_u32 s11, s20, s11
	v_mfma_f32_16x16x32_bf16 v[122:125], v[134:137], v[146:149], v[122:125]
	s_lshl_b32 s10, s24, 1
	s_add_u32 s10, s2, s10
	s_addc_u32 s11, s11, 0
	v_mfma_f32_16x16x32_bf16 v[118:121], v[138:141], v[146:149], v[118:121]
	s_mov_b64 s[24:25], 0x3000
	v_mfma_f32_16x16x32_bf16 v[114:117], v[142:145], v[146:149], v[114:117]
	v_mfma_f32_16x16x32_bf16 v[110:113], v[130:133], v[150:153], v[110:113]
	v_mfma_f32_16x16x32_bf16 v[106:109], v[134:137], v[150:153], v[106:109]
	v_mfma_f32_16x16x32_bf16 v[102:105], v[138:141], v[150:153], v[102:105]
	v_mfma_f32_16x16x32_bf16 v[98:101], v[142:145], v[150:153], v[98:101]
	v_mfma_f32_16x16x32_bf16 v[94:97], v[130:133], v[154:157], v[94:97]
	v_mfma_f32_16x16x32_bf16 v[90:93], v[134:137], v[154:157], v[90:93]
	v_mfma_f32_16x16x32_bf16 v[146:149], v[138:141], v[154:157], v[86:89]
	v_mfma_f32_16x16x32_bf16 v[82:85], v[142:145], v[154:157], v[82:85]
	v_mfma_f32_16x16x32_bf16 v[150:153], v[130:133], v[158:161], v[78:81]
	v_mfma_f32_16x16x32_bf16 v[74:77], v[134:137], v[158:161], v[74:77]
	v_mfma_f32_16x16x32_bf16 v[70:73], v[138:141], v[158:161], v[70:73]
	v_mfma_f32_16x16x32_bf16 v[154:157], v[142:145], v[158:161], v[66:69]
	s_nop 2
	ds_read_b128 v[66:69], v0 offset:53248
	ds_read_b128 v[78:81], v0 offset:54272
	ds_read_b128 v[86:89], v0 offset:55296
	ds_read_b128 v[158:161], v0 offset:56320
	s_waitcnt vmcnt(0) lgkmcnt(0)
	s_barrier
	s_waitcnt lgkmcnt(0)
	v_mfma_f32_16x16x32_bf16 v[62:65], v[130:133], v[66:69], v[62:65]
	v_mfma_f32_16x16x32_bf16 v[162:165], v[134:137], v[66:69], v[58:61]
	v_mfma_f32_16x16x32_bf16 v[166:169], v[138:141], v[66:69], v[54:57]
	v_mfma_f32_16x16x32_bf16 v[50:53], v[142:145], v[66:69], v[50:53]
	v_mfma_f32_16x16x32_bf16 v[170:173], v[130:133], v[78:81], v[46:49]
	v_mfma_f32_16x16x32_bf16 v[42:45], v[134:137], v[78:81], v[42:45]
	v_mfma_f32_16x16x32_bf16 v[38:41], v[138:141], v[78:81], v[38:41]
	v_mfma_f32_16x16x32_bf16 v[174:177], v[142:145], v[78:81], v[34:37]
	v_mfma_f32_16x16x32_bf16 v[30:33], v[130:133], v[86:89], v[30:33]
	v_mfma_f32_16x16x32_bf16 v[178:181], v[134:137], v[86:89], v[26:29]
	v_mfma_f32_16x16x32_bf16 v[22:25], v[138:141], v[86:89], v[22:25]
	v_mfma_f32_16x16x32_bf16 v[18:21], v[142:145], v[86:89], v[18:21]
	v_mfma_f32_16x16x32_bf16 v[14:17], v[130:133], v[158:161], v[14:17]
	v_mfma_f32_16x16x32_bf16 v[10:13], v[134:137], v[158:161], v[10:13]
	v_mfma_f32_16x16x32_bf16 v[6:9], v[138:141], v[158:161], v[6:9]
	v_mfma_f32_16x16x32_bf16 v[2:5], v[142:145], v[158:161], v[2:5]
	ds_read_b128 v[130:133], v182 offset:16384
	ds_read_b128 v[134:137], v182 offset:17408
	ds_read_b128 v[138:141], v182 offset:18432
	ds_read_b128 v[142:145], v182 offset:19456
	ds_read_b128 v[26:29], v0
	ds_read_b128 v[34:37], v0 offset:1024
	ds_read_b128 v[46:49], v0 offset:2048
	ds_read_b128 v[158:161], v0 offset:3072
	s_waitcnt lgkmcnt(0)
	v_mfma_f32_16x16x32_bf16 v[110:113], v[130:133], v[34:37], v[110:113]
	v_mfma_f32_16x16x32_bf16 v[106:109], v[134:137], v[34:37], v[106:109]
	v_mfma_f32_16x16x32_bf16 v[102:105], v[138:141], v[34:37], v[102:105]
	v_mfma_f32_16x16x32_bf16 v[98:101], v[142:145], v[34:37], v[98:101]
	v_mfma_f32_16x16x32_bf16 v[86:89], v[130:133], v[46:49], v[94:97]
	v_mfma_f32_16x16x32_bf16 v[78:81], v[134:137], v[46:49], v[90:93]
	v_mfma_f32_16x16x32_bf16 v[66:69], v[138:141], v[46:49], v[146:149]
	s_nop 5
	v_cvt_pk_bf16_f32 v86, v86, v87
	v_cvt_pk_bf16_f32 v78, v78, v79
	v_cvt_pk_bf16_f32 v79, v80, v81
	v_mfma_f32_16x16x32_bf16 v[34:37], v[138:141], v[158:161], v[70:73]
	s_nop 2
	ds_read_b128 v[70:73], v0 offset:4096
	ds_read_b128 v[90:93], v0 offset:5120
	ds_read_b128 v[94:97], v0 offset:6144
	ds_read_b128 v[146:149], v0 offset:7168
	s_waitcnt vmcnt(0) lgkmcnt(0)
	s_barrier
	v_mfma_f32_16x16x32_bf16 v[126:129], v[130:133], v[26:29], v[126:129]
	v_cvt_pk_bf16_f32 v34, v34, v35
	v_cvt_pk_bf16_f32 v35, v36, v37
	v_mfma_f32_16x16x32_bf16 v[122:125], v[134:137], v[26:29], v[122:125]
	v_cvt_pk_bf16_f32 v66, v66, v67
	v_cvt_pk_bf16_f32 v67, v68, v69
	v_cvt_pk_bf16_f32 v87, v88, v89
	v_mfma_f32_16x16x32_bf16 v[118:121], v[138:141], v[26:29], v[118:121]
	v_mfma_f32_16x16x32_bf16 v[114:117], v[142:145], v[26:29], v[114:117]
	v_mfma_f32_16x16x32_bf16 v[58:61], v[142:145], v[46:49], v[82:85]
	v_mfma_f32_16x16x32_bf16 v[54:57], v[130:133], v[158:161], v[150:153]
	v_mfma_f32_16x16x32_bf16 v[46:49], v[134:137], v[158:161], v[74:77]
	s_nop 5
	v_cvt_pk_bf16_f32 v58, v58, v59
	v_cvt_pk_bf16_f32 v59, v60, v61
	v_cvt_pk_bf16_f32 v54, v54, v55
	v_mfma_f32_16x16x32_bf16 v[26:29], v[142:145], v[158:161], v[154:157]
	v_cvt_pk_bf16_f32 v55, v56, v57
	v_cvt_pk_bf16_f32 v46, v46, v47
	v_cvt_pk_bf16_f32 v47, v48, v49
	v_mfma_f32_16x16x32_bf16 v[150:153], v[130:133], v[70:73], v[62:65]
	v_mfma_f32_16x16x32_bf16 v[154:157], v[134:137], v[70:73], v[162:165]
	s_nop 2
	v_cvt_pk_bf16_f32 v26, v26, v27
	v_cvt_pk_bf16_f32 v27, v28, v29
	v_mfma_f32_16x16x32_bf16 v[82:85], v[138:141], v[70:73], v[166:169]
	v_mfma_f32_16x16x32_bf16 v[74:77], v[142:145], v[70:73], v[50:53]
	s_nop 0
	v_cvt_pk_bf16_f32 v28, v154, v155
	v_cvt_pk_bf16_f32 v29, v156, v157
	v_mfma_f32_16x16x32_bf16 v[70:73], v[130:133], v[90:93], v[170:173]
	v_mfma_f32_16x16x32_bf16 v[62:65], v[134:137], v[90:93], v[42:45]
	v_mfma_f32_16x16x32_bf16 v[50:53], v[138:141], v[90:93], v[38:41]
	v_mfma_f32_16x16x32_bf16 v[42:45], v[142:145], v[90:93], v[174:177]
	v_mov_b32_e32 v90, v196
	s_nop 0
	v_and_b32_e32 v0, 64, v90
	v_lshrrev_b32_e32 v92, 1, v90
	v_lshlrev_b32_e32 v0, 1, v0
	v_and_b32_e32 v92, 24, v92
	v_and_b32_e32 v91, 0xfffff8f, v90
	v_add3_u32 v0, 0, v0, v92
	v_mad_u64_u32 v[92:93], s[12:13], v91, s30, v[0:1]
	v_add_u32_e32 v48, 0x3000, v92
	v_mfma_f32_16x16x32_bf16 v[38:41], v[130:133], v[94:97], v[30:33]
	ds_write2_b64 v48, v[34:35], v[26:27] offset0:104 offset1:108
	v_cvt_pk_bf16_f32 v26, v150, v151
	v_cvt_pk_bf16_f32 v27, v152, v153
	v_mfma_f32_16x16x32_bf16 v[30:33], v[134:137], v[94:97], v[178:181]
	v_add_u32_e32 v34, 0x4000, v92
	ds_write2_b64 v34, v[26:27], v[28:29] offset0:128 offset1:132
	v_cvt_pk_bf16_f32 v26, v82, v83
	v_mfma_f32_16x16x32_bf16 v[22:25], v[138:141], v[94:97], v[22:25]
	v_cvt_pk_bf16_f32 v27, v84, v85
	v_cvt_pk_bf16_f32 v28, v74, v75
	v_cvt_pk_bf16_f32 v29, v76, v77
	v_mfma_f32_16x16x32_bf16 v[18:21], v[142:145], v[94:97], v[18:21]
	ds_write2_b64 v34, v[26:27], v[28:29] offset0:136 offset1:140
	v_cvt_pk_bf16_f32 v26, v70, v71
	v_cvt_pk_bf16_f32 v27, v72, v73
	v_cvt_pk_bf16_f32 v28, v62, v63
	v_cvt_pk_bf16_f32 v29, v64, v65
	v_add_u32_e32 v34, 0x5000, v92
	v_mfma_f32_16x16x32_bf16 v[6:9], v[138:141], v[146:149], v[6:9]
	ds_write2_b64 v34, v[26:27], v[28:29] offset0:160 offset1:164
	v_cvt_pk_bf16_f32 v26, v50, v51
	v_cvt_pk_bf16_f32 v27, v52, v53
	v_mfma_f32_16x16x32_bf16 v[2:5], v[142:145], v[146:149], v[2:5]
	v_cvt_pk_bf16_f32 v28, v42, v43
	v_cvt_pk_bf16_f32 v29, v44, v45
	v_cvt_pk_bf16_f32 v94, v126, v127
	v_cvt_pk_bf16_f32 v95, v128, v129
	v_cvt_pk_bf16_f32 v96, v122, v123
	v_cvt_pk_bf16_f32 v97, v124, v125
	ds_write2_b64 v34, v[26:27], v[28:29] offset0:168 offset1:172
	v_cvt_pk_bf16_f32 v28, v30, v31
	v_add_u32_e32 v30, 0x6000, v92
	v_cvt_pk_bf16_f32 v22, v22, v23
	v_cvt_pk_bf16_f32 v23, v24, v25
	v_cvt_pk_bf16_f32 v18, v18, v19
	v_cvt_pk_bf16_f32 v19, v20, v21
	v_mfma_f32_16x16x32_bf16 v[14:17], v[130:133], v[146:149], v[14:17]
	ds_write2_b64 v92, v[94:95], v[96:97] offset1:4
	v_cvt_pk_bf16_f32 v94, v118, v119
	v_cvt_pk_bf16_f32 v95, v120, v121
	v_mfma_f32_16x16x32_bf16 v[10:13], v[134:137], v[146:149], v[10:13]
	v_cvt_pk_bf16_f32 v96, v114, v115
	v_cvt_pk_bf16_f32 v97, v116, v117
	ds_write2_b64 v30, v[22:23], v[18:19] offset0:200 offset1:204
	v_or_b32_e32 v18, 0x70, v90
	ds_write2_b64 v92, v[94:95], v[96:97] offset0:8 offset1:12
	v_cvt_pk_bf16_f32 v94, v110, v111
	v_cvt_pk_bf16_f32 v95, v112, v113
	v_cvt_pk_bf16_f32 v96, v106, v107
	v_cvt_pk_bf16_f32 v97, v108, v109
	v_add_u32_e32 v91, 0x1000, v92
	v_mad_u64_u32 v[18:19], s[12:13], v18, s30, v[0:1]
	v_lshlrev_b32_e32 v0, 4, v90
	ds_write2_b64 v91, v[94:95], v[96:97] offset0:32 offset1:36
	v_cvt_pk_bf16_f32 v94, v102, v103
	v_cvt_pk_bf16_f32 v95, v104, v105
	v_cvt_pk_bf16_f32 v96, v98, v99
	v_cvt_pk_bf16_f32 v97, v100, v101
	v_add_u32_e32 v80, 0x2000, v92
	v_cvt_pk_bf16_f32 v6, v6, v7
	v_cvt_pk_bf16_f32 v7, v8, v9
	v_cvt_pk_bf16_f32 v2, v2, v3
	v_cvt_pk_bf16_f32 v3, v4, v5
	v_and_b32_e32 v0, 0xf0, v0
	v_ashrrev_i32_e32 v4, 4, v90
	ds_write2_b64 v91, v[94:95], v[96:97] offset0:40 offset1:44
	ds_write2_b64 v80, v[66:67], v[58:59] offset0:72 offset1:76
	ds_write2_b64 v18, v[6:7], v[2:3] offset0:8 offset1:12
	v_lshl_add_u64 v[2:3], s[10:11], 0, v[0:1]
	v_add_u32_e32 v0, 0, v0
	v_ashrrev_i32_e32 v5, 31, v4
	v_cvt_pk_bf16_f32 v26, v38, v39
	v_cvt_pk_bf16_f32 v27, v40, v41
	v_cvt_pk_bf16_f32 v29, v32, v33
	v_cvt_pk_bf16_f32 v14, v14, v15
	v_cvt_pk_bf16_f32 v15, v16, v17
	v_cvt_pk_bf16_f32 v10, v10, v11
	v_cvt_pk_bf16_f32 v11, v12, v13
	v_mad_u64_u32 v[6:7], s[10:11], v4, s30, v[0:1]
	v_lshlrev_b64 v[4:5], 11, v[4:5]
	ds_write2_b64 v80, v[86:87], v[78:79] offset0:64 offset1:68
	ds_write2_b64 v48, v[54:55], v[46:47] offset0:96 offset1:100
	ds_write2_b64 v30, v[26:27], v[28:29] offset0:192 offset1:196
	ds_write2_b64 v18, v[14:15], v[10:11] offset1:4
	s_waitcnt lgkmcnt(0)
	s_barrier
	v_lshl_add_u64 v[8:9], v[2:3], 0, v[4:5]
	v_mov_b32_e32 v214, 0x8000
	v_mov_b32_e32 v215, 0
	ds_read_b128 v[216:219], v6
	ds_read_b128 v[228:231], v6 offset:4352
	ds_read_b128 v[232:235], v6 offset:8704
	ds_read_b128 v[236:239], v6 offset:13056
	ds_read_b128 v[240:243], v6 offset:17408
	ds_read_b128 v[244:247], v6 offset:21760
	ds_read_b128 v[248:251], v6 offset:26112
	ds_read_b128 v[252:255], v6 offset:30464
	s_waitcnt lgkmcnt(7)
	global_store_dwordx4 v[8:9], v[216:219], off
	v_lshl_add_u64 v[8:9], v[8:9], 0, v[214:215]
	s_waitcnt lgkmcnt(6)
	global_store_dwordx4 v[8:9], v[228:231], off
	v_lshl_add_u64 v[8:9], v[8:9], 0, v[214:215]
	s_waitcnt lgkmcnt(5)
	global_store_dwordx4 v[8:9], v[232:235], off
	v_lshl_add_u64 v[8:9], v[8:9], 0, v[214:215]
	s_waitcnt lgkmcnt(4)
	global_store_dwordx4 v[8:9], v[236:239], off
	v_lshl_add_u64 v[8:9], v[8:9], 0, v[214:215]
	s_waitcnt lgkmcnt(3)
	global_store_dwordx4 v[8:9], v[240:243], off
	v_lshl_add_u64 v[8:9], v[8:9], 0, v[214:215]
	s_waitcnt lgkmcnt(2)
	global_store_dwordx4 v[8:9], v[244:247], off
	v_lshl_add_u64 v[8:9], v[8:9], 0, v[214:215]
	s_waitcnt lgkmcnt(1)
	global_store_dwordx4 v[8:9], v[248:251], off
	v_lshl_add_u64 v[8:9], v[8:9], 0, v[214:215]
	s_waitcnt lgkmcnt(0)
	global_store_dwordx4 v[8:9], v[252:255], off
	v_lshl_add_u64 v[8:9], v[8:9], 0, v[214:215]
	ds_read_b128 v[216:219], v6 offset:34816
	ds_read_b128 v[228:231], v6 offset:39168
	ds_read_b128 v[232:235], v6 offset:43520
	ds_read_b128 v[236:239], v6 offset:47872
	ds_read_b128 v[240:243], v6 offset:52224
	ds_read_b128 v[244:247], v6 offset:56576
	ds_read_b128 v[248:251], v6 offset:60928
	ds_read_b128 v[252:255], v6 offset:65280
	s_waitcnt lgkmcnt(7)
	global_store_dwordx4 v[8:9], v[216:219], off
	v_lshl_add_u64 v[8:9], v[8:9], 0, v[214:215]
	s_waitcnt lgkmcnt(6)
	global_store_dwordx4 v[8:9], v[228:231], off
	v_lshl_add_u64 v[8:9], v[8:9], 0, v[214:215]
	s_waitcnt lgkmcnt(5)
	global_store_dwordx4 v[8:9], v[232:235], off
	v_lshl_add_u64 v[8:9], v[8:9], 0, v[214:215]
	s_waitcnt lgkmcnt(4)
	global_store_dwordx4 v[8:9], v[236:239], off
	v_lshl_add_u64 v[8:9], v[8:9], 0, v[214:215]
	s_waitcnt lgkmcnt(3)
	global_store_dwordx4 v[8:9], v[240:243], off
	v_lshl_add_u64 v[8:9], v[8:9], 0, v[214:215]
	s_waitcnt lgkmcnt(2)
	global_store_dwordx4 v[8:9], v[244:247], off
	v_lshl_add_u64 v[8:9], v[8:9], 0, v[214:215]
	s_waitcnt lgkmcnt(1)
	global_store_dwordx4 v[8:9], v[248:251], off
	v_lshl_add_u64 v[8:9], v[8:9], 0, v[214:215]
	s_waitcnt lgkmcnt(0)
	global_store_dwordx4 v[8:9], v[252:255], off
	s_barrier
	s_branch .LBB0_118

.LBB0_175:
	s_nop 0
	v_lshl_add_u32 v10, s26, 14, v126
	v_add_u32_e32 v13, 0x1000, v10
	v_readfirstlane_b32 s2, v10
	s_waitcnt vmcnt(4) lgkmcnt(0)
	s_barrier
	v_add_u32_e32 v11, 0x2000, v10
	s_mov_b32 m0, s2
	v_readfirstlane_b32 s2, v13
	v_add_u32_e32 v12, 0x3000, v10
	global_load_lds_dwordx4 v[116:117], off
	s_mov_b32 m0, s2
	v_readfirstlane_b32 s2, v11
	v_lshl_add_u64 v[120:121], v[118:119], 0, s[12:13]
	global_load_lds_dwordx4 v[114:115], off
	s_mov_b32 m0, s2
	v_readfirstlane_b32 s2, v12
	global_load_lds_dwordx4 v[120:121], off
	s_mov_b32 m0, s2
	s_lshl_b32 s2, s27, 14
	v_lshl_add_u64 v[10:11], v[120:121], 0, s[40:41]
	s_add_i32 s2, s2, 0
	global_load_lds_dwordx4 v[10:11], off
	v_add3_u32 v10, s2, v128, v0
	ds_read_b128 v[98:101], v10 offset:8192
	ds_read_b128 v[102:105], v10 offset:9216
	ds_read_b128 v[106:109], v10 offset:10240
	ds_read_b128 v[110:113], v10 offset:11264
	v_add3_u32 v10, s2, v127, v0
	ds_read_b128 v[78:81], v10
	ds_read_b128 v[82:85], v10 offset:1024
	ds_read_b128 v[94:97], v10 offset:2048
	ds_read_b128 v[130:133], v10 offset:3072
	s_add_i32 s2, s27, 1
	s_cmp_lg_u32 s27, 2
	s_cselect_b32 s2, s2, 0
	s_add_i32 s27, s26, 1
	s_cmp_lg_u32 s26, 2
	s_cselect_b32 s27, s27, 0
	s_waitcnt lgkmcnt(0)
	s_setprio 1
	v_mfma_f32_16x16x32_bf16 v[10:13], v[98:101], v[78:81], v[74:77]
	v_lshl_add_u64 v[124:125], v[116:117], 0, 64
	s_setprio 0
	s_waitcnt vmcnt(4) lgkmcnt(0)
	s_barrier
	s_setprio 1
	v_mfma_f32_16x16x32_bf16 v[14:17], v[102:105], v[78:81], v[70:73]
	s_setprio 0
	v_lshl_add_u64 v[122:123], v[114:115], 0, 64
	v_lshl_add_u64 v[142:143], v[116:117], 0, s[78:79]
	s_setprio 1
	v_mfma_f32_16x16x32_bf16 v[30:33], v[106:109], v[78:81], v[66:69]
	v_lshl_add_u64 v[144:145], v[114:115], 0, s[78:79]
	v_lshl_add_u64 v[116:117], v[116:117], 0, s[84:85]
	v_lshl_add_u64 v[114:115], v[114:115], 0, s[84:85]
	v_mfma_f32_16x16x32_bf16 v[66:69], v[110:113], v[78:81], v[62:65]
	v_mfma_f32_16x16x32_bf16 v[70:73], v[98:101], v[82:85], v[58:61]
	v_mfma_f32_16x16x32_bf16 v[74:77], v[102:105], v[82:85], v[54:57]
	v_mfma_f32_16x16x32_bf16 v[78:81], v[106:109], v[82:85], v[50:53]
	v_mfma_f32_16x16x32_bf16 v[46:49], v[110:113], v[82:85], v[46:49]
	v_mfma_f32_16x16x32_bf16 v[82:85], v[98:101], v[94:97], v[42:45]
	v_mfma_f32_16x16x32_bf16 v[86:89], v[102:105], v[94:97], v[38:41]
	v_mfma_f32_16x16x32_bf16 v[90:93], v[106:109], v[94:97], v[34:37]
	v_mfma_f32_16x16x32_bf16 v[94:97], v[110:113], v[94:97], v[26:29]
	v_mfma_f32_16x16x32_bf16 v[110:113], v[110:113], v[130:133], v[2:5]
	s_nop 2
	v_lshl_add_u32 v2, s27, 14, v126
	v_add_u32_e32 v3, 0x1000, v2
	v_readfirstlane_b32 s26, v2
	v_add_u32_e32 v5, 0x2000, v2
	s_mov_b32 m0, s26
	v_readfirstlane_b32 s26, v3
	v_add_u32_e32 v4, 0x3000, v2
	global_load_lds_dwordx4 v[124:125], off
	s_mov_b32 m0, s26
	v_readfirstlane_b32 s26, v5
	global_load_lds_dwordx4 v[122:123], off
	v_lshl_add_u64 v[2:3], v[120:121], 0, 64
	s_mov_b32 m0, s26
	v_readfirstlane_b32 s26, v4
	global_load_lds_dwordx4 v[2:3], off
	s_mov_b32 m0, s26
	s_lshl_b32 s26, s2, 14
	v_lshl_add_u64 v[2:3], v[120:121], 0, s[36:37]
	s_add_i32 s26, s26, 0
	v_mfma_f32_16x16x32_bf16 v[102:105], v[102:105], v[130:133], v[18:21]
	global_load_lds_dwordx4 v[2:3], off
	v_add3_u32 v26, s26, v127, v0
	s_nop 0
	v_add3_u32 v18, s26, v128, v0
	v_mfma_f32_16x16x32_bf16 v[98:101], v[98:101], v[130:133], v[22:25]
	s_add_i32 s26, s2, 1
	s_cmp_lg_u32 s2, 2
	s_cselect_b32 s26, s26, 0
	v_mfma_f32_16x16x32_bf16 v[106:109], v[106:109], v[130:133], v[6:9]
	s_setprio 0
	ds_read_b128 v[2:5], v18 offset:8192
	s_nop 1
	ds_read_b128 v[6:9], v18 offset:9216
	ds_read_b128 v[122:125], v18 offset:10240
	ds_read_b128 v[130:133], v18 offset:11264
	s_add_i32 s2, s27, 1
	ds_read_b128 v[18:21], v26
	ds_read_b128 v[22:25], v26 offset:1024
	ds_read_b128 v[134:137], v26 offset:2048
	ds_read_b128 v[138:141], v26 offset:3072
	s_cmp_lg_u32 s27, 2
	s_cselect_b32 s2, s2, 0
	s_waitcnt lgkmcnt(0)
	s_setprio 1
	v_mfma_f32_16x16x32_bf16 v[50:53], v[130:133], v[18:21], v[66:69]
	s_setprio 0
	s_waitcnt vmcnt(4) lgkmcnt(0)
	s_barrier
	s_setprio 1
	v_mfma_f32_16x16x32_bf16 v[62:65], v[2:5], v[18:21], v[10:13]
	s_nop 0
	v_lshl_add_u32 v66, s2, 14, v126
	v_add_u32_e32 v67, 0x1000, v66
	v_readfirstlane_b32 s27, v66
	v_add_u32_e32 v69, 0x2000, v66
	s_mov_b32 m0, s27
	v_readfirstlane_b32 s27, v67
	v_add_u32_e32 v68, 0x3000, v66
	global_load_lds_dwordx4 v[142:143], off
	s_mov_b32 m0, s27
	v_readfirstlane_b32 s27, v69
	global_load_lds_dwordx4 v[144:145], off
	v_lshl_add_u64 v[66:67], v[120:121], 0, s[78:79]
	s_mov_b32 m0, s27
	v_readfirstlane_b32 s27, v68
	global_load_lds_dwordx4 v[66:67], off
	v_lshl_add_u64 v[66:67], v[120:121], 0, s[50:51]
	s_mov_b32 m0, s27
	s_lshl_b32 s27, s26, 14
	global_load_lds_dwordx4 v[66:67], off
	s_add_i32 s27, s27, 0
	v_add3_u32 v66, s27, v128, v0
	v_mfma_f32_16x16x32_bf16 v[58:61], v[6:9], v[18:21], v[14:17]
	v_mfma_f32_16x16x32_bf16 v[54:57], v[122:125], v[18:21], v[30:33]
	v_mfma_f32_16x16x32_bf16 v[34:37], v[2:5], v[22:25], v[70:73]
	v_mfma_f32_16x16x32_bf16 v[38:41], v[6:9], v[22:25], v[74:77]
	v_mfma_f32_16x16x32_bf16 v[42:45], v[122:125], v[22:25], v[78:81]
	v_mfma_f32_16x16x32_bf16 v[46:49], v[130:133], v[22:25], v[46:49]
	v_mfma_f32_16x16x32_bf16 v[18:21], v[2:5], v[134:137], v[82:85]
	v_mfma_f32_16x16x32_bf16 v[22:25], v[6:9], v[134:137], v[86:89]
	v_mfma_f32_16x16x32_bf16 v[26:29], v[122:125], v[134:137], v[90:93]
	s_setprio 0
	ds_read_b128 v[78:81], v66 offset:8192
	ds_read_b128 v[82:85], v66 offset:9216
	ds_read_b128 v[86:89], v66 offset:10240
	ds_read_b128 v[90:93], v66 offset:11264
	v_add3_u32 v66, s27, v127, v0
	s_add_i32 s27, s26, 1
	s_setprio 1
	v_mfma_f32_16x16x32_bf16 v[30:33], v[130:133], v[134:137], v[94:97]
	s_cmp_lg_u32 s26, 2
	s_cselect_b32 s27, s27, 0
	s_add_i32 s26, s2, 1
	v_mfma_f32_16x16x32_bf16 v[2:5], v[2:5], v[138:141], v[98:101]
	s_cmp_lg_u32 s2, 2
	s_cselect_b32 s26, s26, 0
	s_add_u32 s12, s12, 0xc0
	v_mfma_f32_16x16x32_bf16 v[6:9], v[6:9], v[138:141], v[102:105]
	s_addc_u32 s13, s13, 0
	s_cmpk_eq_i32 s12, 0x780
	v_mfma_f32_16x16x32_bf16 v[10:13], v[122:125], v[138:141], v[106:109]
	s_setprio 0
	ds_read_b128 v[94:97], v66
	ds_read_b128 v[98:101], v66 offset:1024
	ds_read_b128 v[102:105], v66 offset:2048
	ds_read_b128 v[106:109], v66 offset:3072
	s_setprio 1
	v_mfma_f32_16x16x32_bf16 v[14:17], v[130:133], v[138:141], v[110:113]
	s_setprio 0
	s_waitcnt lgkmcnt(0)
	s_setprio 1
	v_mfma_f32_16x16x32_bf16 v[74:77], v[78:81], v[94:97], v[62:65]
	v_mfma_f32_16x16x32_bf16 v[70:73], v[82:85], v[94:97], v[58:61]
	v_mfma_f32_16x16x32_bf16 v[66:69], v[86:89], v[94:97], v[54:57]
	v_mfma_f32_16x16x32_bf16 v[62:65], v[90:93], v[94:97], v[50:53]
	v_mfma_f32_16x16x32_bf16 v[58:61], v[78:81], v[98:101], v[34:37]
	v_mfma_f32_16x16x32_bf16 v[54:57], v[82:85], v[98:101], v[38:41]
	v_mfma_f32_16x16x32_bf16 v[50:53], v[86:89], v[98:101], v[42:45]
	v_mfma_f32_16x16x32_bf16 v[46:49], v[90:93], v[98:101], v[46:49]
	v_mfma_f32_16x16x32_bf16 v[42:45], v[78:81], v[102:105], v[18:21]
	v_mfma_f32_16x16x32_bf16 v[38:41], v[82:85], v[102:105], v[22:25]
	v_mfma_f32_16x16x32_bf16 v[34:37], v[86:89], v[102:105], v[26:29]
	v_mfma_f32_16x16x32_bf16 v[26:29], v[90:93], v[102:105], v[30:33]
	v_mfma_f32_16x16x32_bf16 v[22:25], v[78:81], v[106:109], v[2:5]
	v_mfma_f32_16x16x32_bf16 v[18:21], v[82:85], v[106:109], v[6:9]
	v_mfma_f32_16x16x32_bf16 v[6:9], v[86:89], v[106:109], v[10:13]
	v_mfma_f32_16x16x32_bf16 v[2:5], v[90:93], v[106:109], v[14:17]
	s_setprio 0
	s_cbranch_scc0 .LBB0_175
	s_waitcnt vmcnt(4) lgkmcnt(0)
	s_barrier
	v_add3_u32 v98, 0, v128, v0
	v_add3_u32 v0, 0, v127, v0
	ds_read_b128 v[10:13], v98 offset:8192
	ds_read_b128 v[14:17], v98 offset:9216
	ds_read_b128 v[30:33], v98 offset:10240
	ds_read_b128 v[78:81], v98 offset:11264
	ds_read_b128 v[82:85], v0
	ds_read_b128 v[86:89], v0 offset:1024
	ds_read_b128 v[90:93], v0 offset:2048
	ds_read_b128 v[94:97], v0 offset:3072
	s_waitcnt vmcnt(0) lgkmcnt(0)
	s_barrier
	s_waitcnt lgkmcnt(0)
	v_mfma_f32_16x16x32_bf16 v[74:77], v[10:13], v[82:85], v[74:77]
	s_add_u32 s2, s19, s10
	s_addc_u32 s11, s20, s11
	s_lshl_b32 s10, s25, 1
	v_mfma_f32_16x16x32_bf16 v[70:73], v[14:17], v[82:85], v[70:73]
	s_add_u32 s10, s2, s10
	s_mov_b32 s2, 0xfffffc0
	s_addc_u32 s11, s11, 0
	v_mfma_f32_16x16x32_bf16 v[66:69], v[30:33], v[82:85], v[66:69]
	s_mov_b64 s[90:91], 0x20080
	s_mov_b64 s[96:97], 0x20040
	s_mov_b64 s[76:77], 0x20000
	v_mfma_f32_16x16x32_bf16 v[62:65], v[78:81], v[82:85], v[62:65]
	v_mfma_f32_16x16x32_bf16 v[58:61], v[10:13], v[86:89], v[58:61]
	v_mfma_f32_16x16x32_bf16 v[54:57], v[14:17], v[86:89], v[54:57]
	v_mfma_f32_16x16x32_bf16 v[50:53], v[30:33], v[86:89], v[50:53]
	v_mfma_f32_16x16x32_bf16 v[46:49], v[78:81], v[86:89], v[46:49]
	v_mfma_f32_16x16x32_bf16 v[42:45], v[10:13], v[90:93], v[42:45]
	v_mfma_f32_16x16x32_bf16 v[38:41], v[14:17], v[90:93], v[38:41]
	v_mfma_f32_16x16x32_bf16 v[34:37], v[30:33], v[90:93], v[34:37]
	v_mfma_f32_16x16x32_bf16 v[26:29], v[78:81], v[90:93], v[26:29]
	v_mfma_f32_16x16x32_bf16 v[10:13], v[10:13], v[94:97], v[22:25]
	v_mfma_f32_16x16x32_bf16 v[14:17], v[14:17], v[94:97], v[18:21]
	v_mfma_f32_16x16x32_bf16 v[6:9], v[30:33], v[94:97], v[6:9]
	v_mfma_f32_16x16x32_bf16 v[2:5], v[78:81], v[94:97], v[2:5]
	s_nop 0
	ds_read_b128 v[18:21], v98 offset:24576
	ds_read_b128 v[22:25], v98 offset:25600
	ds_read_b128 v[30:33], v98 offset:26624
	ds_read_b128 v[78:81], v98 offset:27648
	ds_read_b128 v[82:85], v0 offset:16384
	ds_read_b128 v[86:89], v0 offset:17408
	ds_read_b128 v[90:93], v0 offset:18432
	ds_read_b128 v[94:97], v0 offset:19456
	s_waitcnt vmcnt(0) lgkmcnt(0)
	s_barrier
	v_mfma_f32_16x16x32_bf16 v[74:77], v[18:21], v[82:85], v[74:77]
	v_mfma_f32_16x16x32_bf16 v[70:73], v[22:25], v[82:85], v[70:73]
	v_mfma_f32_16x16x32_bf16 v[54:57], v[22:25], v[86:89], v[54:57]
	v_mfma_f32_16x16x32_bf16 v[38:41], v[22:25], v[90:93], v[38:41]
	v_mfma_f32_16x16x32_bf16 v[14:17], v[22:25], v[94:97], v[14:17]
	v_mov_b32_e32 v22, v196
	v_mfma_f32_16x16x32_bf16 v[66:69], v[30:33], v[82:85], v[66:69]
	v_and_b32_e32 v23, 15, v22
	v_and_b32_e32 v0, 64, v22
	v_lshl_add_u32 v0, v0, 1, 0
	v_mfma_f32_16x16x32_bf16 v[62:65], v[78:81], v[82:85], v[62:65]
	v_mfma_f32_16x16x32_bf16 v[58:61], v[18:21], v[86:89], v[58:61]
	v_mfma_f32_16x16x32_bf16 v[42:45], v[18:21], v[90:93], v[42:45]
	v_mfma_f32_16x16x32_bf16 v[10:13], v[18:21], v[94:97], v[10:13]
	v_lshrrev_b32_e32 v18, 1, v22
	v_and_or_b32 v19, v18, s2, v23
	v_and_b32_e32 v18, 24, v18
	v_mfma_f32_16x16x32_bf16 v[50:53], v[30:33], v[86:89], v[50:53]
	v_mul_lo_u32 v19, v19, s30
	v_add3_u32 v0, v0, v18, v19
	v_cvt_pk_bf16_f32 v18, v74, v75
	v_mfma_f32_16x16x32_bf16 v[46:49], v[78:81], v[86:89], v[46:49]
	v_cvt_pk_bf16_f32 v19, v76, v77
	v_cvt_pk_bf16_f32 v20, v70, v71
	v_cvt_pk_bf16_f32 v21, v72, v73
	v_mfma_f32_16x16x32_bf16 v[6:9], v[30:33], v[94:97], v[6:9]
	ds_write2_b64 v0, v[18:19], v[20:21] offset1:4
	v_cvt_pk_bf16_f32 v18, v66, v67
	v_cvt_pk_bf16_f32 v19, v68, v69
	v_mfma_f32_16x16x32_bf16 v[2:5], v[78:81], v[94:97], v[2:5]
	v_cvt_pk_bf16_f32 v20, v62, v63
	v_cvt_pk_bf16_f32 v21, v64, v65
	ds_write2_b64 v0, v[18:19], v[20:21] offset0:8 offset1:12
	v_cvt_pk_bf16_f32 v18, v58, v59
	v_cvt_pk_bf16_f32 v19, v60, v61
	v_cvt_pk_bf16_f32 v20, v54, v55
	v_cvt_pk_bf16_f32 v21, v56, v57
	v_add_u32_e32 v24, 0x1000, v0
	v_mfma_f32_16x16x32_bf16 v[34:37], v[30:33], v[90:93], v[34:37]
	ds_write2_b64 v24, v[18:19], v[20:21] offset0:32 offset1:36
	v_cvt_pk_bf16_f32 v18, v50, v51
	v_cvt_pk_bf16_f32 v19, v52, v53
	v_mfma_f32_16x16x32_bf16 v[26:29], v[78:81], v[90:93], v[26:29]
	v_cvt_pk_bf16_f32 v20, v46, v47
	v_cvt_pk_bf16_f32 v21, v48, v49
	ds_write2_b64 v24, v[18:19], v[20:21] offset0:40 offset1:44
	v_add_u32_e32 v24, 0x2000, v0
	v_cvt_pk_bf16_f32 v10, v10, v11
	v_cvt_pk_bf16_f32 v11, v12, v13
	v_cvt_pk_bf16_f32 v12, v14, v15
	v_cvt_pk_bf16_f32 v13, v16, v17
	v_add_u32_e32 v0, 0x3000, v0
	v_cvt_pk_bf16_f32 v6, v6, v7
	v_cvt_pk_bf16_f32 v7, v8, v9
	v_cvt_pk_bf16_f32 v2, v2, v3
	v_cvt_pk_bf16_f32 v3, v4, v5
	ds_write2_b64 v0, v[10:11], v[12:13] offset0:96 offset1:100
	ds_write2_b64 v0, v[6:7], v[2:3] offset0:104 offset1:108
	v_lshlrev_b32_e32 v0, 4, v23
	v_ashrrev_i32_e32 v2, 4, v22
	v_cvt_pk_bf16_f32 v18, v42, v43
	v_cvt_pk_bf16_f32 v19, v44, v45
	v_cvt_pk_bf16_f32 v20, v38, v39
	v_cvt_pk_bf16_f32 v21, v40, v41
	v_lshl_add_u64 v[6:7], s[10:11], 0, v[0:1]
	v_add_u32_e32 v0, 0, v0
	v_ashrrev_i32_e32 v3, 31, v2
	ds_write2_b64 v24, v[18:19], v[20:21] offset0:64 offset1:68
	v_cvt_pk_bf16_f32 v18, v34, v35
	v_cvt_pk_bf16_f32 v19, v36, v37
	v_cvt_pk_bf16_f32 v20, v26, v27
	v_cvt_pk_bf16_f32 v21, v28, v29
	v_mad_u64_u32 v[4:5], s[10:11], v2, s30, v[0:1]
	v_lshlrev_b64 v[2:3], 11, v[2:3]
	ds_write2_b64 v24, v[18:19], v[20:21] offset0:72 offset1:76
	s_waitcnt lgkmcnt(0)
	s_barrier
	v_lshl_add_u64 v[8:9], v[6:7], 0, v[2:3]
	v_mov_b32_e32 v214, 0x8000
	v_mov_b32_e32 v215, 0
	ds_read_b128 v[216:219], v4
	ds_read_b128 v[228:231], v4 offset:4352
	ds_read_b128 v[232:235], v4 offset:8704
	ds_read_b128 v[236:239], v4 offset:13056
	ds_read_b128 v[240:243], v4 offset:17408
	ds_read_b128 v[244:247], v4 offset:21760
	ds_read_b128 v[248:251], v4 offset:26112
	ds_read_b128 v[252:255], v4 offset:30464
	s_waitcnt lgkmcnt(7)
	global_store_dwordx4 v[8:9], v[216:219], off
	v_lshl_add_u64 v[8:9], v[8:9], 0, v[214:215]
	s_waitcnt lgkmcnt(6)
	global_store_dwordx4 v[8:9], v[228:231], off
	v_lshl_add_u64 v[8:9], v[8:9], 0, v[214:215]
	s_waitcnt lgkmcnt(5)
	global_store_dwordx4 v[8:9], v[232:235], off
	v_lshl_add_u64 v[8:9], v[8:9], 0, v[214:215]
	s_waitcnt lgkmcnt(4)
	global_store_dwordx4 v[8:9], v[236:239], off
	v_lshl_add_u64 v[8:9], v[8:9], 0, v[214:215]
	s_waitcnt lgkmcnt(3)
	global_store_dwordx4 v[8:9], v[240:243], off
	v_lshl_add_u64 v[8:9], v[8:9], 0, v[214:215]
	s_waitcnt lgkmcnt(2)
	global_store_dwordx4 v[8:9], v[244:247], off
	v_lshl_add_u64 v[8:9], v[8:9], 0, v[214:215]
	s_waitcnt lgkmcnt(1)
	global_store_dwordx4 v[8:9], v[248:251], off
	v_lshl_add_u64 v[8:9], v[8:9], 0, v[214:215]
	s_waitcnt lgkmcnt(0)
	global_store_dwordx4 v[8:9], v[252:255], off
	s_mov_b64 s[10:11], 0
	s_barrier

.LBB0_179:
	v_lshl_add_u64 v[138:139], v[154:155], 0, s[12:13]
	s_mov_b64 s[26:27], 0x1020080
	v_lshl_add_u64 v[140:141], v[138:139], 0, s[26:27]
	s_mov_b64 s[26:27], 0x1000080
	v_lshl_add_u64 v[142:143], v[138:139], 0, s[26:27]
	s_mul_i32 s26, s25, 0x6000
	v_add_u32_e32 v144, s26, v156
	v_add_u32_e32 v132, 0x1000, v144
	v_readfirstlane_b32 s26, v144
	s_waitcnt vmcnt(6) lgkmcnt(0)
	s_barrier
	s_mov_b32 m0, s26
	v_readfirstlane_b32 s26, v132
	v_add_u32_e32 v134, 0x2000, v144
	global_load_lds_dwordx4 v[148:149], off
	s_mov_b32 m0, s26
	v_readfirstlane_b32 s26, v134
	v_add_u32_e32 v136, 0x3000, v144
	global_load_lds_dwordx4 v[150:151], off
	s_mov_b32 m0, s26
	v_readfirstlane_b32 s26, v136
	v_add_u32_e32 v145, 0x4000, v144
	global_load_lds_dwordx4 v[152:153], off
	s_mov_b32 m0, s26
	v_readfirstlane_b32 s26, v145
	global_load_lds_dwordx4 v[146:147], off
	s_mov_b32 m0, s26
	v_lshl_add_u64 v[130:131], v[148:149], 0, 64
	global_load_lds_dwordx4 v[142:143], off
	v_add_u32_e32 v142, 0x5000, v144
	v_lshl_add_u64 v[132:133], v[150:151], 0, 64
	v_readfirstlane_b32 s26, v142
	s_mov_b32 m0, s26
	s_mov_b64 s[26:27], 0x10000c0
	global_load_lds_dwordx4 v[140:141], off
	v_lshl_add_u64 v[140:141], v[138:139], 0, s[26:27]
	s_mov_b64 s[26:27], 0x10200c0
	v_lshl_add_u64 v[138:139], v[138:139], 0, s[26:27]
	s_mul_i32 s26, s2, 0x6000
	s_add_i32 s26, s26, 0
	v_add3_u32 v159, s26, v157, v0
	ds_read_b128 v[142:145], v159 offset:16384
	ds_read_b128 v[160:163], v159 offset:17408
	ds_read_b128 v[164:167], v159 offset:18432
	ds_read_b128 v[168:171], v159 offset:19456
	v_add3_u32 v159, s26, v158, v0
	ds_read_b128 v[172:175], v159
	ds_read_b128 v[176:179], v159 offset:1024
	ds_read_b128 v[180:183], v159 offset:2048
	ds_read_b128 v[184:187], v159 offset:3072
	s_add_i32 s26, s2, 1
	s_waitcnt lgkmcnt(0)
	s_setprio 1
	v_mfma_f32_16x16x32_bf16 v[126:129], v[142:145], v[172:175], v[126:129]
	s_cmp_lg_u32 s2, 2
	s_cselect_b32 s2, s26, 0
	s_add_i32 s26, s25, 1
	v_mfma_f32_16x16x32_bf16 v[122:125], v[160:163], v[172:175], v[122:125]
	s_cmp_lg_u32 s25, 2
	s_cselect_b32 s25, s26, 0
	s_mul_i32 s26, s25, 0x6000
	v_mfma_f32_16x16x32_bf16 v[118:121], v[164:167], v[172:175], v[118:121]
	v_lshl_add_u64 v[134:135], v[152:153], 0, 64
	v_lshl_add_u64 v[136:137], v[146:147], 0, 64
	v_lshl_add_u64 v[148:149], v[148:149], 0, s[78:79]
	v_mfma_f32_16x16x32_bf16 v[114:117], v[168:171], v[172:175], v[114:117]
	v_lshl_add_u64 v[150:151], v[150:151], 0, s[78:79]
	v_lshl_add_u64 v[152:153], v[152:153], 0, s[78:79]
	v_lshl_add_u64 v[146:147], v[146:147], 0, s[78:79]
	v_mfma_f32_16x16x32_bf16 v[110:113], v[142:145], v[176:179], v[110:113]
	v_mfma_f32_16x16x32_bf16 v[106:109], v[160:163], v[176:179], v[106:109]
	v_mfma_f32_16x16x32_bf16 v[102:105], v[164:167], v[176:179], v[102:105]
	v_mfma_f32_16x16x32_bf16 v[98:101], v[168:171], v[176:179], v[98:101]
	v_mfma_f32_16x16x32_bf16 v[94:97], v[142:145], v[180:183], v[94:97]
	v_mfma_f32_16x16x32_bf16 v[90:93], v[160:163], v[180:183], v[90:93]
	v_mfma_f32_16x16x32_bf16 v[86:89], v[164:167], v[180:183], v[86:89]
	v_mfma_f32_16x16x32_bf16 v[82:85], v[168:171], v[180:183], v[82:85]
	v_mfma_f32_16x16x32_bf16 v[78:81], v[142:145], v[184:187], v[78:81]
	v_mfma_f32_16x16x32_bf16 v[74:77], v[160:163], v[184:187], v[74:77]
	v_mfma_f32_16x16x32_bf16 v[70:73], v[164:167], v[184:187], v[70:73]
	v_mfma_f32_16x16x32_bf16 v[66:69], v[168:171], v[184:187], v[66:69]
	s_setprio 0
	ds_read_b128 v[172:175], v159 offset:4096
	ds_read_b128 v[176:179], v159 offset:5120
	ds_read_b128 v[180:183], v159 offset:6144
	ds_read_b128 v[184:187], v159 offset:7168
	s_waitcnt vmcnt(6) lgkmcnt(0)
	s_barrier
	s_waitcnt lgkmcnt(0)
	s_setprio 1
	v_mfma_f32_16x16x32_bf16 v[62:65], v[142:145], v[172:175], v[62:65]
	s_setprio 0
	s_setprio 1
	v_mfma_f32_16x16x32_bf16 v[46:49], v[142:145], v[176:179], v[46:49]
	v_mfma_f32_16x16x32_bf16 v[30:33], v[142:145], v[180:183], v[30:33]
	v_mfma_f32_16x16x32_bf16 v[14:17], v[142:145], v[184:187], v[14:17]
	v_add_u32_e32 v142, s26, v156
	s_nop 0
	v_readfirstlane_b32 s26, v142
	s_mov_b32 m0, s26
	v_mfma_f32_16x16x32_bf16 v[58:61], v[160:163], v[172:175], v[58:61]
	global_load_lds_dwordx4 v[130:131], off
	v_add_u32_e32 v130, 0x1000, v142
	v_mfma_f32_16x16x32_bf16 v[54:57], v[164:167], v[172:175], v[54:57]
	v_readfirstlane_b32 s26, v130
	v_add_u32_e32 v130, 0x2000, v142
	s_mov_b32 m0, s26
	v_readfirstlane_b32 s26, v130
	v_add_u32_e32 v130, 0x3000, v142
	global_load_lds_dwordx4 v[132:133], off
	s_mov_b32 m0, s26
	v_readfirstlane_b32 s26, v130
	v_add_u32_e32 v130, 0x4000, v142
	global_load_lds_dwordx4 v[134:135], off
	s_mov_b32 m0, s26
	v_readfirstlane_b32 s26, v130
	v_add_u32_e32 v130, 0x5000, v142
	global_load_lds_dwordx4 v[136:137], off
	s_mov_b32 m0, s26
	v_readfirstlane_b32 s26, v130
	global_load_lds_dwordx4 v[140:141], off
	s_mov_b32 m0, s26
	s_mul_i32 s26, s2, 0x6000
	global_load_lds_dwordx4 v[138:139], off
	s_add_i32 s26, s26, 0
	v_add3_u32 v142, s26, v157, v0
	v_add3_u32 v159, s26, v158, v0
	v_mfma_f32_16x16x32_bf16 v[50:53], v[168:171], v[172:175], v[50:53]
	s_setprio 0
	ds_read_b128 v[130:133], v142 offset:16384
	ds_read_b128 v[134:137], v142 offset:17408
	ds_read_b128 v[138:141], v142 offset:18432
	ds_read_b128 v[142:145], v142 offset:19456
	s_add_i32 s26, s2, 1
	s_cmp_lg_u32 s2, 2
	s_setprio 1
	v_mfma_f32_16x16x32_bf16 v[42:45], v[160:163], v[176:179], v[42:45]
	s_cselect_b32 s2, s26, 0
	s_add_i32 s26, s25, 1
	s_cmp_lg_u32 s25, 2
	v_mfma_f32_16x16x32_bf16 v[38:41], v[164:167], v[176:179], v[38:41]
	s_cselect_b32 s25, s26, 0
	s_add_u32 s12, s12, 0x80
	s_addc_u32 s13, s13, 0
	v_mfma_f32_16x16x32_bf16 v[34:37], v[168:171], v[176:179], v[34:37]
	s_cmpk_eq_i32 s12, 0x780
	v_mfma_f32_16x16x32_bf16 v[26:29], v[160:163], v[180:183], v[26:29]
	v_mfma_f32_16x16x32_bf16 v[22:25], v[164:167], v[180:183], v[22:25]
	v_mfma_f32_16x16x32_bf16 v[18:21], v[168:171], v[180:183], v[18:21]
	v_mfma_f32_16x16x32_bf16 v[10:13], v[160:163], v[184:187], v[10:13]
	v_mfma_f32_16x16x32_bf16 v[6:9], v[164:167], v[184:187], v[6:9]
	v_mfma_f32_16x16x32_bf16 v[2:5], v[168:171], v[184:187], v[2:5]
	s_setprio 0
	ds_read_b128 v[160:163], v159
	ds_read_b128 v[164:167], v159 offset:1024
	ds_read_b128 v[168:171], v159 offset:2048
	ds_read_b128 v[172:175], v159 offset:3072
	s_waitcnt lgkmcnt(0)
	s_setprio 1
	v_mfma_f32_16x16x32_bf16 v[126:129], v[130:133], v[160:163], v[126:129]
	v_mfma_f32_16x16x32_bf16 v[122:125], v[134:137], v[160:163], v[122:125]
	v_mfma_f32_16x16x32_bf16 v[118:121], v[138:141], v[160:163], v[118:121]
	v_mfma_f32_16x16x32_bf16 v[114:117], v[142:145], v[160:163], v[114:117]
	v_mfma_f32_16x16x32_bf16 v[110:113], v[130:133], v[164:167], v[110:113]
	v_mfma_f32_16x16x32_bf16 v[106:109], v[134:137], v[164:167], v[106:109]
	v_mfma_f32_16x16x32_bf16 v[102:105], v[138:141], v[164:167], v[102:105]
	v_mfma_f32_16x16x32_bf16 v[98:101], v[142:145], v[164:167], v[98:101]
	v_mfma_f32_16x16x32_bf16 v[94:97], v[130:133], v[168:171], v[94:97]
	v_mfma_f32_16x16x32_bf16 v[90:93], v[134:137], v[168:171], v[90:93]
	v_mfma_f32_16x16x32_bf16 v[86:89], v[138:141], v[168:171], v[86:89]
	v_mfma_f32_16x16x32_bf16 v[82:85], v[142:145], v[168:171], v[82:85]
	v_mfma_f32_16x16x32_bf16 v[78:81], v[130:133], v[172:175], v[78:81]
	v_mfma_f32_16x16x32_bf16 v[74:77], v[134:137], v[172:175], v[74:77]
	v_mfma_f32_16x16x32_bf16 v[70:73], v[138:141], v[172:175], v[70:73]
	v_mfma_f32_16x16x32_bf16 v[66:69], v[142:145], v[172:175], v[66:69]
	s_setprio 0
	ds_read_b128 v[160:163], v159 offset:4096
	ds_read_b128 v[164:167], v159 offset:5120
	ds_read_b128 v[168:171], v159 offset:6144
	ds_read_b128 v[172:175], v159 offset:7168
	s_waitcnt lgkmcnt(0)
	s_setprio 1
	v_mfma_f32_16x16x32_bf16 v[62:65], v[130:133], v[160:163], v[62:65]
	v_mfma_f32_16x16x32_bf16 v[58:61], v[134:137], v[160:163], v[58:61]
	v_mfma_f32_16x16x32_bf16 v[54:57], v[138:141], v[160:163], v[54:57]
	v_mfma_f32_16x16x32_bf16 v[50:53], v[142:145], v[160:163], v[50:53]
	v_mfma_f32_16x16x32_bf16 v[46:49], v[130:133], v[164:167], v[46:49]
	v_mfma_f32_16x16x32_bf16 v[42:45], v[134:137], v[164:167], v[42:45]
	v_mfma_f32_16x16x32_bf16 v[38:41], v[138:141], v[164:167], v[38:41]
	v_mfma_f32_16x16x32_bf16 v[34:37], v[142:145], v[164:167], v[34:37]
	v_mfma_f32_16x16x32_bf16 v[30:33], v[130:133], v[168:171], v[30:33]
	v_mfma_f32_16x16x32_bf16 v[26:29], v[134:137], v[168:171], v[26:29]
	v_mfma_f32_16x16x32_bf16 v[22:25], v[138:141], v[168:171], v[22:25]
	v_mfma_f32_16x16x32_bf16 v[18:21], v[142:145], v[168:171], v[18:21]
	v_mfma_f32_16x16x32_bf16 v[14:17], v[130:133], v[172:175], v[14:17]
	v_mfma_f32_16x16x32_bf16 v[10:13], v[134:137], v[172:175], v[10:13]
	v_mfma_f32_16x16x32_bf16 v[6:9], v[138:141], v[172:175], v[6:9]
	v_mfma_f32_16x16x32_bf16 v[2:5], v[142:145], v[172:175], v[2:5]
	s_setprio 0
	s_cbranch_scc0 .LBB0_179
	s_waitcnt vmcnt(6) lgkmcnt(0)
	s_barrier
	v_add3_u32 v182, 0, v157, v0
	v_add3_u32 v0, 0, v158, v0
	ds_read_b128 v[130:133], v182 offset:16384
	ds_read_b128 v[134:137], v182 offset:17408
	ds_read_b128 v[138:141], v182 offset:18432
	ds_read_b128 v[142:145], v182 offset:19456
	ds_read_b128 v[146:149], v0
	ds_read_b128 v[150:153], v0 offset:1024
	ds_read_b128 v[154:157], v0 offset:2048
	ds_read_b128 v[158:161], v0 offset:3072
	s_waitcnt lgkmcnt(0)
	v_mfma_f32_16x16x32_bf16 v[126:129], v[130:133], v[146:149], v[126:129]
	s_add_u32 s2, s19, s10
	s_addc_u32 s11, s20, s11
	s_lshl_b32 s10, s24, 1
	v_mfma_f32_16x16x32_bf16 v[122:125], v[134:137], v[146:149], v[122:125]
	s_add_u32 s10, s2, s10
	s_addc_u32 s11, s11, 0
	v_mfma_f32_16x16x32_bf16 v[118:121], v[138:141], v[146:149], v[118:121]
	v_mfma_f32_16x16x32_bf16 v[114:117], v[142:145], v[146:149], v[114:117]
	v_mfma_f32_16x16x32_bf16 v[110:113], v[130:133], v[150:153], v[110:113]
	v_mfma_f32_16x16x32_bf16 v[106:109], v[134:137], v[150:153], v[106:109]
	v_mfma_f32_16x16x32_bf16 v[102:105], v[138:141], v[150:153], v[102:105]
	v_mfma_f32_16x16x32_bf16 v[98:101], v[142:145], v[150:153], v[98:101]
	v_mfma_f32_16x16x32_bf16 v[94:97], v[130:133], v[154:157], v[94:97]
	v_mfma_f32_16x16x32_bf16 v[90:93], v[134:137], v[154:157], v[90:93]
	v_mfma_f32_16x16x32_bf16 v[146:149], v[138:141], v[154:157], v[86:89]
	v_mfma_f32_16x16x32_bf16 v[82:85], v[142:145], v[154:157], v[82:85]
	v_mfma_f32_16x16x32_bf16 v[150:153], v[130:133], v[158:161], v[78:81]
	v_mfma_f32_16x16x32_bf16 v[74:77], v[134:137], v[158:161], v[74:77]
	v_mfma_f32_16x16x32_bf16 v[70:73], v[138:141], v[158:161], v[70:73]
	v_mfma_f32_16x16x32_bf16 v[154:157], v[142:145], v[158:161], v[66:69]
	s_nop 2
	ds_read_b128 v[66:69], v0 offset:4096
	ds_read_b128 v[78:81], v0 offset:5120
	ds_read_b128 v[86:89], v0 offset:6144
	ds_read_b128 v[158:161], v0 offset:7168
	s_waitcnt vmcnt(0) lgkmcnt(0)
	s_barrier
	s_waitcnt lgkmcnt(0)
	v_mfma_f32_16x16x32_bf16 v[62:65], v[130:133], v[66:69], v[62:65]
	v_mfma_f32_16x16x32_bf16 v[162:165], v[134:137], v[66:69], v[58:61]
	v_mfma_f32_16x16x32_bf16 v[166:169], v[138:141], v[66:69], v[54:57]
	v_mfma_f32_16x16x32_bf16 v[50:53], v[142:145], v[66:69], v[50:53]
	v_mfma_f32_16x16x32_bf16 v[170:173], v[130:133], v[78:81], v[46:49]
	v_mfma_f32_16x16x32_bf16 v[42:45], v[134:137], v[78:81], v[42:45]
	v_mfma_f32_16x16x32_bf16 v[38:41], v[138:141], v[78:81], v[38:41]
	v_mfma_f32_16x16x32_bf16 v[174:177], v[142:145], v[78:81], v[34:37]
	v_mfma_f32_16x16x32_bf16 v[30:33], v[130:133], v[86:89], v[30:33]
	v_mfma_f32_16x16x32_bf16 v[178:181], v[134:137], v[86:89], v[26:29]
	v_mfma_f32_16x16x32_bf16 v[22:25], v[138:141], v[86:89], v[22:25]
	v_mfma_f32_16x16x32_bf16 v[18:21], v[142:145], v[86:89], v[18:21]
	v_mfma_f32_16x16x32_bf16 v[14:17], v[130:133], v[158:161], v[14:17]
	v_mfma_f32_16x16x32_bf16 v[10:13], v[134:137], v[158:161], v[10:13]
	v_mfma_f32_16x16x32_bf16 v[6:9], v[138:141], v[158:161], v[6:9]
	v_mfma_f32_16x16x32_bf16 v[2:5], v[142:145], v[158:161], v[2:5]
	ds_read_b128 v[130:133], v182 offset:40960
	ds_read_b128 v[134:137], v182 offset:41984
	ds_read_b128 v[138:141], v182 offset:43008
	ds_read_b128 v[142:145], v182 offset:44032
	ds_read_b128 v[26:29], v0 offset:24576
	ds_read_b128 v[34:37], v0 offset:25600
	ds_read_b128 v[46:49], v0 offset:26624
	ds_read_b128 v[158:161], v0 offset:27648
	s_waitcnt lgkmcnt(0)
	v_mfma_f32_16x16x32_bf16 v[110:113], v[130:133], v[34:37], v[110:113]
	v_mfma_f32_16x16x32_bf16 v[106:109], v[134:137], v[34:37], v[106:109]
	v_mfma_f32_16x16x32_bf16 v[102:105], v[138:141], v[34:37], v[102:105]
	v_mfma_f32_16x16x32_bf16 v[98:101], v[142:145], v[34:37], v[98:101]
	v_mfma_f32_16x16x32_bf16 v[86:89], v[130:133], v[46:49], v[94:97]
	v_mfma_f32_16x16x32_bf16 v[78:81], v[134:137], v[46:49], v[90:93]
	v_mfma_f32_16x16x32_bf16 v[66:69], v[138:141], v[46:49], v[146:149]
	s_nop 5
	v_cvt_pk_bf16_f32 v86, v86, v87
	v_cvt_pk_bf16_f32 v78, v78, v79
	v_cvt_pk_bf16_f32 v79, v80, v81
	v_mfma_f32_16x16x32_bf16 v[34:37], v[138:141], v[158:161], v[70:73]
	s_nop 2
	ds_read_b128 v[70:73], v0 offset:28672
	ds_read_b128 v[90:93], v0 offset:29696
	ds_read_b128 v[94:97], v0 offset:30720
	ds_read_b128 v[146:149], v0 offset:31744
	s_waitcnt vmcnt(0) lgkmcnt(0)
	s_barrier
	v_mfma_f32_16x16x32_bf16 v[126:129], v[130:133], v[26:29], v[126:129]
	v_cvt_pk_bf16_f32 v34, v34, v35
	v_cvt_pk_bf16_f32 v35, v36, v37
	v_mfma_f32_16x16x32_bf16 v[122:125], v[134:137], v[26:29], v[122:125]
	v_cvt_pk_bf16_f32 v66, v66, v67
	v_cvt_pk_bf16_f32 v67, v68, v69
	v_cvt_pk_bf16_f32 v87, v88, v89
	v_mfma_f32_16x16x32_bf16 v[118:121], v[138:141], v[26:29], v[118:121]
	v_mfma_f32_16x16x32_bf16 v[114:117], v[142:145], v[26:29], v[114:117]
	v_mfma_f32_16x16x32_bf16 v[58:61], v[142:145], v[46:49], v[82:85]
	v_mfma_f32_16x16x32_bf16 v[54:57], v[130:133], v[158:161], v[150:153]
	v_mfma_f32_16x16x32_bf16 v[46:49], v[134:137], v[158:161], v[74:77]
	s_nop 5
	v_cvt_pk_bf16_f32 v58, v58, v59
	v_cvt_pk_bf16_f32 v59, v60, v61
	v_cvt_pk_bf16_f32 v54, v54, v55
	v_mfma_f32_16x16x32_bf16 v[26:29], v[142:145], v[158:161], v[154:157]
	v_cvt_pk_bf16_f32 v55, v56, v57
	v_cvt_pk_bf16_f32 v46, v46, v47
	v_cvt_pk_bf16_f32 v47, v48, v49
	v_mfma_f32_16x16x32_bf16 v[150:153], v[130:133], v[70:73], v[62:65]
	v_mfma_f32_16x16x32_bf16 v[154:157], v[134:137], v[70:73], v[162:165]
	s_nop 2
	v_cvt_pk_bf16_f32 v26, v26, v27
	v_cvt_pk_bf16_f32 v27, v28, v29
	v_mfma_f32_16x16x32_bf16 v[82:85], v[138:141], v[70:73], v[166:169]
	v_mfma_f32_16x16x32_bf16 v[74:77], v[142:145], v[70:73], v[50:53]
	s_nop 0
	v_cvt_pk_bf16_f32 v28, v154, v155
	v_cvt_pk_bf16_f32 v29, v156, v157
	v_mfma_f32_16x16x32_bf16 v[70:73], v[130:133], v[90:93], v[170:173]
	v_mfma_f32_16x16x32_bf16 v[62:65], v[134:137], v[90:93], v[42:45]
	v_mfma_f32_16x16x32_bf16 v[50:53], v[138:141], v[90:93], v[38:41]
	v_mfma_f32_16x16x32_bf16 v[42:45], v[142:145], v[90:93], v[174:177]
	v_mov_b32_e32 v90, v196
	s_nop 0
	v_and_b32_e32 v0, 64, v90
	v_lshrrev_b32_e32 v92, 1, v90
	v_lshlrev_b32_e32 v0, 1, v0
	v_and_b32_e32 v92, 24, v92
	v_and_b32_e32 v91, 0xfffff8f, v90
	v_add3_u32 v0, 0, v0, v92
	v_mad_u64_u32 v[92:93], s[12:13], v91, s30, v[0:1]
	v_add_u32_e32 v48, 0x3000, v92
	v_mfma_f32_16x16x32_bf16 v[38:41], v[130:133], v[94:97], v[30:33]
	ds_write2_b64 v48, v[34:35], v[26:27] offset0:104 offset1:108
	v_cvt_pk_bf16_f32 v26, v150, v151
	v_cvt_pk_bf16_f32 v27, v152, v153
	v_mfma_f32_16x16x32_bf16 v[30:33], v[134:137], v[94:97], v[178:181]
	v_add_u32_e32 v34, 0x4000, v92
	ds_write2_b64 v34, v[26:27], v[28:29] offset0:128 offset1:132
	v_cvt_pk_bf16_f32 v26, v82, v83
	v_mfma_f32_16x16x32_bf16 v[22:25], v[138:141], v[94:97], v[22:25]
	v_cvt_pk_bf16_f32 v27, v84, v85
	v_cvt_pk_bf16_f32 v28, v74, v75
	v_cvt_pk_bf16_f32 v29, v76, v77
	v_mfma_f32_16x16x32_bf16 v[18:21], v[142:145], v[94:97], v[18:21]
	ds_write2_b64 v34, v[26:27], v[28:29] offset0:136 offset1:140
	v_cvt_pk_bf16_f32 v26, v70, v71
	v_cvt_pk_bf16_f32 v27, v72, v73
	v_cvt_pk_bf16_f32 v28, v62, v63
	v_cvt_pk_bf16_f32 v29, v64, v65
	v_add_u32_e32 v34, 0x5000, v92
	v_mfma_f32_16x16x32_bf16 v[6:9], v[138:141], v[146:149], v[6:9]
	ds_write2_b64 v34, v[26:27], v[28:29] offset0:160 offset1:164
	v_cvt_pk_bf16_f32 v26, v50, v51
	v_cvt_pk_bf16_f32 v27, v52, v53
	v_mfma_f32_16x16x32_bf16 v[2:5], v[142:145], v[146:149], v[2:5]
	v_cvt_pk_bf16_f32 v28, v42, v43
	v_cvt_pk_bf16_f32 v29, v44, v45
	v_cvt_pk_bf16_f32 v94, v126, v127
	v_cvt_pk_bf16_f32 v95, v128, v129
	v_cvt_pk_bf16_f32 v96, v122, v123
	v_cvt_pk_bf16_f32 v97, v124, v125
	ds_write2_b64 v34, v[26:27], v[28:29] offset0:168 offset1:172
	v_cvt_pk_bf16_f32 v28, v30, v31
	v_add_u32_e32 v30, 0x6000, v92
	v_cvt_pk_bf16_f32 v22, v22, v23
	v_cvt_pk_bf16_f32 v23, v24, v25
	v_cvt_pk_bf16_f32 v18, v18, v19
	v_cvt_pk_bf16_f32 v19, v20, v21
	v_mfma_f32_16x16x32_bf16 v[14:17], v[130:133], v[146:149], v[14:17]
	ds_write2_b64 v92, v[94:95], v[96:97] offset1:4
	v_cvt_pk_bf16_f32 v94, v118, v119
	v_cvt_pk_bf16_f32 v95, v120, v121
	v_mfma_f32_16x16x32_bf16 v[10:13], v[134:137], v[146:149], v[10:13]
	v_cvt_pk_bf16_f32 v96, v114, v115
	v_cvt_pk_bf16_f32 v97, v116, v117
	ds_write2_b64 v30, v[22:23], v[18:19] offset0:200 offset1:204
	v_or_b32_e32 v18, 0x70, v90
	ds_write2_b64 v92, v[94:95], v[96:97] offset0:8 offset1:12
	v_cvt_pk_bf16_f32 v94, v110, v111
	v_cvt_pk_bf16_f32 v95, v112, v113
	v_cvt_pk_bf16_f32 v96, v106, v107
	v_cvt_pk_bf16_f32 v97, v108, v109
	v_add_u32_e32 v91, 0x1000, v92
	v_mad_u64_u32 v[18:19], s[12:13], v18, s30, v[0:1]
	v_lshlrev_b32_e32 v0, 4, v90
	ds_write2_b64 v91, v[94:95], v[96:97] offset0:32 offset1:36
	v_cvt_pk_bf16_f32 v94, v102, v103
	v_cvt_pk_bf16_f32 v95, v104, v105
	v_cvt_pk_bf16_f32 v96, v98, v99
	v_cvt_pk_bf16_f32 v97, v100, v101
	v_add_u32_e32 v80, 0x2000, v92
	v_cvt_pk_bf16_f32 v6, v6, v7
	v_cvt_pk_bf16_f32 v7, v8, v9
	v_cvt_pk_bf16_f32 v2, v2, v3
	v_cvt_pk_bf16_f32 v3, v4, v5
	v_and_b32_e32 v0, 0xf0, v0
	v_ashrrev_i32_e32 v4, 4, v90
	ds_write2_b64 v91, v[94:95], v[96:97] offset0:40 offset1:44
	ds_write2_b64 v80, v[66:67], v[58:59] offset0:72 offset1:76
	ds_write2_b64 v18, v[6:7], v[2:3] offset0:8 offset1:12
	v_lshl_add_u64 v[2:3], s[10:11], 0, v[0:1]
	v_add_u32_e32 v0, 0, v0
	v_ashrrev_i32_e32 v5, 31, v4
	v_cvt_pk_bf16_f32 v26, v38, v39
	v_cvt_pk_bf16_f32 v27, v40, v41
	v_cvt_pk_bf16_f32 v29, v32, v33
	v_cvt_pk_bf16_f32 v14, v14, v15
	v_cvt_pk_bf16_f32 v15, v16, v17
	v_cvt_pk_bf16_f32 v10, v10, v11
	v_cvt_pk_bf16_f32 v11, v12, v13
	v_mad_u64_u32 v[6:7], s[10:11], v4, s30, v[0:1]
	v_lshlrev_b64 v[4:5], 11, v[4:5]
	ds_write2_b64 v80, v[86:87], v[78:79] offset0:64 offset1:68
	ds_write2_b64 v48, v[54:55], v[46:47] offset0:96 offset1:100
	ds_write2_b64 v30, v[26:27], v[28:29] offset0:192 offset1:196
	ds_write2_b64 v18, v[14:15], v[10:11] offset1:4
	s_waitcnt lgkmcnt(0)
	s_barrier
	v_lshl_add_u64 v[8:9], v[2:3], 0, v[4:5]
	v_mov_b32_e32 v214, 0x8000
	v_mov_b32_e32 v215, 0
	ds_read_b128 v[216:219], v6
	ds_read_b128 v[228:231], v6 offset:4352
	ds_read_b128 v[232:235], v6 offset:8704
	ds_read_b128 v[236:239], v6 offset:13056
	ds_read_b128 v[240:243], v6 offset:17408
	ds_read_b128 v[244:247], v6 offset:21760
	ds_read_b128 v[248:251], v6 offset:26112
	ds_read_b128 v[252:255], v6 offset:30464
	s_waitcnt lgkmcnt(7)
	global_store_dwordx4 v[8:9], v[216:219], off
	v_lshl_add_u64 v[8:9], v[8:9], 0, v[214:215]
	s_waitcnt lgkmcnt(6)
	global_store_dwordx4 v[8:9], v[228:231], off
	v_lshl_add_u64 v[8:9], v[8:9], 0, v[214:215]
	s_waitcnt lgkmcnt(5)
	global_store_dwordx4 v[8:9], v[232:235], off
	v_lshl_add_u64 v[8:9], v[8:9], 0, v[214:215]
	s_waitcnt lgkmcnt(4)
	global_store_dwordx4 v[8:9], v[236:239], off
	v_lshl_add_u64 v[8:9], v[8:9], 0, v[214:215]
	s_waitcnt lgkmcnt(3)
	global_store_dwordx4 v[8:9], v[240:243], off
	v_lshl_add_u64 v[8:9], v[8:9], 0, v[214:215]
	s_waitcnt lgkmcnt(2)
	global_store_dwordx4 v[8:9], v[244:247], off
	v_lshl_add_u64 v[8:9], v[8:9], 0, v[214:215]
	s_waitcnt lgkmcnt(1)
	global_store_dwordx4 v[8:9], v[248:251], off
	v_lshl_add_u64 v[8:9], v[8:9], 0, v[214:215]
	s_waitcnt lgkmcnt(0)
	global_store_dwordx4 v[8:9], v[252:255], off
	v_lshl_add_u64 v[8:9], v[8:9], 0, v[214:215]
	ds_read_b128 v[216:219], v6 offset:34816
	ds_read_b128 v[228:231], v6 offset:39168
	ds_read_b128 v[232:235], v6 offset:43520
	ds_read_b128 v[236:239], v6 offset:47872
	ds_read_b128 v[240:243], v6 offset:52224
	ds_read_b128 v[244:247], v6 offset:56576
	ds_read_b128 v[248:251], v6 offset:60928
	ds_read_b128 v[252:255], v6 offset:65280
	s_waitcnt lgkmcnt(7)
	global_store_dwordx4 v[8:9], v[216:219], off
	v_lshl_add_u64 v[8:9], v[8:9], 0, v[214:215]
	s_waitcnt lgkmcnt(6)
	global_store_dwordx4 v[8:9], v[228:231], off
	v_lshl_add_u64 v[8:9], v[8:9], 0, v[214:215]
	s_waitcnt lgkmcnt(5)
	global_store_dwordx4 v[8:9], v[232:235], off
	v_lshl_add_u64 v[8:9], v[8:9], 0, v[214:215]
	s_waitcnt lgkmcnt(4)
	global_store_dwordx4 v[8:9], v[236:239], off
	v_lshl_add_u64 v[8:9], v[8:9], 0, v[214:215]
	s_waitcnt lgkmcnt(3)
	global_store_dwordx4 v[8:9], v[240:243], off
	v_lshl_add_u64 v[8:9], v[8:9], 0, v[214:215]
	s_waitcnt lgkmcnt(2)
	global_store_dwordx4 v[8:9], v[244:247], off
	v_lshl_add_u64 v[8:9], v[8:9], 0, v[214:215]
	s_waitcnt lgkmcnt(1)
	global_store_dwordx4 v[8:9], v[248:251], off
	v_lshl_add_u64 v[8:9], v[8:9], 0, v[214:215]
	s_waitcnt lgkmcnt(0)
	global_store_dwordx4 v[8:9], v[252:255], off
	s_barrier
	s_branch .LBB0_172

.LBB0_199:
	s_abs_i32 s1, s15
	s_mul_hi_u32 s2, s1, s14
	s_mul_i32 s8, s2, s10
	s_sub_i32 s1, s1, s8
	s_ashr_i32 s0, s15, 31
	s_add_i32 s8, s2, 1
	s_sub_i32 s9, s1, s10
	s_cmp_ge_u32 s1, s10
	s_cselect_b32 s2, s8, s2
	s_cselect_b32 s1, s9, s1
	s_add_i32 s8, s2, 1
	s_cmp_ge_u32 s1, s10
	s_cselect_b32 s1, s8, s2
	s_xor_b32 s1, s1, s0
	s_sub_i32 s0, s1, s0
	s_mul_i32 s1, s0, s10
	s_sub_i32 s18, s15, s1
	s_cmp_eq_u32 s0, 1
	s_mov_b32 s1, 0x8b7c000
	s_cselect_b32 s1, s1, 0xac7c000
	s_cselect_b32 s2, s81, 0x1a81c000
	s_cmp_eq_u32 s0, 0
	s_cselect_b32 s1, 0x1871c000, s1
	v_readlane_b32 s22, v225, 48
	s_cselect_b32 s2, 0xe21c000, s2
	v_readlane_b32 s23, v225, 49
	s_add_u32 s8, s22, s1
	s_addc_u32 s9, s23, 0
	s_ashr_i32 s1, s0, 31
	s_lshl_b64 s[0:1], s[0:1], 20
	s_add_u32 s19, s12, s0
	s_addc_u32 s20, s13, s1
	s_add_u32 s17, s22, s2
	s_addc_u32 s16, s23, 0
	s_cmpk_gt_i32 s18, 0x3ff
	s_mov_b64 s[0:1], -1
	s_cbranch_scc0 .LBB0_201
	s_lshl_b32 s0, s18, 4
	s_add_i32 s0, s0, 0x7fffc000
	s_and_b32 s0, s0, 0x7fffff80
	s_add_i32 s2, s0, 0x8000
	s_lshl_b32 s0, s15, 7
	v_mov_b32_e32 v10, v196
	s_and_b32 s0, s0, 0x380
	s_lshl_b64 s[22:23], s[2:3], 10
	s_add_u32 s22, s8, s22
	v_lshrrev_b32_e32 v0, 2, v10
	v_and_b32_e32 v0, 12, v0
	s_addc_u32 s23, s9, s23
	s_lshl_b32 s1, s0, 10
	v_lshrrev_b32_e64 v0, v0, s57
	s_add_u32 s24, s19, s1
	v_xor_b32_e32 v0, v0, v10
	v_and_b32_e32 v13, 15, v10
	v_lshrrev_b32_e32 v14, 1, v10
	s_mov_b32 s1, 0x3ffffc0
	v_ashrrev_i32_e32 v2, 2, v10
	v_lshlrev_b32_e32 v0, 4, v0
	v_and_or_b32 v15, v14, s1, v13
	v_and_b32_e32 v13, 12, v10
	v_lshrrev_b32_e32 v12, 4, v10
	v_and_b32_e32 v0, 48, v0
	v_ashrrev_i32_e32 v3, 31, v2
	v_lshl_add_u32 v11, v10, 4, 0
	v_lshrrev_b32_e64 v13, v13, s57
	v_lshl_add_u64 v[4:5], s[22:23], 0, v[0:1]
	v_lshlrev_b64 v[6:7], 10, v[2:3]
	s_mov_b64 s[22:23], 0x10000
	v_xor_b32_e32 v12, v13, v12
	v_readfirstlane_b32 s36, v11
	v_add_u32_e32 v13, 0x1000, v11
	s_addc_u32 s25, s20, 0
	v_lshl_add_u64 v[2:3], v[4:5], 0, v[6:7]
	v_lshl_add_u64 v[8:9], v[6:7], 0, s[22:23]
	v_lshlrev_b32_e32 v12, 4, v12
	s_mov_b32 m0, s36
	v_readfirstlane_b32 s37, v13
	v_add_u32_e32 v14, 0x2000, v11
	v_lshl_add_u64 v[4:5], v[4:5], 0, v[8:9]
	v_lshl_add_u64 v[8:9], s[24:25], 0, v[8:9]
	global_load_lds_dwordx4 v[2:3], off
	s_mov_b32 m0, s37
	v_lshl_add_u64 v[6:7], s[24:25], 0, v[6:7]
	v_and_b32_e32 v32, 48, v12
	v_readfirstlane_b32 s38, v14
	v_add_u32_e32 v12, 0x3000, v11
	global_load_lds_dwordx4 v[4:5], off
	v_lshl_add_u64 v[6:7], v[6:7], 0, v[0:1]
	v_lshl_add_u64 v[8:9], v[8:9], 0, v[0:1]
	s_mov_b32 m0, s38
	v_readfirstlane_b32 s39, v12
	v_add_u32_e32 v0, 0x4000, v11
	global_load_lds_dwordx4 v[6:7], off
	s_mov_b32 m0, s39
	v_readfirstlane_b32 s24, v0
	v_add_u32_e32 v0, 0x5000, v11
	v_lshl_add_u64 v[16:17], v[2:3], 0, 64
	global_load_lds_dwordx4 v[8:9], off
	s_mov_b32 m0, s24
	v_readfirstlane_b32 s25, v0
	v_add_u32_e32 v0, 0x6000, v11
	v_lshl_add_u64 v[18:19], v[4:5], 0, 64
	global_load_lds_dwordx4 v[16:17], off
	s_mov_b32 m0, s25
	v_readfirstlane_b32 s26, v0
	v_add_u32_e32 v0, 0x7000, v11
	v_lshl_add_u64 v[20:21], v[6:7], 0, 64
	global_load_lds_dwordx4 v[18:19], off
	s_mov_b32 m0, s26
	v_readfirstlane_b32 s27, v0
	v_lshl_add_u64 v[16:17], v[8:9], 0, 64
	global_load_lds_dwordx4 v[20:21], off
	s_mov_b32 m0, s27
	v_add_u32_e32 v0, 0x8000, v11
	global_load_lds_dwordx4 v[16:17], off
	v_add_u32_e32 v26, 0x9000, v11
	v_readfirstlane_b32 s23, v0
	v_lshl_add_u64 v[22:23], v[2:3], 0, s[78:79]
	s_waitcnt vmcnt(4) lgkmcnt(0)
	s_barrier
	v_add_u32_e32 v25, 0xa000, v11
	s_mov_b32 m0, s23
	v_readfirstlane_b32 s22, v26
	v_lshl_add_u64 v[20:21], v[4:5], 0, s[78:79]
	v_add_u32_e32 v24, 0xb000, v11
	global_load_lds_dwordx4 v[22:23], off
	s_mov_b32 m0, s22
	v_readfirstlane_b32 s21, v25
	v_lshlrev_b32_e32 v10, 6, v10
	v_lshl_add_u64 v[16:17], v[6:7], 0, s[78:79]
	global_load_lds_dwordx4 v[20:21], off
	s_mov_b32 m0, s21
	v_readfirstlane_b32 s1, v24
	v_and_b32_e32 v10, 0x13c0, v10
	v_lshlrev_b32_e32 v15, 6, v15
	v_lshl_add_u64 v[18:19], v[8:9], 0, s[78:79]
	global_load_lds_dwordx4 v[16:17], off
	s_mov_b32 m0, s1
	v_add3_u32 v0, 0, v10, v32
	global_load_lds_dwordx4 v[18:19], off
	v_add3_u32 v10, 0, v15, v32
	v_lshl_add_u64 v[88:89], v[2:3], 0, s[84:85]
	ds_read_b128 v[16:19], v0 offset:8192
	ds_read_b128 v[20:23], v0 offset:9216
	ds_read_b128 v[24:27], v0 offset:10240
	ds_read_b128 v[28:31], v0 offset:11264
	ds_read_b128 v[32:35], v10
	ds_read_b128 v[36:39], v10 offset:1024
	ds_read_b128 v[40:43], v10 offset:2048
	ds_read_b128 v[44:47], v10 offset:3072
	s_waitcnt vmcnt(4) lgkmcnt(0)
	s_barrier
	s_mov_b32 m0, s36
	v_lshl_add_u64 v[90:91], v[4:5], 0, s[84:85]
	global_load_lds_dwordx4 v[88:89], off
	s_mov_b32 m0, s37
	v_lshl_add_u64 v[86:87], v[6:7], 0, s[84:85]
	global_load_lds_dwordx4 v[90:91], off
	s_mov_b32 m0, s38
	v_lshl_add_u64 v[84:85], v[8:9], 0, s[84:85]
	global_load_lds_dwordx4 v[86:87], off
	s_mov_b32 m0, s39
	s_mov_b64 s[40:41], 0x100
	global_load_lds_dwordx4 v[84:85], off
	s_waitcnt lgkmcnt(0)
	s_setprio 1
	v_mfma_f32_16x16x32_bf16 v[48:51], v[16:19], v[32:35], 0
	v_lshl_add_u64 v[116:117], v[2:3], 0, s[40:41]
	s_mov_b32 m0, s24
	v_lshl_add_u64 v[118:119], v[4:5], 0, s[40:41]
	v_mfma_f32_16x16x32_bf16 v[52:55], v[20:23], v[32:35], 0
	v_lshl_add_u64 v[114:115], v[6:7], 0, s[40:41]
	v_lshl_add_u64 v[112:113], v[8:9], 0, s[40:41]
	s_mov_b64 s[40:41], 0x140
	v_mfma_f32_16x16x32_bf16 v[56:59], v[24:27], v[32:35], 0
	v_lshl_add_u64 v[124:125], v[2:3], 0, s[40:41]
	v_lshl_add_u64 v[126:127], v[4:5], 0, s[40:41]
	v_lshl_add_u64 v[122:123], v[6:7], 0, s[40:41]
	v_mfma_f32_16x16x32_bf16 v[32:35], v[28:31], v[32:35], 0
	v_lshl_add_u64 v[120:121], v[8:9], 0, s[40:41]
	s_mov_b64 s[40:41], 0x180
	v_readlane_b32 s88, v225, 56
	v_mfma_f32_16x16x32_bf16 v[60:63], v[16:19], v[36:39], 0
	v_mfma_f32_16x16x32_bf16 v[64:67], v[20:23], v[36:39], 0
	v_mfma_f32_16x16x32_bf16 v[68:71], v[24:27], v[36:39], 0
	v_mfma_f32_16x16x32_bf16 v[36:39], v[28:31], v[36:39], 0
	v_mfma_f32_16x16x32_bf16 v[72:75], v[16:19], v[40:43], 0
	v_mfma_f32_16x16x32_bf16 v[76:79], v[20:23], v[40:43], 0
	v_mfma_f32_16x16x32_bf16 v[80:83], v[24:27], v[40:43], 0
	v_mfma_f32_16x16x32_bf16 v[40:43], v[28:31], v[40:43], 0
	v_mfma_f32_16x16x32_bf16 v[16:19], v[16:19], v[44:47], 0
	v_mfma_f32_16x16x32_bf16 v[20:23], v[20:23], v[44:47], 0
	v_mfma_f32_16x16x32_bf16 v[24:27], v[24:27], v[44:47], 0
	v_mfma_f32_16x16x32_bf16 v[28:31], v[28:31], v[44:47], 0
	s_setprio 0
	ds_read_b128 v[44:47], v0 offset:24576
	ds_read_b128 v[84:87], v0 offset:25600
	ds_read_b128 v[88:91], v0 offset:26624
	ds_read_b128 v[92:95], v0 offset:27648
	ds_read_b128 v[96:99], v10 offset:16384
	ds_read_b128 v[100:103], v10 offset:17408
	ds_read_b128 v[104:107], v10 offset:18432
	ds_read_b128 v[108:111], v10 offset:19456
	s_waitcnt vmcnt(4) lgkmcnt(0)
	s_barrier
	global_load_lds_dwordx4 v[116:117], off
	s_mov_b32 m0, s25
	s_waitcnt lgkmcnt(0)
	s_setprio 1
	v_mfma_f32_16x16x32_bf16 v[48:51], v[44:47], v[96:99], v[48:51]
	global_load_lds_dwordx4 v[118:119], off
	s_mov_b32 m0, s26
	v_mfma_f32_16x16x32_bf16 v[52:55], v[84:87], v[96:99], v[52:55]
	global_load_lds_dwordx4 v[114:115], off
	s_mov_b32 m0, s27
	v_mfma_f32_16x16x32_bf16 v[56:59], v[88:91], v[96:99], v[56:59]
	global_load_lds_dwordx4 v[112:113], off
	s_mov_b32 m0, s23
	v_mfma_f32_16x16x32_bf16 v[32:35], v[92:95], v[96:99], v[32:35]
	v_lshl_add_u64 v[116:117], v[2:3], 0, s[40:41]
	v_lshl_add_u64 v[118:119], v[4:5], 0, s[40:41]
	v_lshl_add_u64 v[114:115], v[6:7], 0, s[40:41]
	v_mfma_f32_16x16x32_bf16 v[60:63], v[44:47], v[100:103], v[60:63]
	v_lshl_add_u64 v[112:113], v[8:9], 0, s[40:41]
	s_mov_b64 s[40:41], 0x1c0
	v_mfma_f32_16x16x32_bf16 v[64:67], v[84:87], v[100:103], v[64:67]
	v_mfma_f32_16x16x32_bf16 v[68:71], v[88:91], v[100:103], v[68:71]
	v_mfma_f32_16x16x32_bf16 v[36:39], v[92:95], v[100:103], v[36:39]
	v_mfma_f32_16x16x32_bf16 v[72:75], v[44:47], v[104:107], v[72:75]
	v_mfma_f32_16x16x32_bf16 v[76:79], v[84:87], v[104:107], v[76:79]
	v_mfma_f32_16x16x32_bf16 v[80:83], v[88:91], v[104:107], v[80:83]
	v_mfma_f32_16x16x32_bf16 v[40:43], v[92:95], v[104:107], v[40:43]
	v_mfma_f32_16x16x32_bf16 v[16:19], v[44:47], v[108:111], v[16:19]
	v_mfma_f32_16x16x32_bf16 v[20:23], v[84:87], v[108:111], v[20:23]
	v_mfma_f32_16x16x32_bf16 v[24:27], v[88:91], v[108:111], v[24:27]
	v_mfma_f32_16x16x32_bf16 v[28:31], v[92:95], v[108:111], v[28:31]
	s_setprio 0
	ds_read_b128 v[44:47], v0 offset:40960
	ds_read_b128 v[84:87], v0 offset:41984
	ds_read_b128 v[88:91], v0 offset:43008
	ds_read_b128 v[92:95], v0 offset:44032
	ds_read_b128 v[96:99], v10 offset:32768
	ds_read_b128 v[100:103], v10 offset:33792
	ds_read_b128 v[104:107], v10 offset:34816
	ds_read_b128 v[108:111], v10 offset:35840
	s_waitcnt vmcnt(4) lgkmcnt(0)
	s_barrier
	global_load_lds_dwordx4 v[124:125], off
	s_mov_b32 m0, s22
	s_waitcnt lgkmcnt(0)
	s_setprio 1
	v_mfma_f32_16x16x32_bf16 v[48:51], v[44:47], v[96:99], v[48:51]
	global_load_lds_dwordx4 v[126:127], off
	s_mov_b32 m0, s21
	v_mfma_f32_16x16x32_bf16 v[52:55], v[84:87], v[96:99], v[52:55]
	global_load_lds_dwordx4 v[122:123], off
	s_mov_b32 m0, s1
	v_mfma_f32_16x16x32_bf16 v[56:59], v[88:91], v[96:99], v[56:59]
	global_load_lds_dwordx4 v[120:121], off
	s_mov_b32 m0, s36
	v_mfma_f32_16x16x32_bf16 v[32:35], v[92:95], v[96:99], v[32:35]
	v_lshl_add_u64 v[124:125], v[2:3], 0, s[40:41]
	v_lshl_add_u64 v[126:127], v[4:5], 0, s[40:41]
	v_lshl_add_u64 v[122:123], v[6:7], 0, s[40:41]
	v_mfma_f32_16x16x32_bf16 v[60:63], v[44:47], v[100:103], v[60:63]
	v_lshl_add_u64 v[120:121], v[8:9], 0, s[40:41]
	s_mov_b64 s[40:41], 0x200
	v_mfma_f32_16x16x32_bf16 v[64:67], v[84:87], v[100:103], v[64:67]
	v_mfma_f32_16x16x32_bf16 v[68:71], v[88:91], v[100:103], v[68:71]
	v_mfma_f32_16x16x32_bf16 v[36:39], v[92:95], v[100:103], v[36:39]
	v_mfma_f32_16x16x32_bf16 v[72:75], v[44:47], v[104:107], v[72:75]
	v_mfma_f32_16x16x32_bf16 v[76:79], v[84:87], v[104:107], v[76:79]
	v_mfma_f32_16x16x32_bf16 v[80:83], v[88:91], v[104:107], v[80:83]
	v_mfma_f32_16x16x32_bf16 v[40:43], v[92:95], v[104:107], v[40:43]
	v_mfma_f32_16x16x32_bf16 v[16:19], v[44:47], v[108:111], v[16:19]
	v_mfma_f32_16x16x32_bf16 v[20:23], v[84:87], v[108:111], v[20:23]
	v_mfma_f32_16x16x32_bf16 v[24:27], v[88:91], v[108:111], v[24:27]
	v_mfma_f32_16x16x32_bf16 v[28:31], v[92:95], v[108:111], v[28:31]
	s_setprio 0
	ds_read_b128 v[44:47], v0 offset:8192
	ds_read_b128 v[84:87], v0 offset:9216
	ds_read_b128 v[88:91], v0 offset:10240
	ds_read_b128 v[92:95], v0 offset:11264
	ds_read_b128 v[96:99], v10
	ds_read_b128 v[100:103], v10 offset:1024
	ds_read_b128 v[104:107], v10 offset:2048
	ds_read_b128 v[108:111], v10 offset:3072
	s_waitcnt vmcnt(4) lgkmcnt(0)
	s_barrier
	global_load_lds_dwordx4 v[116:117], off
	s_mov_b32 m0, s37
	s_waitcnt lgkmcnt(0)
	s_setprio 1
	v_mfma_f32_16x16x32_bf16 v[48:51], v[44:47], v[96:99], v[48:51]
	global_load_lds_dwordx4 v[118:119], off
	s_mov_b32 m0, s38
	v_mfma_f32_16x16x32_bf16 v[52:55], v[84:87], v[96:99], v[52:55]
	global_load_lds_dwordx4 v[114:115], off
	s_mov_b32 m0, s39
	v_mfma_f32_16x16x32_bf16 v[56:59], v[88:91], v[96:99], v[56:59]
	global_load_lds_dwordx4 v[112:113], off
	s_mov_b32 m0, s24
	v_mfma_f32_16x16x32_bf16 v[32:35], v[92:95], v[96:99], v[32:35]
	v_lshl_add_u64 v[116:117], v[2:3], 0, s[40:41]
	v_lshl_add_u64 v[118:119], v[4:5], 0, s[40:41]
	v_lshl_add_u64 v[114:115], v[6:7], 0, s[40:41]
	v_mfma_f32_16x16x32_bf16 v[60:63], v[44:47], v[100:103], v[60:63]
	v_lshl_add_u64 v[112:113], v[8:9], 0, s[40:41]
	s_mov_b64 s[40:41], 0x240
	v_mfma_f32_16x16x32_bf16 v[64:67], v[84:87], v[100:103], v[64:67]
	v_mfma_f32_16x16x32_bf16 v[68:71], v[88:91], v[100:103], v[68:71]
	v_mfma_f32_16x16x32_bf16 v[36:39], v[92:95], v[100:103], v[36:39]
	v_mfma_f32_16x16x32_bf16 v[72:75], v[44:47], v[104:107], v[72:75]
	v_mfma_f32_16x16x32_bf16 v[76:79], v[84:87], v[104:107], v[76:79]
	v_mfma_f32_16x16x32_bf16 v[80:83], v[88:91], v[104:107], v[80:83]
	v_mfma_f32_16x16x32_bf16 v[40:43], v[92:95], v[104:107], v[40:43]
	v_mfma_f32_16x16x32_bf16 v[16:19], v[44:47], v[108:111], v[16:19]
	v_mfma_f32_16x16x32_bf16 v[20:23], v[84:87], v[108:111], v[20:23]
	v_mfma_f32_16x16x32_bf16 v[24:27], v[88:91], v[108:111], v[24:27]
	v_mfma_f32_16x16x32_bf16 v[28:31], v[92:95], v[108:111], v[28:31]
	s_setprio 0
	ds_read_b128 v[44:47], v0 offset:24576
	ds_read_b128 v[84:87], v0 offset:25600
	ds_read_b128 v[88:91], v0 offset:26624
	ds_read_b128 v[92:95], v0 offset:27648
	ds_read_b128 v[96:99], v10 offset:16384
	ds_read_b128 v[100:103], v10 offset:17408
	ds_read_b128 v[104:107], v10 offset:18432
	ds_read_b128 v[108:111], v10 offset:19456
	s_waitcnt vmcnt(4) lgkmcnt(0)
	s_barrier
	global_load_lds_dwordx4 v[124:125], off
	s_mov_b32 m0, s25
	s_waitcnt lgkmcnt(0)
	s_setprio 1
	v_mfma_f32_16x16x32_bf16 v[48:51], v[44:47], v[96:99], v[48:51]
	global_load_lds_dwordx4 v[126:127], off
	s_mov_b32 m0, s26
	v_mfma_f32_16x16x32_bf16 v[52:55], v[84:87], v[96:99], v[52:55]
	global_load_lds_dwordx4 v[122:123], off
	s_mov_b32 m0, s27
	v_mfma_f32_16x16x32_bf16 v[56:59], v[88:91], v[96:99], v[56:59]
	global_load_lds_dwordx4 v[120:121], off
	s_mov_b32 m0, s23
	v_mfma_f32_16x16x32_bf16 v[32:35], v[92:95], v[96:99], v[32:35]
	v_lshl_add_u64 v[124:125], v[2:3], 0, s[40:41]
	v_lshl_add_u64 v[126:127], v[4:5], 0, s[40:41]
	v_lshl_add_u64 v[122:123], v[6:7], 0, s[40:41]
	v_mfma_f32_16x16x32_bf16 v[60:63], v[44:47], v[100:103], v[60:63]
	v_lshl_add_u64 v[120:121], v[8:9], 0, s[40:41]
	s_mov_b64 s[40:41], 0x280
	v_mfma_f32_16x16x32_bf16 v[64:67], v[84:87], v[100:103], v[64:67]
	v_mfma_f32_16x16x32_bf16 v[68:71], v[88:91], v[100:103], v[68:71]
	v_mfma_f32_16x16x32_bf16 v[36:39], v[92:95], v[100:103], v[36:39]
	v_mfma_f32_16x16x32_bf16 v[72:75], v[44:47], v[104:107], v[72:75]
	v_mfma_f32_16x16x32_bf16 v[76:79], v[84:87], v[104:107], v[76:79]
	v_mfma_f32_16x16x32_bf16 v[80:83], v[88:91], v[104:107], v[80:83]
	v_mfma_f32_16x16x32_bf16 v[40:43], v[92:95], v[104:107], v[40:43]
	v_mfma_f32_16x16x32_bf16 v[16:19], v[44:47], v[108:111], v[16:19]
	v_mfma_f32_16x16x32_bf16 v[20:23], v[84:87], v[108:111], v[20:23]
	v_mfma_f32_16x16x32_bf16 v[24:27], v[88:91], v[108:111], v[24:27]
	v_mfma_f32_16x16x32_bf16 v[28:31], v[92:95], v[108:111], v[28:31]
	s_setprio 0
	ds_read_b128 v[44:47], v0 offset:40960
	ds_read_b128 v[84:87], v0 offset:41984
	ds_read_b128 v[88:91], v0 offset:43008
	ds_read_b128 v[92:95], v0 offset:44032
	ds_read_b128 v[96:99], v10 offset:32768
	ds_read_b128 v[100:103], v10 offset:33792
	ds_read_b128 v[104:107], v10 offset:34816
	ds_read_b128 v[108:111], v10 offset:35840
	s_waitcnt vmcnt(4) lgkmcnt(0)
	s_barrier
	global_load_lds_dwordx4 v[116:117], off
	s_mov_b32 m0, s22
	s_waitcnt lgkmcnt(0)
	s_setprio 1
	v_mfma_f32_16x16x32_bf16 v[48:51], v[44:47], v[96:99], v[48:51]
	global_load_lds_dwordx4 v[118:119], off
	s_mov_b32 m0, s21
	v_mfma_f32_16x16x32_bf16 v[52:55], v[84:87], v[96:99], v[52:55]
	global_load_lds_dwordx4 v[114:115], off
	s_mov_b32 m0, s1
	v_mfma_f32_16x16x32_bf16 v[56:59], v[88:91], v[96:99], v[56:59]
	global_load_lds_dwordx4 v[112:113], off
	s_mov_b32 m0, s36
	v_mfma_f32_16x16x32_bf16 v[32:35], v[92:95], v[96:99], v[32:35]
	v_lshl_add_u64 v[116:117], v[2:3], 0, s[40:41]
	v_lshl_add_u64 v[118:119], v[4:5], 0, s[40:41]
	v_lshl_add_u64 v[114:115], v[6:7], 0, s[40:41]
	v_mfma_f32_16x16x32_bf16 v[60:63], v[44:47], v[100:103], v[60:63]
	v_lshl_add_u64 v[112:113], v[8:9], 0, s[40:41]
	s_mov_b64 s[40:41], 0x2c0
	v_mfma_f32_16x16x32_bf16 v[64:67], v[84:87], v[100:103], v[64:67]
	v_mfma_f32_16x16x32_bf16 v[68:71], v[88:91], v[100:103], v[68:71]
	v_mfma_f32_16x16x32_bf16 v[36:39], v[92:95], v[100:103], v[36:39]
	v_mfma_f32_16x16x32_bf16 v[72:75], v[44:47], v[104:107], v[72:75]
	v_mfma_f32_16x16x32_bf16 v[76:79], v[84:87], v[104:107], v[76:79]
	v_mfma_f32_16x16x32_bf16 v[80:83], v[88:91], v[104:107], v[80:83]
	v_mfma_f32_16x16x32_bf16 v[40:43], v[92:95], v[104:107], v[40:43]
	v_mfma_f32_16x16x32_bf16 v[16:19], v[44:47], v[108:111], v[16:19]
	v_mfma_f32_16x16x32_bf16 v[20:23], v[84:87], v[108:111], v[20:23]
	v_mfma_f32_16x16x32_bf16 v[24:27], v[88:91], v[108:111], v[24:27]
	v_mfma_f32_16x16x32_bf16 v[28:31], v[92:95], v[108:111], v[28:31]
	s_setprio 0
	ds_read_b128 v[44:47], v0 offset:8192
	ds_read_b128 v[84:87], v0 offset:9216
	ds_read_b128 v[88:91], v0 offset:10240
	ds_read_b128 v[92:95], v0 offset:11264
	ds_read_b128 v[96:99], v10
	ds_read_b128 v[100:103], v10 offset:1024
	ds_read_b128 v[104:107], v10 offset:2048
	ds_read_b128 v[108:111], v10 offset:3072
	s_waitcnt vmcnt(4) lgkmcnt(0)
	s_barrier
	global_load_lds_dwordx4 v[124:125], off
	s_mov_b32 m0, s37
	s_waitcnt lgkmcnt(0)
	s_setprio 1
	v_mfma_f32_16x16x32_bf16 v[48:51], v[44:47], v[96:99], v[48:51]
	global_load_lds_dwordx4 v[126:127], off
	s_mov_b32 m0, s38
	v_mfma_f32_16x16x32_bf16 v[52:55], v[84:87], v[96:99], v[52:55]
	global_load_lds_dwordx4 v[122:123], off
	s_mov_b32 m0, s39
	v_mfma_f32_16x16x32_bf16 v[56:59], v[88:91], v[96:99], v[56:59]
	global_load_lds_dwordx4 v[120:121], off
	s_mov_b32 m0, s24
	v_mfma_f32_16x16x32_bf16 v[32:35], v[92:95], v[96:99], v[32:35]
	v_lshl_add_u64 v[124:125], v[2:3], 0, s[40:41]
	v_lshl_add_u64 v[126:127], v[4:5], 0, s[40:41]
	v_lshl_add_u64 v[122:123], v[6:7], 0, s[40:41]
	v_mfma_f32_16x16x32_bf16 v[60:63], v[44:47], v[100:103], v[60:63]
	v_lshl_add_u64 v[120:121], v[8:9], 0, s[40:41]
	s_mov_b64 s[40:41], 0x300
	v_mfma_f32_16x16x32_bf16 v[64:67], v[84:87], v[100:103], v[64:67]
	v_mfma_f32_16x16x32_bf16 v[68:71], v[88:91], v[100:103], v[68:71]
	v_mfma_f32_16x16x32_bf16 v[36:39], v[92:95], v[100:103], v[36:39]
	v_mfma_f32_16x16x32_bf16 v[72:75], v[44:47], v[104:107], v[72:75]
	v_mfma_f32_16x16x32_bf16 v[76:79], v[84:87], v[104:107], v[76:79]
	v_mfma_f32_16x16x32_bf16 v[80:83], v[88:91], v[104:107], v[80:83]
	v_mfma_f32_16x16x32_bf16 v[40:43], v[92:95], v[104:107], v[40:43]
	v_mfma_f32_16x16x32_bf16 v[16:19], v[44:47], v[108:111], v[16:19]
	v_mfma_f32_16x16x32_bf16 v[20:23], v[84:87], v[108:111], v[20:23]
	v_mfma_f32_16x16x32_bf16 v[24:27], v[88:91], v[108:111], v[24:27]
	v_mfma_f32_16x16x32_bf16 v[28:31], v[92:95], v[108:111], v[28:31]
	s_setprio 0
	ds_read_b128 v[44:47], v0 offset:24576
	ds_read_b128 v[84:87], v0 offset:25600
	ds_read_b128 v[88:91], v0 offset:26624
	ds_read_b128 v[92:95], v0 offset:27648
	ds_read_b128 v[96:99], v10 offset:16384
	ds_read_b128 v[100:103], v10 offset:17408
	ds_read_b128 v[104:107], v10 offset:18432
	ds_read_b128 v[108:111], v10 offset:19456
	s_waitcnt vmcnt(4) lgkmcnt(0)
	s_barrier
	global_load_lds_dwordx4 v[116:117], off
	s_mov_b32 m0, s25
	s_waitcnt lgkmcnt(0)
	s_setprio 1
	v_mfma_f32_16x16x32_bf16 v[48:51], v[44:47], v[96:99], v[48:51]
	global_load_lds_dwordx4 v[118:119], off
	s_mov_b32 m0, s26
	v_mfma_f32_16x16x32_bf16 v[52:55], v[84:87], v[96:99], v[52:55]
	global_load_lds_dwordx4 v[114:115], off
	s_mov_b32 m0, s27
	v_mfma_f32_16x16x32_bf16 v[56:59], v[88:91], v[96:99], v[56:59]
	global_load_lds_dwordx4 v[112:113], off
	s_mov_b32 m0, s23
	v_mfma_f32_16x16x32_bf16 v[32:35], v[92:95], v[96:99], v[32:35]
	v_lshl_add_u64 v[116:117], v[2:3], 0, s[40:41]
	v_lshl_add_u64 v[118:119], v[4:5], 0, s[40:41]
	v_lshl_add_u64 v[114:115], v[6:7], 0, s[40:41]
	v_mfma_f32_16x16x32_bf16 v[60:63], v[44:47], v[100:103], v[60:63]
	v_lshl_add_u64 v[112:113], v[8:9], 0, s[40:41]
	s_mov_b64 s[40:41], 0x340
	v_mfma_f32_16x16x32_bf16 v[64:67], v[84:87], v[100:103], v[64:67]
	v_mfma_f32_16x16x32_bf16 v[68:71], v[88:91], v[100:103], v[68:71]
	v_mfma_f32_16x16x32_bf16 v[36:39], v[92:95], v[100:103], v[36:39]
	v_mfma_f32_16x16x32_bf16 v[72:75], v[44:47], v[104:107], v[72:75]
	v_mfma_f32_16x16x32_bf16 v[76:79], v[84:87], v[104:107], v[76:79]
	v_mfma_f32_16x16x32_bf16 v[80:83], v[88:91], v[104:107], v[80:83]
	v_mfma_f32_16x16x32_bf16 v[40:43], v[92:95], v[104:107], v[40:43]
	v_mfma_f32_16x16x32_bf16 v[16:19], v[44:47], v[108:111], v[16:19]
	v_mfma_f32_16x16x32_bf16 v[20:23], v[84:87], v[108:111], v[20:23]
	v_mfma_f32_16x16x32_bf16 v[24:27], v[88:91], v[108:111], v[24:27]
	v_mfma_f32_16x16x32_bf16 v[28:31], v[92:95], v[108:111], v[28:31]
	s_setprio 0
	ds_read_b128 v[44:47], v0 offset:40960
	ds_read_b128 v[84:87], v0 offset:41984
	ds_read_b128 v[88:91], v0 offset:43008
	ds_read_b128 v[92:95], v0 offset:44032
	ds_read_b128 v[96:99], v10 offset:32768
	ds_read_b128 v[100:103], v10 offset:33792
	ds_read_b128 v[104:107], v10 offset:34816
	ds_read_b128 v[108:111], v10 offset:35840
	s_waitcnt vmcnt(4) lgkmcnt(0)
	s_barrier
	global_load_lds_dwordx4 v[124:125], off
	s_mov_b32 m0, s22
	s_waitcnt lgkmcnt(0)
	s_setprio 1
	v_mfma_f32_16x16x32_bf16 v[48:51], v[44:47], v[96:99], v[48:51]
	global_load_lds_dwordx4 v[126:127], off
	s_mov_b32 m0, s21
	v_mfma_f32_16x16x32_bf16 v[52:55], v[84:87], v[96:99], v[52:55]
	global_load_lds_dwordx4 v[122:123], off
	s_mov_b32 m0, s1
	v_mfma_f32_16x16x32_bf16 v[56:59], v[88:91], v[96:99], v[56:59]
	global_load_lds_dwordx4 v[120:121], off
	s_mov_b32 m0, s36
	v_mfma_f32_16x16x32_bf16 v[32:35], v[92:95], v[96:99], v[32:35]
	v_lshl_add_u64 v[124:125], v[2:3], 0, s[40:41]
	v_lshl_add_u64 v[126:127], v[4:5], 0, s[40:41]
	v_lshl_add_u64 v[122:123], v[6:7], 0, s[40:41]
	v_mfma_f32_16x16x32_bf16 v[60:63], v[44:47], v[100:103], v[60:63]
	v_lshl_add_u64 v[120:121], v[8:9], 0, s[40:41]
	v_mfma_f32_16x16x32_bf16 v[64:67], v[84:87], v[100:103], v[64:67]
	v_mfma_f32_16x16x32_bf16 v[68:71], v[88:91], v[100:103], v[68:71]
	v_mfma_f32_16x16x32_bf16 v[36:39], v[92:95], v[100:103], v[36:39]
	v_mfma_f32_16x16x32_bf16 v[72:75], v[44:47], v[104:107], v[72:75]
	v_mfma_f32_16x16x32_bf16 v[76:79], v[84:87], v[104:107], v[76:79]
	v_mfma_f32_16x16x32_bf16 v[80:83], v[88:91], v[104:107], v[80:83]
	v_mfma_f32_16x16x32_bf16 v[40:43], v[92:95], v[104:107], v[40:43]
	v_mfma_f32_16x16x32_bf16 v[16:19], v[44:47], v[108:111], v[16:19]
	v_mfma_f32_16x16x32_bf16 v[20:23], v[84:87], v[108:111], v[20:23]
	v_mfma_f32_16x16x32_bf16 v[24:27], v[88:91], v[108:111], v[24:27]
	v_mfma_f32_16x16x32_bf16 v[28:31], v[92:95], v[108:111], v[28:31]
	s_setprio 0
	ds_read_b128 v[44:47], v0 offset:8192
	ds_read_b128 v[84:87], v0 offset:9216
	ds_read_b128 v[88:91], v0 offset:10240
	ds_read_b128 v[92:95], v0 offset:11264
	ds_read_b128 v[96:99], v10
	ds_read_b128 v[100:103], v10 offset:1024
	ds_read_b128 v[104:107], v10 offset:2048
	ds_read_b128 v[108:111], v10 offset:3072
	s_waitcnt vmcnt(4) lgkmcnt(0)
	s_barrier
	global_load_lds_dwordx4 v[116:117], off
	s_mov_b32 m0, s37
	s_waitcnt lgkmcnt(0)
	s_setprio 1
	v_mfma_f32_16x16x32_bf16 v[48:51], v[44:47], v[96:99], v[48:51]
	global_load_lds_dwordx4 v[118:119], off
	s_mov_b32 m0, s38
	v_mfma_f32_16x16x32_bf16 v[52:55], v[84:87], v[96:99], v[52:55]
	global_load_lds_dwordx4 v[114:115], off
	s_mov_b32 m0, s39
	v_mfma_f32_16x16x32_bf16 v[56:59], v[88:91], v[96:99], v[56:59]
	global_load_lds_dwordx4 v[112:113], off
	s_mov_b32 m0, s24
	v_mfma_f32_16x16x32_bf16 v[32:35], v[92:95], v[96:99], v[32:35]
	s_mov_b64 s[36:37], 0x380
	v_lshl_add_u64 v[116:117], v[2:3], 0, s[36:37]
	v_lshl_add_u64 v[118:119], v[4:5], 0, s[36:37]
	v_mfma_f32_16x16x32_bf16 v[60:63], v[44:47], v[100:103], v[60:63]
	v_lshl_add_u64 v[114:115], v[6:7], 0, s[36:37]
	v_lshl_add_u64 v[112:113], v[8:9], 0, s[36:37]
	v_mfma_f32_16x16x32_bf16 v[64:67], v[84:87], v[100:103], v[64:67]
	v_mfma_f32_16x16x32_bf16 v[68:71], v[88:91], v[100:103], v[68:71]
	v_mfma_f32_16x16x32_bf16 v[36:39], v[92:95], v[100:103], v[36:39]
	v_mfma_f32_16x16x32_bf16 v[72:75], v[44:47], v[104:107], v[72:75]
	v_mfma_f32_16x16x32_bf16 v[76:79], v[84:87], v[104:107], v[76:79]
	v_mfma_f32_16x16x32_bf16 v[80:83], v[88:91], v[104:107], v[80:83]
	v_mfma_f32_16x16x32_bf16 v[40:43], v[92:95], v[104:107], v[40:43]
	v_mfma_f32_16x16x32_bf16 v[16:19], v[44:47], v[108:111], v[16:19]
	v_mfma_f32_16x16x32_bf16 v[20:23], v[84:87], v[108:111], v[20:23]
	v_mfma_f32_16x16x32_bf16 v[24:27], v[88:91], v[108:111], v[24:27]
	v_mfma_f32_16x16x32_bf16 v[28:31], v[92:95], v[108:111], v[28:31]
	s_setprio 0
	ds_read_b128 v[44:47], v0 offset:24576
	ds_read_b128 v[84:87], v0 offset:25600
	ds_read_b128 v[88:91], v0 offset:26624
	ds_read_b128 v[92:95], v0 offset:27648
	ds_read_b128 v[96:99], v10 offset:16384
	ds_read_b128 v[100:103], v10 offset:17408
	ds_read_b128 v[104:107], v10 offset:18432
	ds_read_b128 v[108:111], v10 offset:19456
	s_waitcnt vmcnt(4) lgkmcnt(0)
	s_barrier
	global_load_lds_dwordx4 v[124:125], off
	s_mov_b32 m0, s25
	s_waitcnt lgkmcnt(0)
	s_setprio 1
	v_mfma_f32_16x16x32_bf16 v[48:51], v[44:47], v[96:99], v[48:51]
	global_load_lds_dwordx4 v[126:127], off
	s_mov_b32 m0, s26
	v_mfma_f32_16x16x32_bf16 v[52:55], v[84:87], v[96:99], v[52:55]
	global_load_lds_dwordx4 v[122:123], off
	s_mov_b32 m0, s27
	v_mfma_f32_16x16x32_bf16 v[56:59], v[88:91], v[96:99], v[56:59]
	global_load_lds_dwordx4 v[120:121], off
	s_mov_b32 m0, s23
	v_mfma_f32_16x16x32_bf16 v[32:35], v[92:95], v[96:99], v[32:35]
	s_mov_b64 s[26:27], 0x3c0
	s_mov_b64 s[24:25], 0x3000
	v_mfma_f32_16x16x32_bf16 v[60:63], v[44:47], v[100:103], v[60:63]
	v_mfma_f32_16x16x32_bf16 v[64:67], v[84:87], v[100:103], v[64:67]
	v_mfma_f32_16x16x32_bf16 v[68:71], v[88:91], v[100:103], v[68:71]
	v_mfma_f32_16x16x32_bf16 v[36:39], v[92:95], v[100:103], v[36:39]
	v_mfma_f32_16x16x32_bf16 v[72:75], v[44:47], v[104:107], v[72:75]
	v_mfma_f32_16x16x32_bf16 v[76:79], v[84:87], v[104:107], v[76:79]
	v_mfma_f32_16x16x32_bf16 v[80:83], v[88:91], v[104:107], v[80:83]
	v_mfma_f32_16x16x32_bf16 v[40:43], v[92:95], v[104:107], v[40:43]
	v_mfma_f32_16x16x32_bf16 v[16:19], v[44:47], v[108:111], v[16:19]
	v_mfma_f32_16x16x32_bf16 v[20:23], v[84:87], v[108:111], v[20:23]
	v_mfma_f32_16x16x32_bf16 v[24:27], v[88:91], v[108:111], v[24:27]
	v_mfma_f32_16x16x32_bf16 v[28:31], v[92:95], v[108:111], v[28:31]
	s_setprio 0
	ds_read_b128 v[44:47], v0 offset:40960
	ds_read_b128 v[84:87], v0 offset:41984
	ds_read_b128 v[88:91], v0 offset:43008
	ds_read_b128 v[92:95], v0 offset:44032
	ds_read_b128 v[96:99], v10 offset:32768
	ds_read_b128 v[100:103], v10 offset:33792
	ds_read_b128 v[104:107], v10 offset:34816
	ds_read_b128 v[108:111], v10 offset:35840
	s_waitcnt vmcnt(4) lgkmcnt(0)
	s_barrier
	global_load_lds_dwordx4 v[116:117], off
	s_mov_b32 m0, s22
	s_waitcnt lgkmcnt(0)
	s_setprio 1
	v_mfma_f32_16x16x32_bf16 v[48:51], v[44:47], v[96:99], v[48:51]
	global_load_lds_dwordx4 v[118:119], off
	s_mov_b32 m0, s21
	v_mfma_f32_16x16x32_bf16 v[52:55], v[84:87], v[96:99], v[52:55]
	global_load_lds_dwordx4 v[114:115], off
	s_mov_b32 m0, s1
	v_readfirstlane_b32 s1, v11
	global_load_lds_dwordx4 v[112:113], off
	v_mfma_f32_16x16x32_bf16 v[56:59], v[88:91], v[96:99], v[56:59]
	s_mov_b32 m0, s1
	v_readfirstlane_b32 s1, v13
	s_lshl_b64 s[22:23], s[2:3], 11
	v_mfma_f32_16x16x32_bf16 v[32:35], v[92:95], v[96:99], v[32:35]
	v_mfma_f32_16x16x32_bf16 v[60:63], v[44:47], v[100:103], v[60:63]
	v_mfma_f32_16x16x32_bf16 v[64:67], v[84:87], v[100:103], v[64:67]
	v_mfma_f32_16x16x32_bf16 v[68:71], v[88:91], v[100:103], v[68:71]
	v_mfma_f32_16x16x32_bf16 v[36:39], v[92:95], v[100:103], v[36:39]
	v_mfma_f32_16x16x32_bf16 v[72:75], v[44:47], v[104:107], v[72:75]
	v_mfma_f32_16x16x32_bf16 v[76:79], v[84:87], v[104:107], v[76:79]
	v_mfma_f32_16x16x32_bf16 v[80:83], v[88:91], v[104:107], v[80:83]
	v_mfma_f32_16x16x32_bf16 v[40:43], v[92:95], v[104:107], v[40:43]
	v_lshl_add_u64 v[104:105], v[8:9], 0, s[26:27]
	v_lshl_add_u64 v[106:107], v[6:7], 0, s[26:27]
	v_mfma_f32_16x16x32_bf16 v[16:19], v[44:47], v[108:111], v[16:19]
	v_mfma_f32_16x16x32_bf16 v[20:23], v[84:87], v[108:111], v[20:23]
	v_mfma_f32_16x16x32_bf16 v[24:27], v[88:91], v[108:111], v[24:27]
	v_mfma_f32_16x16x32_bf16 v[28:31], v[92:95], v[108:111], v[28:31]
	v_lshl_add_u64 v[108:109], v[2:3], 0, s[26:27]
	v_lshl_add_u64 v[110:111], v[4:5], 0, s[26:27]
	s_setprio 0
	ds_read_b128 v[2:5], v0 offset:8192
	ds_read_b128 v[6:9], v0 offset:9216
	ds_read_b128 v[44:47], v0 offset:10240
	ds_read_b128 v[84:87], v0 offset:11264
	ds_read_b128 v[88:91], v10
	ds_read_b128 v[92:95], v10 offset:1024
	ds_read_b128 v[96:99], v10 offset:2048
	ds_read_b128 v[100:103], v10 offset:3072
	s_waitcnt vmcnt(4) lgkmcnt(0)
	s_barrier
	global_load_lds_dwordx4 v[108:109], off
	s_mov_b32 m0, s1
	v_readfirstlane_b32 s1, v14
	global_load_lds_dwordx4 v[110:111], off
	s_mov_b32 m0, s1
	v_readfirstlane_b32 s1, v12
	global_load_lds_dwordx4 v[106:107], off
	s_mov_b32 m0, s1
	s_waitcnt lgkmcnt(0)
	s_setprio 1
	v_mfma_f32_16x16x32_bf16 v[48:51], v[2:5], v[88:91], v[48:51]
	global_load_lds_dwordx4 v[104:105], off
	s_add_u32 s1, s17, s22
	v_mfma_f32_16x16x32_bf16 v[52:55], v[6:9], v[88:91], v[52:55]
	s_addc_u32 s2, s16, s23
	s_lshl_b32 s0, s0, 1
	s_add_u32 s0, s1, s0
	v_mfma_f32_16x16x32_bf16 v[56:59], v[44:47], v[88:91], v[56:59]
	s_addc_u32 s1, s2, 0
	s_mov_b32 s2, 0xfffffc0
	v_mfma_f32_16x16x32_bf16 v[32:35], v[84:87], v[88:91], v[32:35]
	v_mfma_f32_16x16x32_bf16 v[60:63], v[2:5], v[92:95], v[60:63]
	v_mfma_f32_16x16x32_bf16 v[64:67], v[6:9], v[92:95], v[64:67]
	v_mfma_f32_16x16x32_bf16 v[68:71], v[44:47], v[92:95], v[68:71]
	v_mfma_f32_16x16x32_bf16 v[36:39], v[84:87], v[92:95], v[36:39]
	v_mfma_f32_16x16x32_bf16 v[72:75], v[2:5], v[96:99], v[72:75]
	v_mfma_f32_16x16x32_bf16 v[76:79], v[6:9], v[96:99], v[76:79]
	v_mfma_f32_16x16x32_bf16 v[80:83], v[44:47], v[96:99], v[80:83]
	v_mfma_f32_16x16x32_bf16 v[40:43], v[84:87], v[96:99], v[40:43]
	v_mfma_f32_16x16x32_bf16 v[2:5], v[2:5], v[100:103], v[16:19]
	v_mfma_f32_16x16x32_bf16 v[6:9], v[6:9], v[100:103], v[20:23]
	v_mfma_f32_16x16x32_bf16 v[16:19], v[44:47], v[100:103], v[24:27]
	v_mfma_f32_16x16x32_bf16 v[20:23], v[84:87], v[100:103], v[28:31]
	s_setprio 0
	ds_read_b128 v[12:15], v0 offset:24576
	s_nop 0
	ds_read_b128 v[24:27], v0 offset:25600
	ds_read_b128 v[28:31], v0 offset:26624
	ds_read_b128 v[44:47], v0 offset:27648
	ds_read_b128 v[84:87], v10 offset:16384
	ds_read_b128 v[88:91], v10 offset:17408
	ds_read_b128 v[92:95], v10 offset:18432
	ds_read_b128 v[96:99], v10 offset:19456
	s_waitcnt vmcnt(4) lgkmcnt(0)
	s_barrier
	s_waitcnt lgkmcnt(0)
	s_setprio 1
	v_mfma_f32_16x16x32_bf16 v[48:51], v[12:15], v[84:87], v[48:51]
	v_mfma_f32_16x16x32_bf16 v[52:55], v[24:27], v[84:87], v[52:55]
	v_mfma_f32_16x16x32_bf16 v[56:59], v[28:31], v[84:87], v[56:59]
	v_mfma_f32_16x16x32_bf16 v[32:35], v[44:47], v[84:87], v[32:35]
	v_mfma_f32_16x16x32_bf16 v[60:63], v[12:15], v[88:91], v[60:63]
	v_mfma_f32_16x16x32_bf16 v[64:67], v[24:27], v[88:91], v[64:67]
	v_mfma_f32_16x16x32_bf16 v[68:71], v[28:31], v[88:91], v[68:71]
	v_mfma_f32_16x16x32_bf16 v[36:39], v[44:47], v[88:91], v[36:39]
	v_mfma_f32_16x16x32_bf16 v[72:75], v[12:15], v[92:95], v[72:75]
	v_mfma_f32_16x16x32_bf16 v[76:79], v[24:27], v[92:95], v[76:79]
	v_mfma_f32_16x16x32_bf16 v[80:83], v[28:31], v[92:95], v[80:83]
	v_mfma_f32_16x16x32_bf16 v[40:43], v[44:47], v[92:95], v[40:43]
	v_mfma_f32_16x16x32_bf16 v[2:5], v[12:15], v[96:99], v[2:5]
	v_mfma_f32_16x16x32_bf16 v[6:9], v[24:27], v[96:99], v[6:9]
	v_mfma_f32_16x16x32_bf16 v[12:15], v[28:31], v[96:99], v[16:19]
	v_mfma_f32_16x16x32_bf16 v[16:19], v[44:47], v[96:99], v[20:23]
	s_nop 2
	s_setprio 0
	ds_read_b128 v[20:23], v0 offset:40960
	ds_read_b128 v[24:27], v0 offset:41984
	ds_read_b128 v[28:31], v0 offset:43008
	ds_read_b128 v[44:47], v0 offset:44032
	ds_read_b128 v[84:87], v10 offset:32768
	ds_read_b128 v[88:91], v10 offset:33792
	ds_read_b128 v[92:95], v10 offset:34816
	ds_read_b128 v[96:99], v10 offset:35840
	s_waitcnt vmcnt(0) lgkmcnt(0)
	s_barrier
	s_waitcnt lgkmcnt(0)
	s_setprio 1
	v_mfma_f32_16x16x32_bf16 v[48:51], v[20:23], v[84:87], v[48:51]
	v_mfma_f32_16x16x32_bf16 v[52:55], v[24:27], v[84:87], v[52:55]
	v_mfma_f32_16x16x32_bf16 v[56:59], v[28:31], v[84:87], v[56:59]
	v_mfma_f32_16x16x32_bf16 v[32:35], v[44:47], v[84:87], v[32:35]
	v_mfma_f32_16x16x32_bf16 v[60:63], v[20:23], v[88:91], v[60:63]
	v_mfma_f32_16x16x32_bf16 v[64:67], v[24:27], v[88:91], v[64:67]
	v_mfma_f32_16x16x32_bf16 v[68:71], v[28:31], v[88:91], v[68:71]
	v_mfma_f32_16x16x32_bf16 v[36:39], v[44:47], v[88:91], v[36:39]
	v_mfma_f32_16x16x32_bf16 v[72:75], v[20:23], v[92:95], v[72:75]
	v_mfma_f32_16x16x32_bf16 v[76:79], v[24:27], v[92:95], v[76:79]
	v_mfma_f32_16x16x32_bf16 v[80:83], v[28:31], v[92:95], v[80:83]
	v_mfma_f32_16x16x32_bf16 v[40:43], v[44:47], v[92:95], v[40:43]
	v_mfma_f32_16x16x32_bf16 v[2:5], v[20:23], v[96:99], v[2:5]
	v_mfma_f32_16x16x32_bf16 v[6:9], v[24:27], v[96:99], v[6:9]
	v_mfma_f32_16x16x32_bf16 v[12:15], v[28:31], v[96:99], v[12:15]
	v_mfma_f32_16x16x32_bf16 v[16:19], v[44:47], v[96:99], v[16:19]
	s_setprio 0
	ds_read_b128 v[20:23], v0 offset:8192
	ds_read_b128 v[24:27], v0 offset:9216
	ds_read_b128 v[28:31], v0 offset:10240
	ds_read_b128 v[44:47], v0 offset:11264
	ds_read_b128 v[84:87], v10
	ds_read_b128 v[88:91], v10 offset:1024
	ds_read_b128 v[92:95], v10 offset:2048
	ds_read_b128 v[96:99], v10 offset:3072
	s_waitcnt vmcnt(0) lgkmcnt(0)
	s_barrier
	s_setprio 1
	v_mfma_f32_16x16x32_bf16 v[48:51], v[20:23], v[84:87], v[48:51]
	v_mfma_f32_16x16x32_bf16 v[52:55], v[24:27], v[84:87], v[52:55]
	v_mfma_f32_16x16x32_bf16 v[60:63], v[20:23], v[88:91], v[60:63]
	v_mfma_f32_16x16x32_bf16 v[72:75], v[20:23], v[92:95], v[72:75]
	v_mfma_f32_16x16x32_bf16 v[2:5], v[20:23], v[96:99], v[2:5]
	v_mov_b32_e32 v22, v196
	s_setprio 0
	s_nop 3
	v_cvt_pk_bf16_f32 v20, v52, v53
	s_setprio 1
	v_mfma_f32_16x16x32_bf16 v[56:59], v[28:31], v[84:87], v[56:59]
	v_and_b32_e32 v23, 15, v22
	v_and_b32_e32 v0, 64, v22
	v_lshl_add_u32 v0, v0, 1, 0
	v_mfma_f32_16x16x32_bf16 v[32:35], v[44:47], v[84:87], v[32:35]
	v_cvt_pk_bf16_f32 v21, v54, v55
	v_cvt_pk_bf16_f32 v2, v2, v3
	v_cvt_pk_bf16_f32 v3, v4, v5
	v_mfma_f32_16x16x32_bf16 v[10:13], v[28:31], v[96:99], v[12:15]
	v_mfma_f32_16x16x32_bf16 v[14:17], v[44:47], v[96:99], v[16:19]
	s_nop 2
	v_lshrrev_b32_e32 v18, 1, v22
	v_mfma_f32_16x16x32_bf16 v[64:67], v[24:27], v[88:91], v[64:67]
	v_and_or_b32 v19, v18, s2, v23
	v_and_b32_e32 v18, 24, v18
	v_mul_lo_u32 v19, v19, s30
	v_mfma_f32_16x16x32_bf16 v[68:71], v[28:31], v[88:91], v[68:71]
	v_add3_u32 v0, v0, v18, v19
	v_cvt_pk_bf16_f32 v18, v48, v49
	v_cvt_pk_bf16_f32 v19, v50, v51
	v_mfma_f32_16x16x32_bf16 v[36:39], v[44:47], v[88:91], v[36:39]
	ds_write2_b64 v0, v[18:19], v[20:21] offset1:4
	v_cvt_pk_bf16_f32 v18, v56, v57
	v_cvt_pk_bf16_f32 v19, v58, v59
	v_mfma_f32_16x16x32_bf16 v[6:9], v[24:27], v[96:99], v[6:9]
	v_cvt_pk_bf16_f32 v20, v32, v33
	v_cvt_pk_bf16_f32 v21, v34, v35
	ds_write2_b64 v0, v[18:19], v[20:21] offset0:8 offset1:12
	v_mfma_f32_16x16x32_bf16 v[76:79], v[24:27], v[92:95], v[76:79]
	v_cvt_pk_bf16_f32 v18, v60, v61
	v_cvt_pk_bf16_f32 v19, v62, v63
	v_cvt_pk_bf16_f32 v20, v64, v65
	v_cvt_pk_bf16_f32 v21, v66, v67
	v_add_u32_e32 v24, 0x1000, v0
	ds_write2_b64 v24, v[18:19], v[20:21] offset0:32 offset1:36
	v_cvt_pk_bf16_f32 v18, v68, v69
	v_cvt_pk_bf16_f32 v19, v70, v71
	v_cvt_pk_bf16_f32 v20, v36, v37
	v_cvt_pk_bf16_f32 v21, v38, v39
	v_mfma_f32_16x16x32_bf16 v[80:83], v[28:31], v[92:95], v[80:83]
	ds_write2_b64 v24, v[18:19], v[20:21] offset0:40 offset1:44
	v_add_u32_e32 v24, 0x2000, v0
	v_cvt_pk_bf16_f32 v4, v6, v7
	v_mfma_f32_16x16x32_bf16 v[40:43], v[44:47], v[92:95], v[40:43]
	v_cvt_pk_bf16_f32 v5, v8, v9
	v_add_u32_e32 v0, 0x3000, v0
	ds_write2_b64 v0, v[2:3], v[4:5] offset0:96 offset1:100
	v_cvt_pk_bf16_f32 v2, v10, v11
	v_cvt_pk_bf16_f32 v3, v12, v13
	v_cvt_pk_bf16_f32 v4, v14, v15
	v_cvt_pk_bf16_f32 v5, v16, v17
	ds_write2_b64 v0, v[2:3], v[4:5] offset0:104 offset1:108
	v_lshlrev_b32_e32 v0, 4, v23
	v_ashrrev_i32_e32 v2, 4, v22
	v_cvt_pk_bf16_f32 v18, v72, v73
	v_cvt_pk_bf16_f32 v19, v74, v75
	v_cvt_pk_bf16_f32 v20, v76, v77
	v_cvt_pk_bf16_f32 v21, v78, v79
	v_lshl_add_u64 v[6:7], s[0:1], 0, v[0:1]
	v_add_u32_e32 v0, 0, v0
	v_ashrrev_i32_e32 v3, 31, v2
	ds_write2_b64 v24, v[18:19], v[20:21] offset0:64 offset1:68
	v_cvt_pk_bf16_f32 v18, v80, v81
	v_cvt_pk_bf16_f32 v19, v82, v83
	v_cvt_pk_bf16_f32 v20, v40, v41
	v_cvt_pk_bf16_f32 v21, v42, v43
	v_mad_u64_u32 v[4:5], s[0:1], v2, s30, v[0:1]
	v_lshlrev_b64 v[2:3], 11, v[2:3]
	ds_write2_b64 v24, v[18:19], v[20:21] offset0:72 offset1:76
	s_setprio 0
	s_waitcnt lgkmcnt(0)
	s_barrier
	v_lshl_add_u64 v[8:9], v[6:7], 0, v[2:3]
	v_mov_b32_e32 v214, 0x8000
	v_mov_b32_e32 v215, 0
	ds_read_b128 v[216:219], v4
	ds_read_b128 v[228:231], v4 offset:4352
	ds_read_b128 v[232:235], v4 offset:8704
	ds_read_b128 v[236:239], v4 offset:13056
	ds_read_b128 v[240:243], v4 offset:17408
	ds_read_b128 v[244:247], v4 offset:21760
	ds_read_b128 v[248:251], v4 offset:26112
	ds_read_b128 v[252:255], v4 offset:30464
	s_waitcnt lgkmcnt(7)
	global_store_dwordx4 v[8:9], v[216:219], off
	v_lshl_add_u64 v[8:9], v[8:9], 0, v[214:215]
	s_waitcnt lgkmcnt(6)
	global_store_dwordx4 v[8:9], v[228:231], off
	v_lshl_add_u64 v[8:9], v[8:9], 0, v[214:215]
	s_waitcnt lgkmcnt(5)
	global_store_dwordx4 v[8:9], v[232:235], off
	v_lshl_add_u64 v[8:9], v[8:9], 0, v[214:215]
	s_waitcnt lgkmcnt(4)
	global_store_dwordx4 v[8:9], v[236:239], off
	v_lshl_add_u64 v[8:9], v[8:9], 0, v[214:215]
	s_waitcnt lgkmcnt(3)
	global_store_dwordx4 v[8:9], v[240:243], off
	v_lshl_add_u64 v[8:9], v[8:9], 0, v[214:215]
	s_waitcnt lgkmcnt(2)
	global_store_dwordx4 v[8:9], v[244:247], off
	v_lshl_add_u64 v[8:9], v[8:9], 0, v[214:215]
	s_waitcnt lgkmcnt(1)
	global_store_dwordx4 v[8:9], v[248:251], off
	v_lshl_add_u64 v[8:9], v[8:9], 0, v[214:215]
	s_waitcnt lgkmcnt(0)
	global_store_dwordx4 v[8:9], v[252:255], off
	s_mov_b64 s[0:1], 0
	s_barrier
.LBB0_201:
	s_andn2_b64 vcc, exec, s[0:1]
	s_cbranch_vccnz .LBB0_198
	s_lshr_b32 s1, s18, 3
	s_and_b32 s0, s15, 7
	s_and_b32 s1, s1, 0xfffff8
	v_mov_b32_e32 v14, v196
	s_or_b32 s0, s1, s0
	s_lshl_b32 s0, s0, 8
	v_lshrrev_b32_e32 v0, 2, v14
	s_lshl_b32 s1, s18, 4
	v_and_b32_e32 v0, 12, v0
	s_and_b32 s2, s1, 0x380
	s_ashr_i32 s1, s0, 31
	v_lshrrev_b32_e64 v0, v0, s57
	s_lshl_b64 s[22:23], s[0:1], 10
	v_xor_b32_e32 v0, v0, v14
	s_add_u32 s22, s8, s22
	v_ashrrev_i32_e32 v2, 2, v14
	v_lshlrev_b32_e32 v0, 4, v0
	s_addc_u32 s23, s9, s23
	s_lshl_b32 s8, s2, 10
	v_and_b32_e32 v0, 48, v0
	v_ashrrev_i32_e32 v3, 31, v2
	v_lshl_add_u32 v19, v14, 4, 0
	s_add_u32 s8, s19, s8
	v_lshl_add_u64 v[6:7], s[22:23], 0, v[0:1]
	v_lshlrev_b64 v[8:9], 10, v[2:3]
	s_mov_b64 s[18:19], 0x10000
	v_readfirstlane_b32 s25, v19
	v_add_u32_e32 v21, 0x1000, v19
	v_lshl_add_u64 v[10:11], v[8:9], 0, s[18:19]
	v_lshl_add_u64 v[2:3], v[6:7], 0, v[8:9]
	s_mov_b32 m0, s25
	v_readfirstlane_b32 s24, v21
	v_add_u32_e32 v20, 0x2000, v19
	v_lshl_add_u64 v[4:5], v[6:7], 0, v[10:11]
	global_load_lds_dwordx4 v[2:3], off
	s_mov_b32 m0, s24
	v_readfirstlane_b32 s23, v20
	v_add_u32_e32 v18, 0x3000, v19
	s_addc_u32 s9, s20, 0
	v_lshrrev_b32_e32 v15, 4, v14
	v_lshl_add_u64 v[6:7], v[2:3], 0, s[76:77]
	s_mov_b64 s[18:19], 0x30000
	v_lshlrev_b32_e32 v24, 6, v14
	v_and_b32_e32 v14, 12, v14
	global_load_lds_dwordx4 v[4:5], off
	s_mov_b32 m0, s23
	v_readfirstlane_b32 s22, v18
	v_add_u32_e32 v28, 0x4000, v19
	v_lshl_add_u64 v[12:13], v[2:3], 0, s[18:19]
	v_lshrrev_b32_e64 v14, v14, s57
	global_load_lds_dwordx4 v[6:7], off
	s_mov_b32 m0, s22
	v_lshl_add_u64 v[6:7], s[8:9], 0, v[8:9]
	v_readfirstlane_b32 s40, v28
	v_add_u32_e32 v29, 0x5000, v19
	v_lshl_add_u64 v[10:11], s[8:9], 0, v[10:11]
	v_xor_b32_e32 v14, v14, v15
	global_load_lds_dwordx4 v[12:13], off
	v_lshl_add_u64 v[8:9], v[6:7], 0, v[0:1]
	s_mov_b32 m0, s40
	v_readfirstlane_b32 s41, v29
	v_add_u32_e32 v27, 0x6000, v19
	v_lshlrev_b32_e32 v25, 4, v14
	v_lshl_add_u64 v[6:7], v[10:11], 0, v[0:1]
	global_load_lds_dwordx4 v[8:9], off
	s_mov_b32 m0, s41
	v_readfirstlane_b32 s39, v27
	v_add_u32_e32 v26, 0x7000, v19
	v_lshl_add_u64 v[14:15], v[2:3], 0, 64
	v_and_b32_e32 v0, 48, v25
	global_load_lds_dwordx4 v[6:7], off
	s_mov_b32 m0, s39
	v_readfirstlane_b32 s38, v26
	v_add_u32_e32 v25, 0x8000, v19
	v_lshl_add_u64 v[16:17], v[4:5], 0, 64
	global_load_lds_dwordx4 v[14:15], off
	s_mov_b32 m0, s38
	v_readfirstlane_b32 s37, v25
	v_lshl_add_u64 v[22:23], v[2:3], 0, s[96:97]
	global_load_lds_dwordx4 v[16:17], off
	s_mov_b32 m0, s37
	s_mov_b64 s[18:19], 0x30040
	global_load_lds_dwordx4 v[22:23], off
	v_add_u32_e32 v22, 0x9000, v19
	v_add_u32_e32 v23, 0xa000, v19
	v_readfirstlane_b32 s26, v22
	v_and_b32_e32 v36, 0x13c0, v24
	v_lshl_add_u64 v[12:13], v[2:3], 0, s[18:19]
	s_mov_b32 m0, s26
	v_and_b32_e32 v46, 0xffffe3c0, v24
	v_readfirstlane_b32 s27, v23
	v_add_u32_e32 v24, 0xb000, v19
	v_lshl_add_u64 v[10:11], v[8:9], 0, 64
	global_load_lds_dwordx4 v[12:13], off
	s_mov_b32 m0, s27
	v_readfirstlane_b32 s36, v24
	v_lshl_add_u64 v[12:13], v[6:7], 0, 64
	global_load_lds_dwordx4 v[10:11], off
	s_mov_b32 m0, s36
	s_mov_b64 s[8:9], 0x30080
	global_load_lds_dwordx4 v[12:13], off
	v_add_u32_e32 v12, 0xc000, v19
	v_lshl_add_u64 v[16:17], v[2:3], 0, s[8:9]
	v_readfirstlane_b32 s8, v12
	v_lshl_add_u64 v[14:15], v[2:3], 0, s[78:79]
	s_waitcnt vmcnt(6) lgkmcnt(0)
	s_barrier
	s_mov_b32 m0, s8
	v_add_u32_e32 v13, 0xd000, v19
	global_load_lds_dwordx4 v[14:15], off
	v_readfirstlane_b32 s9, v13
	v_add_u32_e32 v14, 0xe000, v19
	v_lshl_add_u64 v[32:33], v[4:5], 0, s[78:79]
	s_mov_b32 m0, s9
	v_readfirstlane_b32 s19, v14
	v_add_u32_e32 v15, 0xf000, v19
	v_lshl_add_u64 v[34:35], v[2:3], 0, s[90:91]
	global_load_lds_dwordx4 v[32:33], off
	s_mov_b32 m0, s19
	v_readfirstlane_b32 s18, v15
	global_load_lds_dwordx4 v[34:35], off
	s_mov_b64 s[20:21], 0x200c0
	s_mov_b32 m0, s18
	v_lshl_add_u64 v[166:167], v[2:3], 0, s[20:21]
	global_load_lds_dwordx4 v[16:17], off
	s_mov_b64 s[20:21], 0x300c0
	v_add_u32_e32 v16, 0x10000, v19
	v_lshl_add_u64 v[168:169], v[2:3], 0, s[20:21]
	v_readfirstlane_b32 s20, v16
	v_add_u32_e32 v17, 0x11000, v19
	v_lshl_add_u64 v[10:11], v[8:9], 0, s[78:79]
	s_mov_b32 m0, s20
	v_readfirstlane_b32 s21, v17
	v_lshl_add_u64 v[30:31], v[6:7], 0, s[78:79]
	global_load_lds_dwordx4 v[10:11], off
	s_mov_b32 m0, s21
	v_add3_u32 v10, 0, v36, v0
	global_load_lds_dwordx4 v[30:31], off
	v_add3_u32 v0, 0, v46, v0
	v_lshl_add_u64 v[162:163], v[2:3], 0, s[84:85]
	ds_read_b128 v[30:33], v10 offset:16384
	ds_read_b128 v[34:37], v10 offset:17408
	ds_read_b128 v[38:41], v10 offset:18432
	ds_read_b128 v[42:45], v10 offset:19456
	ds_read_b128 v[46:49], v0
	ds_read_b128 v[50:53], v0 offset:1024
	ds_read_b128 v[54:57], v0 offset:2048
	ds_read_b128 v[58:61], v0 offset:3072
	ds_read_b128 v[110:113], v0 offset:4096
	ds_read_b128 v[114:117], v0 offset:5120
	ds_read_b128 v[118:121], v0 offset:6144
	ds_read_b128 v[122:125], v0 offset:7168
	s_waitcnt vmcnt(6) lgkmcnt(0)
	s_barrier
	s_mov_b32 m0, s25
	v_lshl_add_u64 v[164:165], v[4:5], 0, s[84:85]
	global_load_lds_dwordx4 v[162:163], off
	s_mov_b32 m0, s24
	v_lshl_add_u64 v[170:171], v[8:9], 0, s[84:85]
	global_load_lds_dwordx4 v[164:165], off
	s_mov_b32 m0, s23
	v_lshl_add_u64 v[172:173], v[6:7], 0, s[84:85]
	global_load_lds_dwordx4 v[166:167], off
	s_mov_b32 m0, s22
	s_waitcnt lgkmcnt(0)
	v_mfma_f32_16x16x32_bf16 v[62:65], v[30:33], v[46:49], 0
	global_load_lds_dwordx4 v[168:169], off
	s_mov_b32 m0, s40
	v_mfma_f32_16x16x32_bf16 v[66:69], v[34:37], v[46:49], 0
	global_load_lds_dwordx4 v[170:171], off
	s_mov_b32 m0, s41
	v_mfma_f32_16x16x32_bf16 v[70:73], v[38:41], v[46:49], 0
	global_load_lds_dwordx4 v[172:173], off
	s_mov_b32 s44, s59
	v_mfma_f32_16x16x32_bf16 v[46:49], v[42:45], v[46:49], 0
	s_mov_b64 s[58:59], 0x100
	v_lshl_add_u64 v[190:191], v[2:3], 0, s[58:59]
	s_mov_b32 m0, s39
	v_mfma_f32_16x16x32_bf16 v[74:77], v[30:33], v[50:53], 0
	v_lshl_add_u64 v[192:193], v[4:5], 0, s[58:59]
	s_mov_b64 s[42:43], 0x20100
	v_lshl_add_u64 v[194:195], v[2:3], 0, s[42:43]
	v_mfma_f32_16x16x32_bf16 v[78:81], v[34:37], v[50:53], 0
	s_mov_b64 s[42:43], 0x30100
	v_lshl_add_u64 v[214:215], v[2:3], 0, s[42:43]
	v_lshl_add_u64 v[216:217], v[8:9], 0, s[58:59]
	v_mfma_f32_16x16x32_bf16 v[82:85], v[38:41], v[50:53], 0
	v_lshl_add_u64 v[218:219], v[6:7], 0, s[58:59]
	v_add_u32_e32 v11, 0xc000, v10
	s_mov_b64 s[58:59], 0x140
	v_mfma_f32_16x16x32_bf16 v[50:53], v[42:45], v[50:53], 0
	s_mov_b64 s[42:43], 0x20140
	s_lshl_b64 s[0:1], s[0:1], 11
	s_add_u32 s0, s17, s0
	v_mfma_f32_16x16x32_bf16 v[86:89], v[30:33], v[54:57], 0
	s_addc_u32 s1, s16, s1
	s_lshl_b32 s2, s2, 1
	s_add_u32 s0, s0, s2
	v_mfma_f32_16x16x32_bf16 v[90:93], v[34:37], v[54:57], 0
	s_addc_u32 s1, s1, 0
	s_movk_i32 s57, 0x1320
	s_mov_b32 s56, 0x800000
	v_mfma_f32_16x16x32_bf16 v[94:97], v[38:41], v[54:57], 0
	v_readlane_b32 s88, v225, 56
	v_mfma_f32_16x16x32_bf16 v[54:57], v[42:45], v[54:57], 0
	v_mfma_f32_16x16x32_bf16 v[98:101], v[30:33], v[58:61], 0
	v_mfma_f32_16x16x32_bf16 v[102:105], v[34:37], v[58:61], 0
	v_mfma_f32_16x16x32_bf16 v[106:109], v[38:41], v[58:61], 0
	v_mfma_f32_16x16x32_bf16 v[58:61], v[42:45], v[58:61], 0
	v_mfma_f32_16x16x32_bf16 v[126:129], v[30:33], v[110:113], 0
	v_mfma_f32_16x16x32_bf16 v[130:133], v[34:37], v[110:113], 0
	v_mfma_f32_16x16x32_bf16 v[134:137], v[38:41], v[110:113], 0
	v_mfma_f32_16x16x32_bf16 v[110:113], v[42:45], v[110:113], 0
	v_mfma_f32_16x16x32_bf16 v[138:141], v[30:33], v[114:117], 0
	v_mfma_f32_16x16x32_bf16 v[142:145], v[34:37], v[114:117], 0
	v_mfma_f32_16x16x32_bf16 v[146:149], v[38:41], v[114:117], 0
	v_mfma_f32_16x16x32_bf16 v[114:117], v[42:45], v[114:117], 0
	v_mfma_f32_16x16x32_bf16 v[150:153], v[30:33], v[118:121], 0
	v_mfma_f32_16x16x32_bf16 v[154:157], v[34:37], v[118:121], 0
	v_mfma_f32_16x16x32_bf16 v[158:161], v[38:41], v[118:121], 0
	v_mfma_f32_16x16x32_bf16 v[118:121], v[42:45], v[118:121], 0
	v_mfma_f32_16x16x32_bf16 v[30:33], v[30:33], v[122:125], 0
	v_mfma_f32_16x16x32_bf16 v[34:37], v[34:37], v[122:125], 0
	v_mfma_f32_16x16x32_bf16 v[38:41], v[38:41], v[122:125], 0
	v_mfma_f32_16x16x32_bf16 v[42:45], v[42:45], v[122:125], 0
	ds_read_b128 v[122:125], v10 offset:40960
	ds_read_b128 v[162:165], v10 offset:41984
	ds_read_b128 v[166:169], v10 offset:43008
	ds_read_b128 v[170:173], v10 offset:44032
	ds_read_b128 v[174:177], v0 offset:24576
	ds_read_b128 v[178:181], v0 offset:25600
	ds_read_b128 v[182:185], v0 offset:26624
	ds_read_b128 v[186:189], v0 offset:27648
	s_waitcnt lgkmcnt(0)
	v_mfma_f32_16x16x32_bf16 v[62:65], v[122:125], v[174:177], v[62:65]
	v_mfma_f32_16x16x32_bf16 v[66:69], v[162:165], v[174:177], v[66:69]
	v_mfma_f32_16x16x32_bf16 v[70:73], v[166:169], v[174:177], v[70:73]
	v_mfma_f32_16x16x32_bf16 v[46:49], v[170:173], v[174:177], v[46:49]
	v_mfma_f32_16x16x32_bf16 v[74:77], v[122:125], v[178:181], v[74:77]
	v_mfma_f32_16x16x32_bf16 v[78:81], v[162:165], v[178:181], v[78:81]
	v_mfma_f32_16x16x32_bf16 v[82:85], v[166:169], v[178:181], v[82:85]
	v_mfma_f32_16x16x32_bf16 v[50:53], v[170:173], v[178:181], v[50:53]
	v_mfma_f32_16x16x32_bf16 v[86:89], v[122:125], v[182:185], v[86:89]
	v_mfma_f32_16x16x32_bf16 v[90:93], v[162:165], v[182:185], v[90:93]
	v_mfma_f32_16x16x32_bf16 v[94:97], v[166:169], v[182:185], v[94:97]
	v_mfma_f32_16x16x32_bf16 v[54:57], v[170:173], v[182:185], v[54:57]
	v_mfma_f32_16x16x32_bf16 v[98:101], v[122:125], v[186:189], v[98:101]
	v_mfma_f32_16x16x32_bf16 v[102:105], v[162:165], v[186:189], v[102:105]
	v_mfma_f32_16x16x32_bf16 v[106:109], v[166:169], v[186:189], v[106:109]
	v_mfma_f32_16x16x32_bf16 v[58:61], v[170:173], v[186:189], v[58:61]
	ds_read_b128 v[174:177], v0 offset:28672
	ds_read_b128 v[178:181], v0 offset:29696
	ds_read_b128 v[182:185], v0 offset:30720
	ds_read_b128 v[186:189], v0 offset:31744
	s_waitcnt vmcnt(6) lgkmcnt(0)
	s_barrier
	global_load_lds_dwordx4 v[190:191], off
	s_mov_b32 m0, s38
	s_waitcnt lgkmcnt(0)
	v_mfma_f32_16x16x32_bf16 v[126:129], v[122:125], v[174:177], v[126:129]
	global_load_lds_dwordx4 v[192:193], off
	s_mov_b32 m0, s37
	v_mfma_f32_16x16x32_bf16 v[130:133], v[162:165], v[174:177], v[130:133]
	global_load_lds_dwordx4 v[194:195], off
	s_mov_b32 m0, s26
	v_mfma_f32_16x16x32_bf16 v[134:137], v[166:169], v[174:177], v[134:137]
	global_load_lds_dwordx4 v[214:215], off
	s_mov_b32 m0, s27
	v_mfma_f32_16x16x32_bf16 v[110:113], v[170:173], v[174:177], v[110:113]
	global_load_lds_dwordx4 v[216:217], off
	s_mov_b32 m0, s36
	v_mfma_f32_16x16x32_bf16 v[138:141], v[122:125], v[178:181], v[138:141]
	global_load_lds_dwordx4 v[218:219], off
	v_lshl_add_u64 v[190:191], v[2:3], 0, s[58:59]
	v_mfma_f32_16x16x32_bf16 v[142:145], v[162:165], v[178:181], v[142:145]
	s_mov_b32 m0, s8
	v_lshl_add_u64 v[192:193], v[4:5], 0, s[58:59]
	v_lshl_add_u64 v[194:195], v[2:3], 0, s[42:43]
	v_mfma_f32_16x16x32_bf16 v[146:149], v[166:169], v[178:181], v[146:149]
	s_mov_b64 s[42:43], 0x30140
	v_lshl_add_u64 v[214:215], v[2:3], 0, s[42:43]
	v_lshl_add_u64 v[216:217], v[8:9], 0, s[58:59]
	v_mfma_f32_16x16x32_bf16 v[114:117], v[170:173], v[178:181], v[114:117]
	v_lshl_add_u64 v[218:219], v[6:7], 0, s[58:59]
	s_mov_b64 s[58:59], 0x180
	s_mov_b64 s[42:43], 0x20180
	v_mfma_f32_16x16x32_bf16 v[150:153], v[122:125], v[182:185], v[150:153]
	v_mfma_f32_16x16x32_bf16 v[154:157], v[162:165], v[182:185], v[154:157]
	v_mfma_f32_16x16x32_bf16 v[158:161], v[166:169], v[182:185], v[158:161]
	v_mfma_f32_16x16x32_bf16 v[118:121], v[170:173], v[182:185], v[118:121]
	v_mfma_f32_16x16x32_bf16 v[30:33], v[122:125], v[186:189], v[30:33]
	v_mfma_f32_16x16x32_bf16 v[34:37], v[162:165], v[186:189], v[34:37]
	v_mfma_f32_16x16x32_bf16 v[38:41], v[166:169], v[186:189], v[38:41]
	v_mfma_f32_16x16x32_bf16 v[42:45], v[170:173], v[186:189], v[42:45]
	ds_read_b128 v[122:125], v11 offset:16384
	ds_read_b128 v[162:165], v11 offset:17408
	ds_read_b128 v[166:169], v11 offset:18432
	ds_read_b128 v[170:173], v11 offset:19456
	ds_read_b128 v[174:177], v0 offset:49152
	ds_read_b128 v[178:181], v0 offset:50176
	ds_read_b128 v[182:185], v0 offset:51200
	ds_read_b128 v[186:189], v0 offset:52224
	s_waitcnt lgkmcnt(0)
	v_mfma_f32_16x16x32_bf16 v[62:65], v[122:125], v[174:177], v[62:65]
	v_mfma_f32_16x16x32_bf16 v[66:69], v[162:165], v[174:177], v[66:69]
	v_mfma_f32_16x16x32_bf16 v[70:73], v[166:169], v[174:177], v[70:73]
	v_mfma_f32_16x16x32_bf16 v[46:49], v[170:173], v[174:177], v[46:49]
	v_mfma_f32_16x16x32_bf16 v[74:77], v[122:125], v[178:181], v[74:77]
	v_mfma_f32_16x16x32_bf16 v[78:81], v[162:165], v[178:181], v[78:81]
	v_mfma_f32_16x16x32_bf16 v[82:85], v[166:169], v[178:181], v[82:85]
	v_mfma_f32_16x16x32_bf16 v[50:53], v[170:173], v[178:181], v[50:53]
	v_mfma_f32_16x16x32_bf16 v[86:89], v[122:125], v[182:185], v[86:89]
	v_mfma_f32_16x16x32_bf16 v[90:93], v[162:165], v[182:185], v[90:93]
	v_mfma_f32_16x16x32_bf16 v[94:97], v[166:169], v[182:185], v[94:97]
	v_mfma_f32_16x16x32_bf16 v[54:57], v[170:173], v[182:185], v[54:57]
	v_mfma_f32_16x16x32_bf16 v[98:101], v[122:125], v[186:189], v[98:101]
	v_mfma_f32_16x16x32_bf16 v[102:105], v[162:165], v[186:189], v[102:105]
	v_mfma_f32_16x16x32_bf16 v[106:109], v[166:169], v[186:189], v[106:109]
	v_mfma_f32_16x16x32_bf16 v[58:61], v[170:173], v[186:189], v[58:61]
	ds_read_b128 v[174:177], v0 offset:53248
	ds_read_b128 v[178:181], v0 offset:54272
	ds_read_b128 v[182:185], v0 offset:55296
	ds_read_b128 v[186:189], v0 offset:56320
	s_waitcnt vmcnt(6) lgkmcnt(0)
	s_barrier
	global_load_lds_dwordx4 v[190:191], off
	s_mov_b32 m0, s9
	s_waitcnt lgkmcnt(0)
	v_mfma_f32_16x16x32_bf16 v[126:129], v[122:125], v[174:177], v[126:129]
	global_load_lds_dwordx4 v[192:193], off
	s_mov_b32 m0, s19
	v_mfma_f32_16x16x32_bf16 v[130:133], v[162:165], v[174:177], v[130:133]
	global_load_lds_dwordx4 v[194:195], off
	s_mov_b32 m0, s18
	v_mfma_f32_16x16x32_bf16 v[134:137], v[166:169], v[174:177], v[134:137]
	global_load_lds_dwordx4 v[214:215], off
	s_mov_b32 m0, s20
	v_mfma_f32_16x16x32_bf16 v[110:113], v[170:173], v[174:177], v[110:113]
	global_load_lds_dwordx4 v[216:217], off
	s_mov_b32 m0, s21
	v_mfma_f32_16x16x32_bf16 v[138:141], v[122:125], v[178:181], v[138:141]
	global_load_lds_dwordx4 v[218:219], off
	v_lshl_add_u64 v[190:191], v[2:3], 0, s[58:59]
	v_mfma_f32_16x16x32_bf16 v[142:145], v[162:165], v[178:181], v[142:145]
	s_mov_b32 m0, s25
	v_lshl_add_u64 v[192:193], v[4:5], 0, s[58:59]
	v_lshl_add_u64 v[194:195], v[2:3], 0, s[42:43]
	v_mfma_f32_16x16x32_bf16 v[146:149], v[166:169], v[178:181], v[146:149]
	s_mov_b64 s[42:43], 0x30180
	v_lshl_add_u64 v[214:215], v[2:3], 0, s[42:43]
	v_lshl_add_u64 v[216:217], v[8:9], 0, s[58:59]
	v_mfma_f32_16x16x32_bf16 v[114:117], v[170:173], v[178:181], v[114:117]
	v_lshl_add_u64 v[218:219], v[6:7], 0, s[58:59]
	s_mov_b64 s[42:43], 0x1c0
	s_mov_b64 s[58:59], 0x340
	v_mfma_f32_16x16x32_bf16 v[150:153], v[122:125], v[182:185], v[150:153]
	v_mfma_f32_16x16x32_bf16 v[154:157], v[162:165], v[182:185], v[154:157]
	v_mfma_f32_16x16x32_bf16 v[158:161], v[166:169], v[182:185], v[158:161]
	v_mfma_f32_16x16x32_bf16 v[118:121], v[170:173], v[182:185], v[118:121]
	v_mfma_f32_16x16x32_bf16 v[30:33], v[122:125], v[186:189], v[30:33]
	v_mfma_f32_16x16x32_bf16 v[34:37], v[162:165], v[186:189], v[34:37]
	v_mfma_f32_16x16x32_bf16 v[38:41], v[166:169], v[186:189], v[38:41]
	v_mfma_f32_16x16x32_bf16 v[42:45], v[170:173], v[186:189], v[42:45]
	ds_read_b128 v[122:125], v10 offset:16384
	ds_read_b128 v[162:165], v10 offset:17408
	ds_read_b128 v[166:169], v10 offset:18432
	ds_read_b128 v[170:173], v10 offset:19456
	ds_read_b128 v[174:177], v0
	ds_read_b128 v[178:181], v0 offset:1024
	ds_read_b128 v[182:185], v0 offset:2048
	ds_read_b128 v[186:189], v0 offset:3072
	s_waitcnt lgkmcnt(0)
	v_mfma_f32_16x16x32_bf16 v[62:65], v[122:125], v[174:177], v[62:65]
	v_mfma_f32_16x16x32_bf16 v[66:69], v[162:165], v[174:177], v[66:69]
	v_mfma_f32_16x16x32_bf16 v[70:73], v[166:169], v[174:177], v[70:73]
	v_mfma_f32_16x16x32_bf16 v[46:49], v[170:173], v[174:177], v[46:49]
	v_mfma_f32_16x16x32_bf16 v[74:77], v[122:125], v[178:181], v[74:77]
	v_mfma_f32_16x16x32_bf16 v[78:81], v[162:165], v[178:181], v[78:81]
	v_mfma_f32_16x16x32_bf16 v[82:85], v[166:169], v[178:181], v[82:85]
	v_mfma_f32_16x16x32_bf16 v[50:53], v[170:173], v[178:181], v[50:53]
	v_mfma_f32_16x16x32_bf16 v[86:89], v[122:125], v[182:185], v[86:89]
	v_mfma_f32_16x16x32_bf16 v[90:93], v[162:165], v[182:185], v[90:93]
	v_mfma_f32_16x16x32_bf16 v[94:97], v[166:169], v[182:185], v[94:97]
	v_mfma_f32_16x16x32_bf16 v[54:57], v[170:173], v[182:185], v[54:57]
	v_mfma_f32_16x16x32_bf16 v[98:101], v[122:125], v[186:189], v[98:101]
	v_mfma_f32_16x16x32_bf16 v[102:105], v[162:165], v[186:189], v[102:105]
	v_mfma_f32_16x16x32_bf16 v[106:109], v[166:169], v[186:189], v[106:109]
	v_mfma_f32_16x16x32_bf16 v[58:61], v[170:173], v[186:189], v[58:61]
	ds_read_b128 v[174:177], v0 offset:4096
	ds_read_b128 v[178:181], v0 offset:5120
	ds_read_b128 v[182:185], v0 offset:6144
	ds_read_b128 v[186:189], v0 offset:7168
	s_waitcnt vmcnt(6) lgkmcnt(0)
	s_barrier
	global_load_lds_dwordx4 v[190:191], off
	s_mov_b32 m0, s24
	s_waitcnt lgkmcnt(0)
	v_mfma_f32_16x16x32_bf16 v[126:129], v[122:125], v[174:177], v[126:129]
	global_load_lds_dwordx4 v[192:193], off
	s_mov_b32 m0, s23
	v_mfma_f32_16x16x32_bf16 v[130:133], v[162:165], v[174:177], v[130:133]
	global_load_lds_dwordx4 v[194:195], off
	s_mov_b32 m0, s22
	v_mfma_f32_16x16x32_bf16 v[134:137], v[166:169], v[174:177], v[134:137]
	global_load_lds_dwordx4 v[214:215], off
	s_mov_b32 m0, s40
	v_mfma_f32_16x16x32_bf16 v[110:113], v[170:173], v[174:177], v[110:113]
	global_load_lds_dwordx4 v[216:217], off
	s_mov_b32 m0, s41
	v_mfma_f32_16x16x32_bf16 v[138:141], v[122:125], v[178:181], v[138:141]
	global_load_lds_dwordx4 v[218:219], off
	v_lshl_add_u64 v[190:191], v[2:3], 0, s[42:43]
	v_mfma_f32_16x16x32_bf16 v[142:145], v[162:165], v[178:181], v[142:145]
	s_mov_b32 m0, s39
	v_lshl_add_u64 v[192:193], v[4:5], 0, s[42:43]
	s_mov_b64 s[24:25], 0x201c0
	v_mfma_f32_16x16x32_bf16 v[146:149], v[166:169], v[178:181], v[146:149]
	v_lshl_add_u64 v[194:195], v[2:3], 0, s[24:25]
	s_mov_b64 s[22:23], 0x301c0
	v_lshl_add_u64 v[214:215], v[2:3], 0, s[22:23]
	v_mfma_f32_16x16x32_bf16 v[114:117], v[170:173], v[178:181], v[114:117]
	v_lshl_add_u64 v[216:217], v[8:9], 0, s[42:43]
	v_lshl_add_u64 v[218:219], v[6:7], 0, s[42:43]
	s_mov_b64 s[24:25], 0x200
	v_mfma_f32_16x16x32_bf16 v[150:153], v[122:125], v[182:185], v[150:153]
	s_mov_b64 s[22:23], 0x20200
	s_mov_b64 s[40:41], 0x20300
	v_readfirstlane_b32 s39, v15
	v_mfma_f32_16x16x32_bf16 v[154:157], v[162:165], v[182:185], v[154:157]
	s_mov_b64 s[42:43], 0x300
	v_mfma_f32_16x16x32_bf16 v[158:161], v[166:169], v[182:185], v[158:161]
	v_mfma_f32_16x16x32_bf16 v[118:121], v[170:173], v[182:185], v[118:121]
	v_mfma_f32_16x16x32_bf16 v[30:33], v[122:125], v[186:189], v[30:33]
	v_mfma_f32_16x16x32_bf16 v[34:37], v[162:165], v[186:189], v[34:37]
	v_mfma_f32_16x16x32_bf16 v[38:41], v[166:169], v[186:189], v[38:41]
	v_mfma_f32_16x16x32_bf16 v[42:45], v[170:173], v[186:189], v[42:45]
	ds_read_b128 v[122:125], v10 offset:40960
	ds_read_b128 v[162:165], v10 offset:41984
	ds_read_b128 v[166:169], v10 offset:43008
	ds_read_b128 v[170:173], v10 offset:44032
	ds_read_b128 v[174:177], v0 offset:24576
	ds_read_b128 v[178:181], v0 offset:25600
	ds_read_b128 v[182:185], v0 offset:26624
	ds_read_b128 v[186:189], v0 offset:27648
	s_waitcnt lgkmcnt(0)
	v_mfma_f32_16x16x32_bf16 v[62:65], v[122:125], v[174:177], v[62:65]
	v_mfma_f32_16x16x32_bf16 v[66:69], v[162:165], v[174:177], v[66:69]
	v_mfma_f32_16x16x32_bf16 v[70:73], v[166:169], v[174:177], v[70:73]
	v_mfma_f32_16x16x32_bf16 v[46:49], v[170:173], v[174:177], v[46:49]
	v_mfma_f32_16x16x32_bf16 v[74:77], v[122:125], v[178:181], v[74:77]
	v_mfma_f32_16x16x32_bf16 v[78:81], v[162:165], v[178:181], v[78:81]
	v_mfma_f32_16x16x32_bf16 v[82:85], v[166:169], v[178:181], v[82:85]
	v_mfma_f32_16x16x32_bf16 v[50:53], v[170:173], v[178:181], v[50:53]
	v_mfma_f32_16x16x32_bf16 v[86:89], v[122:125], v[182:185], v[86:89]
	v_mfma_f32_16x16x32_bf16 v[90:93], v[162:165], v[182:185], v[90:93]
	v_mfma_f32_16x16x32_bf16 v[94:97], v[166:169], v[182:185], v[94:97]
	v_mfma_f32_16x16x32_bf16 v[54:57], v[170:173], v[182:185], v[54:57]
	v_mfma_f32_16x16x32_bf16 v[98:101], v[122:125], v[186:189], v[98:101]
	v_mfma_f32_16x16x32_bf16 v[102:105], v[162:165], v[186:189], v[102:105]
	v_mfma_f32_16x16x32_bf16 v[106:109], v[166:169], v[186:189], v[106:109]
	v_mfma_f32_16x16x32_bf16 v[58:61], v[170:173], v[186:189], v[58:61]
	ds_read_b128 v[174:177], v0 offset:28672
	ds_read_b128 v[178:181], v0 offset:29696
	ds_read_b128 v[182:185], v0 offset:30720
	ds_read_b128 v[186:189], v0 offset:31744
	s_waitcnt vmcnt(6) lgkmcnt(0)
	s_barrier
	global_load_lds_dwordx4 v[190:191], off
	s_mov_b32 m0, s38
	s_waitcnt lgkmcnt(0)
	v_mfma_f32_16x16x32_bf16 v[126:129], v[122:125], v[174:177], v[126:129]
	global_load_lds_dwordx4 v[192:193], off
	s_mov_b32 m0, s37
	v_mfma_f32_16x16x32_bf16 v[130:133], v[162:165], v[174:177], v[130:133]
	global_load_lds_dwordx4 v[194:195], off
	s_mov_b32 m0, s26
	v_mfma_f32_16x16x32_bf16 v[134:137], v[166:169], v[174:177], v[134:137]
	global_load_lds_dwordx4 v[214:215], off
	s_mov_b32 m0, s27
	v_mfma_f32_16x16x32_bf16 v[110:113], v[170:173], v[174:177], v[110:113]
	global_load_lds_dwordx4 v[216:217], off
	s_mov_b32 m0, s36
	v_mfma_f32_16x16x32_bf16 v[138:141], v[122:125], v[178:181], v[138:141]
	global_load_lds_dwordx4 v[218:219], off
	v_lshl_add_u64 v[190:191], v[2:3], 0, s[24:25]
	v_mfma_f32_16x16x32_bf16 v[142:145], v[162:165], v[178:181], v[142:145]
	s_mov_b32 m0, s8
	v_lshl_add_u64 v[192:193], v[4:5], 0, s[24:25]
	v_lshl_add_u64 v[194:195], v[2:3], 0, s[22:23]
	v_mfma_f32_16x16x32_bf16 v[146:149], v[166:169], v[178:181], v[146:149]
	s_mov_b64 s[22:23], 0x30200
	v_lshl_add_u64 v[214:215], v[2:3], 0, s[22:23]
	v_lshl_add_u64 v[216:217], v[8:9], 0, s[24:25]
	v_mfma_f32_16x16x32_bf16 v[114:117], v[170:173], v[178:181], v[114:117]
	v_lshl_add_u64 v[218:219], v[6:7], 0, s[24:25]
	s_mov_b64 s[22:23], 0x240
	v_readfirstlane_b32 s24, v25
	v_mfma_f32_16x16x32_bf16 v[150:153], v[122:125], v[182:185], v[150:153]
	s_mov_b64 s[26:27], 0x202c0
	v_readfirstlane_b32 s25, v22
	s_mov_b64 s[36:37], 0x2c0
	v_mfma_f32_16x16x32_bf16 v[154:157], v[162:165], v[182:185], v[154:157]
	v_readfirstlane_b32 s38, v14
	v_mfma_f32_16x16x32_bf16 v[158:161], v[166:169], v[182:185], v[158:161]
	v_mfma_f32_16x16x32_bf16 v[118:121], v[170:173], v[182:185], v[118:121]
	v_mfma_f32_16x16x32_bf16 v[30:33], v[122:125], v[186:189], v[30:33]
	v_mfma_f32_16x16x32_bf16 v[34:37], v[162:165], v[186:189], v[34:37]
	v_mfma_f32_16x16x32_bf16 v[38:41], v[166:169], v[186:189], v[38:41]
	v_mfma_f32_16x16x32_bf16 v[42:45], v[170:173], v[186:189], v[42:45]
	ds_read_b128 v[122:125], v11 offset:16384
	ds_read_b128 v[162:165], v11 offset:17408
	ds_read_b128 v[166:169], v11 offset:18432
	ds_read_b128 v[170:173], v11 offset:19456
	ds_read_b128 v[174:177], v0 offset:49152
	ds_read_b128 v[178:181], v0 offset:50176
	ds_read_b128 v[182:185], v0 offset:51200
	ds_read_b128 v[186:189], v0 offset:52224
	s_waitcnt lgkmcnt(0)
	v_mfma_f32_16x16x32_bf16 v[62:65], v[122:125], v[174:177], v[62:65]
	v_mfma_f32_16x16x32_bf16 v[66:69], v[162:165], v[174:177], v[66:69]
	v_mfma_f32_16x16x32_bf16 v[70:73], v[166:169], v[174:177], v[70:73]
	v_mfma_f32_16x16x32_bf16 v[46:49], v[170:173], v[174:177], v[46:49]
	v_mfma_f32_16x16x32_bf16 v[74:77], v[122:125], v[178:181], v[74:77]
	v_mfma_f32_16x16x32_bf16 v[78:81], v[162:165], v[178:181], v[78:81]
	v_mfma_f32_16x16x32_bf16 v[82:85], v[166:169], v[178:181], v[82:85]
	v_mfma_f32_16x16x32_bf16 v[50:53], v[170:173], v[178:181], v[50:53]
	v_mfma_f32_16x16x32_bf16 v[86:89], v[122:125], v[182:185], v[86:89]
	v_mfma_f32_16x16x32_bf16 v[90:93], v[162:165], v[182:185], v[90:93]
	v_mfma_f32_16x16x32_bf16 v[94:97], v[166:169], v[182:185], v[94:97]
	v_mfma_f32_16x16x32_bf16 v[54:57], v[170:173], v[182:185], v[54:57]
	v_mfma_f32_16x16x32_bf16 v[98:101], v[122:125], v[186:189], v[98:101]
	v_mfma_f32_16x16x32_bf16 v[102:105], v[162:165], v[186:189], v[102:105]
	v_mfma_f32_16x16x32_bf16 v[106:109], v[166:169], v[186:189], v[106:109]
	v_mfma_f32_16x16x32_bf16 v[58:61], v[170:173], v[186:189], v[58:61]
	ds_read_b128 v[174:177], v0 offset:53248
	ds_read_b128 v[178:181], v0 offset:54272
	ds_read_b128 v[182:185], v0 offset:55296
	ds_read_b128 v[186:189], v0 offset:56320
	s_waitcnt vmcnt(6) lgkmcnt(0)
	s_barrier
	global_load_lds_dwordx4 v[190:191], off
	s_mov_b32 m0, s9
	s_waitcnt lgkmcnt(0)
	v_mfma_f32_16x16x32_bf16 v[126:129], v[122:125], v[174:177], v[126:129]
	global_load_lds_dwordx4 v[192:193], off
	s_mov_b32 m0, s19
	v_mfma_f32_16x16x32_bf16 v[130:133], v[162:165], v[174:177], v[130:133]
	global_load_lds_dwordx4 v[194:195], off
	s_mov_b32 m0, s18
	v_mfma_f32_16x16x32_bf16 v[134:137], v[166:169], v[174:177], v[134:137]
	global_load_lds_dwordx4 v[214:215], off
	s_mov_b32 m0, s20
	v_mfma_f32_16x16x32_bf16 v[110:113], v[170:173], v[174:177], v[110:113]
	global_load_lds_dwordx4 v[216:217], off
	s_mov_b32 m0, s21
	v_mfma_f32_16x16x32_bf16 v[138:141], v[122:125], v[178:181], v[138:141]
	global_load_lds_dwordx4 v[218:219], off
	s_mov_b64 s[8:9], 0x20240
	v_mfma_f32_16x16x32_bf16 v[142:145], v[162:165], v[178:181], v[142:145]
	v_lshl_add_u64 v[194:195], v[2:3], 0, s[8:9]
	s_mov_b64 s[8:9], 0x30240
	v_lshl_add_u64 v[214:215], v[2:3], 0, s[8:9]
	v_mfma_f32_16x16x32_bf16 v[146:149], v[166:169], v[178:181], v[146:149]
	v_readfirstlane_b32 s8, v19
	v_lshl_add_u64 v[190:191], v[2:3], 0, s[22:23]
	s_mov_b32 m0, s8
	v_mfma_f32_16x16x32_bf16 v[114:117], v[170:173], v[178:181], v[114:117]
	v_readfirstlane_b32 s9, v21
	v_lshl_add_u64 v[192:193], v[4:5], 0, s[22:23]
	v_readfirstlane_b32 s18, v20
	v_mfma_f32_16x16x32_bf16 v[150:153], v[122:125], v[182:185], v[150:153]
	s_mov_b64 s[20:21], 0x20280
	v_readfirstlane_b32 s19, v18
	v_lshl_add_u64 v[216:217], v[8:9], 0, s[22:23]
	v_mfma_f32_16x16x32_bf16 v[154:157], v[162:165], v[182:185], v[154:157]
	v_lshl_add_u64 v[218:219], v[6:7], 0, s[22:23]
	s_mov_b64 s[22:23], 0x280
	v_mfma_f32_16x16x32_bf16 v[158:161], v[166:169], v[182:185], v[158:161]
	v_mfma_f32_16x16x32_bf16 v[118:121], v[170:173], v[182:185], v[118:121]
	v_mfma_f32_16x16x32_bf16 v[30:33], v[122:125], v[186:189], v[30:33]
	v_mfma_f32_16x16x32_bf16 v[34:37], v[162:165], v[186:189], v[34:37]
	v_mfma_f32_16x16x32_bf16 v[38:41], v[166:169], v[186:189], v[38:41]
	v_mfma_f32_16x16x32_bf16 v[42:45], v[170:173], v[186:189], v[42:45]
	ds_read_b128 v[122:125], v10 offset:16384
	ds_read_b128 v[162:165], v10 offset:17408
	ds_read_b128 v[166:169], v10 offset:18432
	ds_read_b128 v[170:173], v10 offset:19456
	ds_read_b128 v[174:177], v0
	ds_read_b128 v[178:181], v0 offset:1024
	ds_read_b128 v[182:185], v0 offset:2048
	ds_read_b128 v[186:189], v0 offset:3072
	s_waitcnt lgkmcnt(0)
	v_mfma_f32_16x16x32_bf16 v[62:65], v[122:125], v[174:177], v[62:65]
	v_mfma_f32_16x16x32_bf16 v[66:69], v[162:165], v[174:177], v[66:69]
	v_mfma_f32_16x16x32_bf16 v[70:73], v[166:169], v[174:177], v[70:73]
	v_mfma_f32_16x16x32_bf16 v[46:49], v[170:173], v[174:177], v[46:49]
	v_mfma_f32_16x16x32_bf16 v[74:77], v[122:125], v[178:181], v[74:77]
	v_mfma_f32_16x16x32_bf16 v[78:81], v[162:165], v[178:181], v[78:81]
	v_mfma_f32_16x16x32_bf16 v[82:85], v[166:169], v[178:181], v[82:85]
	v_mfma_f32_16x16x32_bf16 v[50:53], v[170:173], v[178:181], v[50:53]
	v_mfma_f32_16x16x32_bf16 v[86:89], v[122:125], v[182:185], v[86:89]
	v_mfma_f32_16x16x32_bf16 v[90:93], v[162:165], v[182:185], v[90:93]
	v_mfma_f32_16x16x32_bf16 v[94:97], v[166:169], v[182:185], v[94:97]
	v_mfma_f32_16x16x32_bf16 v[54:57], v[170:173], v[182:185], v[54:57]
	v_mfma_f32_16x16x32_bf16 v[98:101], v[122:125], v[186:189], v[98:101]
	v_mfma_f32_16x16x32_bf16 v[102:105], v[162:165], v[186:189], v[102:105]
	v_mfma_f32_16x16x32_bf16 v[106:109], v[166:169], v[186:189], v[106:109]
	v_mfma_f32_16x16x32_bf16 v[58:61], v[170:173], v[186:189], v[58:61]
	ds_read_b128 v[174:177], v0 offset:4096
	ds_read_b128 v[178:181], v0 offset:5120
	ds_read_b128 v[182:185], v0 offset:6144
	ds_read_b128 v[186:189], v0 offset:7168
	s_waitcnt vmcnt(6) lgkmcnt(0)
	s_barrier
	global_load_lds_dwordx4 v[190:191], off
	s_mov_b32 m0, s9
	v_lshl_add_u64 v[190:191], v[2:3], 0, s[20:21]
	global_load_lds_dwordx4 v[192:193], off
	s_mov_b32 m0, s18
	s_mov_b64 s[20:21], 0x30280
	global_load_lds_dwordx4 v[194:195], off
	s_mov_b32 m0, s19
	v_lshl_add_u64 v[192:193], v[2:3], 0, s[20:21]
	v_readfirstlane_b32 s21, v28
	global_load_lds_dwordx4 v[214:215], off
	s_mov_b32 m0, s21
	v_readfirstlane_b32 s20, v29
	global_load_lds_dwordx4 v[216:217], off
	s_mov_b32 m0, s20
	s_waitcnt lgkmcnt(0)
	v_mfma_f32_16x16x32_bf16 v[126:129], v[122:125], v[174:177], v[126:129]
	global_load_lds_dwordx4 v[218:219], off
	v_lshl_add_u64 v[194:195], v[8:9], 0, s[22:23]
	v_mfma_f32_16x16x32_bf16 v[130:133], v[162:165], v[174:177], v[130:133]
	v_lshl_add_u64 v[214:215], v[6:7], 0, s[22:23]
	v_mfma_f32_16x16x32_bf16 v[134:137], v[166:169], v[174:177], v[134:137]
	v_mfma_f32_16x16x32_bf16 v[110:113], v[170:173], v[174:177], v[110:113]
	v_mfma_f32_16x16x32_bf16 v[138:141], v[122:125], v[178:181], v[138:141]
	v_mfma_f32_16x16x32_bf16 v[142:145], v[162:165], v[178:181], v[142:145]
	v_mfma_f32_16x16x32_bf16 v[146:149], v[166:169], v[178:181], v[146:149]
	v_mfma_f32_16x16x32_bf16 v[114:117], v[170:173], v[178:181], v[114:117]
	v_mfma_f32_16x16x32_bf16 v[150:153], v[122:125], v[182:185], v[150:153]
	v_mfma_f32_16x16x32_bf16 v[154:157], v[162:165], v[182:185], v[154:157]
	v_mfma_f32_16x16x32_bf16 v[158:161], v[166:169], v[182:185], v[158:161]
	v_mfma_f32_16x16x32_bf16 v[118:121], v[170:173], v[182:185], v[118:121]
	v_mfma_f32_16x16x32_bf16 v[30:33], v[122:125], v[186:189], v[30:33]
	v_mfma_f32_16x16x32_bf16 v[34:37], v[162:165], v[186:189], v[34:37]
	v_mfma_f32_16x16x32_bf16 v[38:41], v[166:169], v[186:189], v[38:41]
	v_mfma_f32_16x16x32_bf16 v[42:45], v[170:173], v[186:189], v[42:45]
	ds_read_b128 v[18:21], v10 offset:40960
	ds_read_b128 v[122:125], v10 offset:41984
	ds_read_b128 v[162:165], v10 offset:43008
	ds_read_b128 v[166:169], v10 offset:44032
	ds_read_b128 v[170:173], v0 offset:24576
	ds_read_b128 v[174:177], v0 offset:25600
	ds_read_b128 v[178:181], v0 offset:26624
	ds_read_b128 v[182:185], v0 offset:27648
	v_lshl_add_u64 v[186:187], v[2:3], 0, s[22:23]
	v_lshl_add_u64 v[188:189], v[4:5], 0, s[22:23]
	v_readfirstlane_b32 s22, v27
	s_waitcnt lgkmcnt(0)
	v_mfma_f32_16x16x32_bf16 v[62:65], v[18:21], v[170:173], v[62:65]
	s_mov_b32 m0, s22
	v_readfirstlane_b32 s23, v26
	v_mfma_f32_16x16x32_bf16 v[66:69], v[122:125], v[170:173], v[66:69]
	v_mfma_f32_16x16x32_bf16 v[70:73], v[162:165], v[170:173], v[70:73]
	v_mfma_f32_16x16x32_bf16 v[46:49], v[166:169], v[170:173], v[46:49]
	v_mfma_f32_16x16x32_bf16 v[74:77], v[18:21], v[174:177], v[74:77]
	v_mfma_f32_16x16x32_bf16 v[78:81], v[122:125], v[174:177], v[78:81]
	v_mfma_f32_16x16x32_bf16 v[82:85], v[162:165], v[174:177], v[82:85]
	v_mfma_f32_16x16x32_bf16 v[50:53], v[166:169], v[174:177], v[50:53]
	v_mfma_f32_16x16x32_bf16 v[86:89], v[18:21], v[178:181], v[86:89]
	v_mfma_f32_16x16x32_bf16 v[90:93], v[122:125], v[178:181], v[90:93]
	v_mfma_f32_16x16x32_bf16 v[94:97], v[162:165], v[178:181], v[94:97]
	v_mfma_f32_16x16x32_bf16 v[54:57], v[166:169], v[178:181], v[54:57]
	v_mfma_f32_16x16x32_bf16 v[98:101], v[18:21], v[182:185], v[98:101]
	v_mfma_f32_16x16x32_bf16 v[102:105], v[122:125], v[182:185], v[102:105]
	v_mfma_f32_16x16x32_bf16 v[106:109], v[162:165], v[182:185], v[106:109]
	v_mfma_f32_16x16x32_bf16 v[58:61], v[166:169], v[182:185], v[58:61]
	ds_read_b128 v[170:173], v0 offset:28672
	ds_read_b128 v[174:177], v0 offset:29696
	ds_read_b128 v[178:181], v0 offset:30720
	ds_read_b128 v[182:185], v0 offset:31744
	s_waitcnt vmcnt(6) lgkmcnt(0)
	s_barrier
	global_load_lds_dwordx4 v[186:187], off
	s_mov_b32 m0, s23
	v_lshl_add_u64 v[186:187], v[2:3], 0, s[26:27]
	global_load_lds_dwordx4 v[188:189], off
	s_mov_b32 m0, s24
	s_mov_b64 s[26:27], 0x302c0
	global_load_lds_dwordx4 v[190:191], off
	s_mov_b32 m0, s25
	v_lshl_add_u64 v[188:189], v[2:3], 0, s[26:27]
	v_readfirstlane_b32 s26, v23
	global_load_lds_dwordx4 v[192:193], off
	s_mov_b32 m0, s26
	v_readfirstlane_b32 s27, v24
	global_load_lds_dwordx4 v[194:195], off
	s_mov_b32 m0, s27
	s_waitcnt lgkmcnt(0)
	v_mfma_f32_16x16x32_bf16 v[126:129], v[18:21], v[170:173], v[126:129]
	global_load_lds_dwordx4 v[214:215], off
	v_lshl_add_u64 v[190:191], v[8:9], 0, s[36:37]
	v_mfma_f32_16x16x32_bf16 v[130:133], v[122:125], v[170:173], v[130:133]
	v_lshl_add_u64 v[192:193], v[6:7], 0, s[36:37]
	v_mfma_f32_16x16x32_bf16 v[134:137], v[162:165], v[170:173], v[134:137]
	v_mfma_f32_16x16x32_bf16 v[110:113], v[166:169], v[170:173], v[110:113]
	v_mfma_f32_16x16x32_bf16 v[138:141], v[18:21], v[174:177], v[138:141]
	v_mfma_f32_16x16x32_bf16 v[142:145], v[122:125], v[174:177], v[142:145]
	v_mfma_f32_16x16x32_bf16 v[146:149], v[162:165], v[174:177], v[146:149]
	v_mfma_f32_16x16x32_bf16 v[114:117], v[166:169], v[174:177], v[114:117]
	v_mfma_f32_16x16x32_bf16 v[150:153], v[18:21], v[178:181], v[150:153]
	v_mfma_f32_16x16x32_bf16 v[154:157], v[122:125], v[178:181], v[154:157]
	v_mfma_f32_16x16x32_bf16 v[158:161], v[162:165], v[178:181], v[158:161]
	v_mfma_f32_16x16x32_bf16 v[118:121], v[166:169], v[178:181], v[118:121]
	v_mfma_f32_16x16x32_bf16 v[18:21], v[18:21], v[182:185], v[30:33]
	v_mfma_f32_16x16x32_bf16 v[28:31], v[122:125], v[182:185], v[34:37]
	v_mfma_f32_16x16x32_bf16 v[32:35], v[162:165], v[182:185], v[38:41]
	v_mfma_f32_16x16x32_bf16 v[36:39], v[166:169], v[182:185], v[42:45]
	ds_read_b128 v[22:25], v11 offset:16384
	s_nop 1
	ds_read_b128 v[40:43], v11 offset:17408
	ds_read_b128 v[122:125], v11 offset:18432
	ds_read_b128 v[162:165], v11 offset:19456
	ds_read_b128 v[166:169], v0 offset:49152
	ds_read_b128 v[170:173], v0 offset:50176
	ds_read_b128 v[174:177], v0 offset:51200
	ds_read_b128 v[178:181], v0 offset:52224
	v_lshl_add_u64 v[182:183], v[2:3], 0, s[36:37]
	v_lshl_add_u64 v[184:185], v[4:5], 0, s[36:37]
	v_readfirstlane_b32 s36, v12
	s_waitcnt lgkmcnt(0)
	v_mfma_f32_16x16x32_bf16 v[62:65], v[22:25], v[166:169], v[62:65]
	s_mov_b32 m0, s36
	v_readfirstlane_b32 s37, v13
	v_mfma_f32_16x16x32_bf16 v[66:69], v[40:43], v[166:169], v[66:69]
	v_mfma_f32_16x16x32_bf16 v[70:73], v[122:125], v[166:169], v[70:73]
	v_mfma_f32_16x16x32_bf16 v[44:47], v[162:165], v[166:169], v[46:49]
	v_mfma_f32_16x16x32_bf16 v[74:77], v[22:25], v[170:173], v[74:77]
	v_mfma_f32_16x16x32_bf16 v[78:81], v[40:43], v[170:173], v[78:81]
	v_mfma_f32_16x16x32_bf16 v[82:85], v[122:125], v[170:173], v[82:85]
	v_mfma_f32_16x16x32_bf16 v[48:51], v[162:165], v[170:173], v[50:53]
	v_mfma_f32_16x16x32_bf16 v[86:89], v[22:25], v[174:177], v[86:89]
	v_mfma_f32_16x16x32_bf16 v[90:93], v[40:43], v[174:177], v[90:93]
	v_mfma_f32_16x16x32_bf16 v[94:97], v[122:125], v[174:177], v[94:97]
	v_mfma_f32_16x16x32_bf16 v[52:55], v[162:165], v[174:177], v[54:57]
	v_mfma_f32_16x16x32_bf16 v[98:101], v[22:25], v[178:181], v[98:101]
	v_mfma_f32_16x16x32_bf16 v[102:105], v[40:43], v[178:181], v[102:105]
	v_mfma_f32_16x16x32_bf16 v[106:109], v[122:125], v[178:181], v[106:109]
	v_mfma_f32_16x16x32_bf16 v[56:59], v[162:165], v[178:181], v[58:61]
	ds_read_b128 v[166:169], v0 offset:53248
	ds_read_b128 v[170:173], v0 offset:54272
	ds_read_b128 v[174:177], v0 offset:55296
	ds_read_b128 v[178:181], v0 offset:56320
	s_waitcnt vmcnt(6) lgkmcnt(0)
	s_barrier
	global_load_lds_dwordx4 v[182:183], off
	s_mov_b32 m0, s37
	v_lshl_add_u64 v[182:183], v[2:3], 0, s[40:41]
	global_load_lds_dwordx4 v[184:185], off
	s_mov_b32 m0, s38
	s_mov_b64 s[40:41], 0x30300
	global_load_lds_dwordx4 v[186:187], off
	s_mov_b32 m0, s39
	v_lshl_add_u64 v[184:185], v[2:3], 0, s[40:41]
	v_readfirstlane_b32 s40, v16
	global_load_lds_dwordx4 v[188:189], off
	s_mov_b32 m0, s40
	v_readfirstlane_b32 s41, v17
	global_load_lds_dwordx4 v[190:191], off
	s_mov_b32 m0, s41
	s_waitcnt lgkmcnt(0)
	v_mfma_f32_16x16x32_bf16 v[126:129], v[22:25], v[166:169], v[126:129]
	global_load_lds_dwordx4 v[192:193], off
	s_mov_b32 m0, s8
	v_mfma_f32_16x16x32_bf16 v[130:133], v[40:43], v[166:169], v[130:133]
	v_lshl_add_u64 v[186:187], v[8:9], 0, s[42:43]
	v_lshl_add_u64 v[188:189], v[6:7], 0, s[42:43]
	v_mfma_f32_16x16x32_bf16 v[134:137], v[122:125], v[166:169], v[134:137]
	v_mfma_f32_16x16x32_bf16 v[110:113], v[162:165], v[166:169], v[110:113]
	v_mfma_f32_16x16x32_bf16 v[138:141], v[22:25], v[170:173], v[138:141]
	v_mfma_f32_16x16x32_bf16 v[142:145], v[40:43], v[170:173], v[142:145]
	v_mfma_f32_16x16x32_bf16 v[146:149], v[122:125], v[170:173], v[146:149]
	v_mfma_f32_16x16x32_bf16 v[114:117], v[162:165], v[170:173], v[114:117]
	v_mfma_f32_16x16x32_bf16 v[150:153], v[22:25], v[174:177], v[150:153]
	v_mfma_f32_16x16x32_bf16 v[154:157], v[40:43], v[174:177], v[154:157]
	v_mfma_f32_16x16x32_bf16 v[158:161], v[122:125], v[174:177], v[158:161]
	v_mfma_f32_16x16x32_bf16 v[118:121], v[162:165], v[174:177], v[118:121]
	v_mfma_f32_16x16x32_bf16 v[18:21], v[22:25], v[178:181], v[18:21]
	v_mfma_f32_16x16x32_bf16 v[22:25], v[40:43], v[178:181], v[28:31]
	v_mfma_f32_16x16x32_bf16 v[26:29], v[122:125], v[178:181], v[32:35]
	v_mfma_f32_16x16x32_bf16 v[30:33], v[162:165], v[178:181], v[36:39]
	ds_read_b128 v[12:15], v10 offset:16384
	s_nop 1
	ds_read_b128 v[34:37], v10 offset:17408
	ds_read_b128 v[38:41], v10 offset:18432
	ds_read_b128 v[122:125], v10 offset:19456
	ds_read_b128 v[162:165], v0
	ds_read_b128 v[166:169], v0 offset:1024
	ds_read_b128 v[170:173], v0 offset:2048
	ds_read_b128 v[174:177], v0 offset:3072
	v_lshl_add_u64 v[178:179], v[2:3], 0, s[42:43]
	v_lshl_add_u64 v[180:181], v[4:5], 0, s[42:43]
	s_waitcnt lgkmcnt(0)
	v_mfma_f32_16x16x32_bf16 v[60:63], v[12:15], v[162:165], v[62:65]
	s_mov_b64 s[42:43], 0x20340
	v_mfma_f32_16x16x32_bf16 v[64:67], v[34:37], v[162:165], v[66:69]
	v_mfma_f32_16x16x32_bf16 v[68:71], v[38:41], v[162:165], v[70:73]
	v_mfma_f32_16x16x32_bf16 v[42:45], v[122:125], v[162:165], v[44:47]
	v_mfma_f32_16x16x32_bf16 v[72:75], v[12:15], v[166:169], v[74:77]
	v_mfma_f32_16x16x32_bf16 v[76:79], v[34:37], v[166:169], v[78:81]
	v_mfma_f32_16x16x32_bf16 v[80:83], v[38:41], v[166:169], v[82:85]
	v_mfma_f32_16x16x32_bf16 v[46:49], v[122:125], v[166:169], v[48:51]
	v_mfma_f32_16x16x32_bf16 v[84:87], v[12:15], v[170:173], v[86:89]
	v_mfma_f32_16x16x32_bf16 v[88:91], v[34:37], v[170:173], v[90:93]
	v_mfma_f32_16x16x32_bf16 v[92:95], v[38:41], v[170:173], v[94:97]
	v_mfma_f32_16x16x32_bf16 v[50:53], v[122:125], v[170:173], v[52:55]
	v_mfma_f32_16x16x32_bf16 v[96:99], v[12:15], v[174:177], v[98:101]
	v_mfma_f32_16x16x32_bf16 v[100:103], v[34:37], v[174:177], v[102:105]
	v_mfma_f32_16x16x32_bf16 v[104:107], v[38:41], v[174:177], v[106:109]
	v_mfma_f32_16x16x32_bf16 v[54:57], v[122:125], v[174:177], v[56:59]
	ds_read_b128 v[162:165], v0 offset:4096
	ds_read_b128 v[166:169], v0 offset:5120
	ds_read_b128 v[170:173], v0 offset:6144
	ds_read_b128 v[174:177], v0 offset:7168
	s_waitcnt vmcnt(6) lgkmcnt(0)
	s_barrier
	global_load_lds_dwordx4 v[178:179], off
	s_mov_b32 m0, s9
	s_waitcnt lgkmcnt(0)
	v_mfma_f32_16x16x32_bf16 v[126:129], v[12:15], v[162:165], v[126:129]
	global_load_lds_dwordx4 v[180:181], off
	s_mov_b32 m0, s18
	v_mfma_f32_16x16x32_bf16 v[130:133], v[34:37], v[162:165], v[130:133]
	global_load_lds_dwordx4 v[182:183], off
	s_mov_b32 m0, s19
	v_mfma_f32_16x16x32_bf16 v[134:137], v[38:41], v[162:165], v[134:137]
	global_load_lds_dwordx4 v[184:185], off
	s_mov_b32 m0, s21
	v_mfma_f32_16x16x32_bf16 v[108:111], v[122:125], v[162:165], v[110:113]
	global_load_lds_dwordx4 v[186:187], off
	s_mov_b32 m0, s20
	v_mfma_f32_16x16x32_bf16 v[138:141], v[12:15], v[166:169], v[138:141]
	global_load_lds_dwordx4 v[188:189], off
	v_lshl_add_u64 v[178:179], v[2:3], 0, s[58:59]
	v_mfma_f32_16x16x32_bf16 v[142:145], v[34:37], v[166:169], v[142:145]
	s_mov_b32 m0, s22
	v_lshl_add_u64 v[180:181], v[4:5], 0, s[58:59]
	v_lshl_add_u64 v[182:183], v[2:3], 0, s[42:43]
	v_mfma_f32_16x16x32_bf16 v[146:149], v[38:41], v[166:169], v[146:149]
	s_mov_b64 s[42:43], 0x30340
	v_lshl_add_u64 v[184:185], v[2:3], 0, s[42:43]
	v_lshl_add_u64 v[186:187], v[8:9], 0, s[58:59]
	v_mfma_f32_16x16x32_bf16 v[112:115], v[122:125], v[166:169], v[114:117]
	v_lshl_add_u64 v[188:189], v[6:7], 0, s[58:59]
	s_mov_b64 s[58:59], 0x380
	v_mfma_f32_16x16x32_bf16 v[150:153], v[12:15], v[170:173], v[150:153]
	v_mfma_f32_16x16x32_bf16 v[154:157], v[34:37], v[170:173], v[154:157]
	v_mfma_f32_16x16x32_bf16 v[158:161], v[38:41], v[170:173], v[158:161]
	v_mfma_f32_16x16x32_bf16 v[116:119], v[122:125], v[170:173], v[118:121]
	v_mfma_f32_16x16x32_bf16 v[12:15], v[12:15], v[174:177], v[18:21]
	v_mfma_f32_16x16x32_bf16 v[16:19], v[34:37], v[174:177], v[22:25]
	v_mfma_f32_16x16x32_bf16 v[20:23], v[38:41], v[174:177], v[26:29]
	v_mfma_f32_16x16x32_bf16 v[24:27], v[122:125], v[174:177], v[30:33]
	s_nop 2
	ds_read_b128 v[28:31], v10 offset:40960
	ds_read_b128 v[32:35], v10 offset:41984
	ds_read_b128 v[36:39], v10 offset:43008
	ds_read_b128 v[120:123], v10 offset:44032
	ds_read_b128 v[162:165], v0 offset:24576
	ds_read_b128 v[166:169], v0 offset:25600
	ds_read_b128 v[170:173], v0 offset:26624
	ds_read_b128 v[174:177], v0 offset:27648
	s_waitcnt lgkmcnt(0)
	v_mfma_f32_16x16x32_bf16 v[58:61], v[28:31], v[162:165], v[60:63]
	v_mfma_f32_16x16x32_bf16 v[62:65], v[32:35], v[162:165], v[64:67]
	v_mfma_f32_16x16x32_bf16 v[66:69], v[36:39], v[162:165], v[68:71]
	v_mfma_f32_16x16x32_bf16 v[40:43], v[120:123], v[162:165], v[42:45]
	v_mfma_f32_16x16x32_bf16 v[70:73], v[28:31], v[166:169], v[72:75]
	v_mfma_f32_16x16x32_bf16 v[74:77], v[32:35], v[166:169], v[76:79]
	v_mfma_f32_16x16x32_bf16 v[78:81], v[36:39], v[166:169], v[80:83]
	v_mfma_f32_16x16x32_bf16 v[44:47], v[120:123], v[166:169], v[46:49]
	v_mfma_f32_16x16x32_bf16 v[82:85], v[28:31], v[170:173], v[84:87]
	v_mfma_f32_16x16x32_bf16 v[86:89], v[32:35], v[170:173], v[88:91]
	v_mfma_f32_16x16x32_bf16 v[90:93], v[36:39], v[170:173], v[92:95]
	v_mfma_f32_16x16x32_bf16 v[48:51], v[120:123], v[170:173], v[50:53]
	v_mfma_f32_16x16x32_bf16 v[94:97], v[28:31], v[174:177], v[96:99]
	v_mfma_f32_16x16x32_bf16 v[98:101], v[32:35], v[174:177], v[100:103]
	v_mfma_f32_16x16x32_bf16 v[102:105], v[36:39], v[174:177], v[104:107]
	v_mfma_f32_16x16x32_bf16 v[52:55], v[120:123], v[174:177], v[54:57]
	ds_read_b128 v[162:165], v0 offset:28672
	ds_read_b128 v[166:169], v0 offset:29696
	ds_read_b128 v[170:173], v0 offset:30720
	ds_read_b128 v[174:177], v0 offset:31744
	s_waitcnt vmcnt(6) lgkmcnt(0)
	s_barrier
	global_load_lds_dwordx4 v[178:179], off
	s_mov_b32 m0, s23
	s_waitcnt lgkmcnt(0)
	v_mfma_f32_16x16x32_bf16 v[124:127], v[28:31], v[162:165], v[126:129]
	global_load_lds_dwordx4 v[180:181], off
	s_mov_b32 m0, s24
	v_mfma_f32_16x16x32_bf16 v[128:131], v[32:35], v[162:165], v[130:133]
	global_load_lds_dwordx4 v[182:183], off
	s_mov_b32 m0, s25
	v_mfma_f32_16x16x32_bf16 v[132:135], v[36:39], v[162:165], v[134:137]
	global_load_lds_dwordx4 v[184:185], off
	s_mov_b32 m0, s26
	v_mfma_f32_16x16x32_bf16 v[106:109], v[120:123], v[162:165], v[108:111]
	global_load_lds_dwordx4 v[186:187], off
	s_mov_b32 m0, s27
	v_mfma_f32_16x16x32_bf16 v[136:139], v[28:31], v[166:169], v[138:141]
	global_load_lds_dwordx4 v[188:189], off
	s_mov_b32 m0, s36
	v_mfma_f32_16x16x32_bf16 v[140:143], v[32:35], v[166:169], v[142:145]
	v_lshl_add_u64 v[178:179], v[4:5], 0, s[58:59]
	s_mov_b64 s[22:23], 0x20380
	v_lshl_add_u64 v[180:181], v[2:3], 0, s[22:23]
	v_mfma_f32_16x16x32_bf16 v[144:147], v[36:39], v[166:169], v[146:149]
	s_mov_b64 s[22:23], 0x30380
	v_lshl_add_u64 v[182:183], v[2:3], 0, s[22:23]
	v_lshl_add_u64 v[184:185], v[8:9], 0, s[58:59]
	v_mfma_f32_16x16x32_bf16 v[110:113], v[120:123], v[166:169], v[112:115]
	v_lshl_add_u64 v[186:187], v[6:7], 0, s[58:59]
	s_mov_b64 s[22:23], 0x203c0
	s_mov_b64 s[26:27], 0x3c0
	v_mfma_f32_16x16x32_bf16 v[148:151], v[28:31], v[170:173], v[150:153]
	s_mov_b64 s[24:25], 0x3000
	v_mfma_f32_16x16x32_bf16 v[152:155], v[32:35], v[170:173], v[154:157]
	v_mfma_f32_16x16x32_bf16 v[156:159], v[36:39], v[170:173], v[158:161]
	v_mfma_f32_16x16x32_bf16 v[114:117], v[120:123], v[170:173], v[116:119]
	v_mfma_f32_16x16x32_bf16 v[12:15], v[28:31], v[174:177], v[12:15]
	v_mfma_f32_16x16x32_bf16 v[16:19], v[32:35], v[174:177], v[16:19]
	v_mfma_f32_16x16x32_bf16 v[20:23], v[36:39], v[174:177], v[20:23]
	v_mfma_f32_16x16x32_bf16 v[24:27], v[120:123], v[174:177], v[24:27]
	ds_read_b128 v[28:31], v11 offset:16384
	ds_read_b128 v[32:35], v11 offset:17408
	ds_read_b128 v[36:39], v11 offset:18432
	ds_read_b128 v[118:121], v11 offset:19456
	ds_read_b128 v[160:163], v0 offset:49152
	ds_read_b128 v[164:167], v0 offset:50176
	ds_read_b128 v[168:171], v0 offset:51200
	ds_read_b128 v[172:175], v0 offset:52224
	v_lshl_add_u64 v[176:177], v[2:3], 0, s[58:59]
	s_mov_b32 s59, s44
	s_waitcnt lgkmcnt(0)
	v_mfma_f32_16x16x32_bf16 v[56:59], v[28:31], v[160:163], v[58:61]
	v_mfma_f32_16x16x32_bf16 v[60:63], v[32:35], v[160:163], v[62:65]
	v_mfma_f32_16x16x32_bf16 v[64:67], v[36:39], v[160:163], v[66:69]
	v_mfma_f32_16x16x32_bf16 v[40:43], v[118:121], v[160:163], v[40:43]
	v_mfma_f32_16x16x32_bf16 v[68:71], v[28:31], v[164:167], v[70:73]
	v_mfma_f32_16x16x32_bf16 v[72:75], v[32:35], v[164:167], v[74:77]
	v_mfma_f32_16x16x32_bf16 v[76:79], v[36:39], v[164:167], v[78:81]
	v_mfma_f32_16x16x32_bf16 v[44:47], v[118:121], v[164:167], v[44:47]
	v_mfma_f32_16x16x32_bf16 v[80:83], v[28:31], v[168:171], v[82:85]
	v_mfma_f32_16x16x32_bf16 v[84:87], v[32:35], v[168:171], v[86:89]
	v_mfma_f32_16x16x32_bf16 v[88:91], v[36:39], v[168:171], v[90:93]
	v_mfma_f32_16x16x32_bf16 v[48:51], v[118:121], v[168:171], v[48:51]
	v_mfma_f32_16x16x32_bf16 v[92:95], v[28:31], v[172:175], v[94:97]
	v_mfma_f32_16x16x32_bf16 v[96:99], v[32:35], v[172:175], v[98:101]
	v_mfma_f32_16x16x32_bf16 v[100:103], v[36:39], v[172:175], v[102:105]
	v_mfma_f32_16x16x32_bf16 v[52:55], v[118:121], v[172:175], v[52:55]
	ds_read_b128 v[160:163], v0 offset:53248
	ds_read_b128 v[164:167], v0 offset:54272
	ds_read_b128 v[168:171], v0 offset:55296
	ds_read_b128 v[172:175], v0 offset:56320
	s_waitcnt vmcnt(6) lgkmcnt(0)
	s_barrier
	global_load_lds_dwordx4 v[176:177], off
	s_mov_b32 m0, s37
	s_waitcnt lgkmcnt(0)
	v_mfma_f32_16x16x32_bf16 v[122:125], v[28:31], v[160:163], v[124:127]
	global_load_lds_dwordx4 v[178:179], off
	s_mov_b32 m0, s38
	v_mfma_f32_16x16x32_bf16 v[126:129], v[32:35], v[160:163], v[128:131]
	global_load_lds_dwordx4 v[180:181], off
	s_mov_b32 m0, s39
	v_mfma_f32_16x16x32_bf16 v[130:133], v[36:39], v[160:163], v[132:135]
	global_load_lds_dwordx4 v[182:183], off
	s_mov_b32 m0, s40
	v_mfma_f32_16x16x32_bf16 v[104:107], v[118:121], v[160:163], v[106:109]
	global_load_lds_dwordx4 v[184:185], off
	s_mov_b32 m0, s41
	v_mfma_f32_16x16x32_bf16 v[134:137], v[28:31], v[164:167], v[136:139]
	global_load_lds_dwordx4 v[186:187], off
	v_lshl_add_u64 v[176:177], v[6:7], 0, s[26:27]
	v_mfma_f32_16x16x32_bf16 v[138:141], v[32:35], v[164:167], v[140:143]
	s_mov_b32 m0, s8
	v_mfma_f32_16x16x32_bf16 v[142:145], v[36:39], v[164:167], v[144:147]
	v_mfma_f32_16x16x32_bf16 v[108:111], v[118:121], v[164:167], v[110:113]
	v_lshl_add_u64 v[166:167], v[2:3], 0, s[26:27]
	v_mfma_f32_16x16x32_bf16 v[146:149], v[28:31], v[168:171], v[148:151]
	v_mfma_f32_16x16x32_bf16 v[150:153], v[32:35], v[168:171], v[152:155]
	v_mfma_f32_16x16x32_bf16 v[154:157], v[36:39], v[168:171], v[156:159]
	v_mfma_f32_16x16x32_bf16 v[112:115], v[118:121], v[168:171], v[114:117]
	v_lshl_add_u64 v[170:171], v[2:3], 0, s[22:23]
	s_mov_b64 s[22:23], 0x303c0
	v_lshl_add_u64 v[168:169], v[4:5], 0, s[26:27]
	v_mfma_f32_16x16x32_bf16 v[12:15], v[28:31], v[172:175], v[12:15]
	v_mfma_f32_16x16x32_bf16 v[16:19], v[32:35], v[172:175], v[16:19]
	v_mfma_f32_16x16x32_bf16 v[20:23], v[36:39], v[172:175], v[20:23]
	v_mfma_f32_16x16x32_bf16 v[24:27], v[118:121], v[172:175], v[24:27]
	v_lshl_add_u64 v[172:173], v[2:3], 0, s[22:23]
	v_lshl_add_u64 v[174:175], v[8:9], 0, s[26:27]
	ds_read_b128 v[2:5], v10 offset:16384
	ds_read_b128 v[6:9], v10 offset:17408
	ds_read_b128 v[28:31], v10 offset:18432
	ds_read_b128 v[32:35], v10 offset:19456
	ds_read_b128 v[36:39], v0
	ds_read_b128 v[116:119], v0 offset:1024
	ds_read_b128 v[158:161], v0 offset:2048
	ds_read_b128 v[162:165], v0 offset:3072
	s_waitcnt lgkmcnt(0)
	v_mfma_f32_16x16x32_bf16 v[56:59], v[2:5], v[36:39], v[56:59]
	v_mfma_f32_16x16x32_bf16 v[60:63], v[6:9], v[36:39], v[60:63]
	v_mfma_f32_16x16x32_bf16 v[64:67], v[28:31], v[36:39], v[64:67]
	v_mfma_f32_16x16x32_bf16 v[36:39], v[32:35], v[36:39], v[40:43]
	v_mfma_f32_16x16x32_bf16 v[40:43], v[2:5], v[116:119], v[68:71]
	v_mfma_f32_16x16x32_bf16 v[68:71], v[6:9], v[116:119], v[72:75]
	v_mfma_f32_16x16x32_bf16 v[72:75], v[28:31], v[116:119], v[76:79]
	v_mfma_f32_16x16x32_bf16 v[44:47], v[32:35], v[116:119], v[44:47]
	v_mfma_f32_16x16x32_bf16 v[76:79], v[2:5], v[158:161], v[80:83]
	v_mfma_f32_16x16x32_bf16 v[80:83], v[6:9], v[158:161], v[84:87]
	v_mfma_f32_16x16x32_bf16 v[84:87], v[28:31], v[158:161], v[88:91]
	v_mfma_f32_16x16x32_bf16 v[48:51], v[32:35], v[158:161], v[48:51]
	v_mfma_f32_16x16x32_bf16 v[88:91], v[2:5], v[162:165], v[92:95]
	v_mfma_f32_16x16x32_bf16 v[92:95], v[6:9], v[162:165], v[96:99]
	v_mfma_f32_16x16x32_bf16 v[96:99], v[28:31], v[162:165], v[100:103]
	v_mfma_f32_16x16x32_bf16 v[52:55], v[32:35], v[162:165], v[52:55]
	s_nop 1
	ds_read_b128 v[100:103], v0 offset:4096
	ds_read_b128 v[116:119], v0 offset:5120
	ds_read_b128 v[158:161], v0 offset:6144
	ds_read_b128 v[162:165], v0 offset:7168
	s_waitcnt vmcnt(6) lgkmcnt(0)
	s_barrier
	global_load_lds_dwordx4 v[166:167], off
	s_mov_b32 m0, s9
	s_waitcnt lgkmcnt(0)
	v_mfma_f32_16x16x32_bf16 v[120:123], v[2:5], v[100:103], v[122:125]
	global_load_lds_dwordx4 v[168:169], off
	s_mov_b32 m0, s18
	v_mfma_f32_16x16x32_bf16 v[124:127], v[6:9], v[100:103], v[126:129]
	global_load_lds_dwordx4 v[170:171], off
	s_mov_b32 m0, s19
	v_mfma_f32_16x16x32_bf16 v[128:131], v[28:31], v[100:103], v[130:133]
	global_load_lds_dwordx4 v[172:173], off
	s_mov_b32 m0, s21
	v_mfma_f32_16x16x32_bf16 v[100:103], v[32:35], v[100:103], v[104:107]
	global_load_lds_dwordx4 v[174:175], off
	s_mov_b32 m0, s20
	v_mfma_f32_16x16x32_bf16 v[104:107], v[2:5], v[116:119], v[134:137]
	global_load_lds_dwordx4 v[176:177], off
	v_mfma_f32_16x16x32_bf16 v[132:135], v[6:9], v[116:119], v[138:141]
	v_mfma_f32_16x16x32_bf16 v[136:139], v[28:31], v[116:119], v[142:145]
	v_mfma_f32_16x16x32_bf16 v[108:111], v[32:35], v[116:119], v[108:111]
	v_mfma_f32_16x16x32_bf16 v[116:119], v[2:5], v[158:161], v[146:149]
	v_mfma_f32_16x16x32_bf16 v[140:143], v[6:9], v[158:161], v[150:153]
	v_mfma_f32_16x16x32_bf16 v[144:147], v[28:31], v[158:161], v[154:157]
	v_mfma_f32_16x16x32_bf16 v[112:115], v[32:35], v[158:161], v[112:115]
	v_mfma_f32_16x16x32_bf16 v[2:5], v[2:5], v[162:165], v[12:15]
	v_mfma_f32_16x16x32_bf16 v[6:9], v[6:9], v[162:165], v[16:19]
	v_mfma_f32_16x16x32_bf16 v[12:15], v[28:31], v[162:165], v[20:23]
	v_mfma_f32_16x16x32_bf16 v[16:19], v[32:35], v[162:165], v[24:27]
	s_nop 1
	ds_read_b128 v[20:23], v10 offset:40960
	ds_read_b128 v[24:27], v10 offset:41984
	ds_read_b128 v[28:31], v10 offset:43008
	ds_read_b128 v[32:35], v10 offset:44032
	ds_read_b128 v[148:151], v0 offset:24576
	ds_read_b128 v[152:155], v0 offset:25600
	ds_read_b128 v[156:159], v0 offset:26624
	ds_read_b128 v[160:163], v0 offset:27648
	s_waitcnt lgkmcnt(0)
	v_mfma_f32_16x16x32_bf16 v[56:59], v[20:23], v[148:151], v[56:59]
	v_mfma_f32_16x16x32_bf16 v[60:63], v[24:27], v[148:151], v[60:63]
	v_mfma_f32_16x16x32_bf16 v[64:67], v[28:31], v[148:151], v[64:67]
	v_mfma_f32_16x16x32_bf16 v[36:39], v[32:35], v[148:151], v[36:39]
	v_mfma_f32_16x16x32_bf16 v[40:43], v[20:23], v[152:155], v[40:43]
	v_mfma_f32_16x16x32_bf16 v[68:71], v[24:27], v[152:155], v[68:71]
	v_mfma_f32_16x16x32_bf16 v[72:75], v[28:31], v[152:155], v[72:75]
	v_mfma_f32_16x16x32_bf16 v[44:47], v[32:35], v[152:155], v[44:47]
	v_mfma_f32_16x16x32_bf16 v[76:79], v[20:23], v[156:159], v[76:79]
	v_mfma_f32_16x16x32_bf16 v[80:83], v[24:27], v[156:159], v[80:83]
	v_mfma_f32_16x16x32_bf16 v[84:87], v[28:31], v[156:159], v[84:87]
	v_mfma_f32_16x16x32_bf16 v[48:51], v[32:35], v[156:159], v[48:51]
	v_mfma_f32_16x16x32_bf16 v[88:91], v[20:23], v[160:163], v[88:91]
	v_mfma_f32_16x16x32_bf16 v[92:95], v[24:27], v[160:163], v[92:95]
	v_mfma_f32_16x16x32_bf16 v[96:99], v[28:31], v[160:163], v[96:99]
	v_mfma_f32_16x16x32_bf16 v[52:55], v[32:35], v[160:163], v[52:55]
	ds_read_b128 v[148:151], v0 offset:28672
	ds_read_b128 v[152:155], v0 offset:29696
	ds_read_b128 v[156:159], v0 offset:30720
	ds_read_b128 v[160:163], v0 offset:31744
	s_waitcnt vmcnt(6) lgkmcnt(0)
	s_barrier
	s_waitcnt lgkmcnt(0)
	v_mfma_f32_16x16x32_bf16 v[120:123], v[20:23], v[148:151], v[120:123]
	v_mfma_f32_16x16x32_bf16 v[124:127], v[24:27], v[148:151], v[124:127]
	v_mfma_f32_16x16x32_bf16 v[128:131], v[28:31], v[148:151], v[128:131]
	v_mfma_f32_16x16x32_bf16 v[100:103], v[32:35], v[148:151], v[100:103]
	v_mfma_f32_16x16x32_bf16 v[104:107], v[20:23], v[152:155], v[104:107]
	v_mfma_f32_16x16x32_bf16 v[132:135], v[24:27], v[152:155], v[132:135]
	v_mfma_f32_16x16x32_bf16 v[136:139], v[28:31], v[152:155], v[136:139]
	v_mfma_f32_16x16x32_bf16 v[108:111], v[32:35], v[152:155], v[108:111]
	v_mfma_f32_16x16x32_bf16 v[116:119], v[20:23], v[156:159], v[116:119]
	v_mfma_f32_16x16x32_bf16 v[140:143], v[24:27], v[156:159], v[140:143]
	v_mfma_f32_16x16x32_bf16 v[144:147], v[28:31], v[156:159], v[144:147]
	v_mfma_f32_16x16x32_bf16 v[112:115], v[32:35], v[156:159], v[112:115]
	v_mfma_f32_16x16x32_bf16 v[2:5], v[20:23], v[160:163], v[2:5]
	v_mfma_f32_16x16x32_bf16 v[6:9], v[24:27], v[160:163], v[6:9]
	v_mfma_f32_16x16x32_bf16 v[12:15], v[28:31], v[160:163], v[12:15]
	v_mfma_f32_16x16x32_bf16 v[16:19], v[32:35], v[160:163], v[16:19]
	ds_read_b128 v[20:23], v11 offset:16384
	ds_read_b128 v[24:27], v11 offset:17408
	ds_read_b128 v[28:31], v11 offset:18432
	ds_read_b128 v[32:35], v11 offset:19456
	ds_read_b128 v[148:151], v0 offset:49152
	ds_read_b128 v[152:155], v0 offset:50176
	ds_read_b128 v[156:159], v0 offset:51200
	ds_read_b128 v[160:163], v0 offset:52224
	s_waitcnt lgkmcnt(0)
	v_mfma_f32_16x16x32_bf16 v[56:59], v[20:23], v[148:151], v[56:59]
	v_mfma_f32_16x16x32_bf16 v[60:63], v[24:27], v[148:151], v[60:63]
	v_mfma_f32_16x16x32_bf16 v[64:67], v[28:31], v[148:151], v[64:67]
	v_mfma_f32_16x16x32_bf16 v[36:39], v[32:35], v[148:151], v[36:39]
	v_mfma_f32_16x16x32_bf16 v[40:43], v[20:23], v[152:155], v[40:43]
	v_mfma_f32_16x16x32_bf16 v[68:71], v[24:27], v[152:155], v[68:71]
	v_mfma_f32_16x16x32_bf16 v[72:75], v[28:31], v[152:155], v[72:75]
	v_mfma_f32_16x16x32_bf16 v[44:47], v[32:35], v[152:155], v[44:47]
	v_mfma_f32_16x16x32_bf16 v[76:79], v[20:23], v[156:159], v[76:79]
	v_mfma_f32_16x16x32_bf16 v[80:83], v[24:27], v[156:159], v[80:83]
	v_mfma_f32_16x16x32_bf16 v[84:87], v[28:31], v[156:159], v[84:87]
	v_mfma_f32_16x16x32_bf16 v[48:51], v[32:35], v[156:159], v[48:51]
	v_mfma_f32_16x16x32_bf16 v[88:91], v[20:23], v[160:163], v[88:91]
	v_mfma_f32_16x16x32_bf16 v[92:95], v[24:27], v[160:163], v[92:95]
	v_mfma_f32_16x16x32_bf16 v[96:99], v[28:31], v[160:163], v[96:99]
	v_mfma_f32_16x16x32_bf16 v[52:55], v[32:35], v[160:163], v[52:55]
	ds_read_b128 v[148:151], v0 offset:53248
	ds_read_b128 v[152:155], v0 offset:54272
	ds_read_b128 v[156:159], v0 offset:55296
	ds_read_b128 v[160:163], v0 offset:56320
	s_waitcnt vmcnt(0) lgkmcnt(0)
	s_barrier
	s_waitcnt lgkmcnt(0)
	v_mfma_f32_16x16x32_bf16 v[120:123], v[20:23], v[148:151], v[120:123]
	v_mfma_f32_16x16x32_bf16 v[124:127], v[24:27], v[148:151], v[124:127]
	v_mfma_f32_16x16x32_bf16 v[128:131], v[28:31], v[148:151], v[128:131]
	v_mfma_f32_16x16x32_bf16 v[100:103], v[32:35], v[148:151], v[100:103]
	v_mfma_f32_16x16x32_bf16 v[104:107], v[20:23], v[152:155], v[104:107]
	v_mfma_f32_16x16x32_bf16 v[132:135], v[24:27], v[152:155], v[132:135]
	v_mfma_f32_16x16x32_bf16 v[136:139], v[28:31], v[152:155], v[136:139]
	v_mfma_f32_16x16x32_bf16 v[108:111], v[32:35], v[152:155], v[108:111]
	v_mfma_f32_16x16x32_bf16 v[116:119], v[20:23], v[156:159], v[116:119]
	v_mfma_f32_16x16x32_bf16 v[140:143], v[24:27], v[156:159], v[140:143]
	v_mfma_f32_16x16x32_bf16 v[144:147], v[28:31], v[156:159], v[144:147]
	v_mfma_f32_16x16x32_bf16 v[112:115], v[32:35], v[156:159], v[112:115]
	v_mfma_f32_16x16x32_bf16 v[2:5], v[20:23], v[160:163], v[2:5]
	v_mfma_f32_16x16x32_bf16 v[6:9], v[24:27], v[160:163], v[6:9]
	v_mfma_f32_16x16x32_bf16 v[12:15], v[28:31], v[160:163], v[12:15]
	v_mfma_f32_16x16x32_bf16 v[16:19], v[32:35], v[160:163], v[16:19]
	ds_read_b128 v[20:23], v10 offset:16384
	ds_read_b128 v[24:27], v10 offset:17408
	ds_read_b128 v[28:31], v10 offset:18432
	ds_read_b128 v[32:35], v10 offset:19456
	ds_read_b128 v[148:151], v0
	ds_read_b128 v[152:155], v0 offset:1024
	ds_read_b128 v[156:159], v0 offset:2048
	ds_read_b128 v[160:163], v0 offset:3072
	s_waitcnt lgkmcnt(0)
	v_mfma_f32_16x16x32_bf16 v[56:59], v[20:23], v[148:151], v[56:59]
	v_mfma_f32_16x16x32_bf16 v[60:63], v[24:27], v[148:151], v[60:63]
	v_mfma_f32_16x16x32_bf16 v[64:67], v[28:31], v[148:151], v[64:67]
	v_mfma_f32_16x16x32_bf16 v[36:39], v[32:35], v[148:151], v[36:39]
	v_mfma_f32_16x16x32_bf16 v[40:43], v[20:23], v[152:155], v[40:43]
	v_mfma_f32_16x16x32_bf16 v[68:71], v[24:27], v[152:155], v[68:71]
	v_mfma_f32_16x16x32_bf16 v[72:75], v[28:31], v[152:155], v[72:75]
	v_mfma_f32_16x16x32_bf16 v[44:47], v[32:35], v[152:155], v[44:47]
	v_mfma_f32_16x16x32_bf16 v[76:79], v[20:23], v[156:159], v[76:79]
	v_mfma_f32_16x16x32_bf16 v[80:83], v[24:27], v[156:159], v[80:83]
	v_mfma_f32_16x16x32_bf16 v[84:87], v[28:31], v[156:159], v[84:87]
	v_mfma_f32_16x16x32_bf16 v[48:51], v[32:35], v[156:159], v[48:51]
	v_mfma_f32_16x16x32_bf16 v[88:91], v[20:23], v[160:163], v[88:91]
	v_mfma_f32_16x16x32_bf16 v[92:95], v[24:27], v[160:163], v[92:95]
	v_mfma_f32_16x16x32_bf16 v[96:99], v[28:31], v[160:163], v[96:99]
	v_mfma_f32_16x16x32_bf16 v[52:55], v[32:35], v[160:163], v[52:55]
	ds_read_b128 v[148:151], v0 offset:4096
	ds_read_b128 v[152:155], v0 offset:5120
	ds_read_b128 v[156:159], v0 offset:6144
	ds_read_b128 v[160:163], v0 offset:7168
	s_waitcnt vmcnt(0) lgkmcnt(0)
	s_barrier
	v_mfma_f32_16x16x32_bf16 v[120:123], v[20:23], v[148:151], v[120:123]
	v_mfma_f32_16x16x32_bf16 v[104:107], v[20:23], v[152:155], v[104:107]
	v_mfma_f32_16x16x32_bf16 v[116:119], v[20:23], v[156:159], v[116:119]
	v_mfma_f32_16x16x32_bf16 v[20:23], v[20:23], v[160:163], v[2:5]
	s_nop 2
	v_mov_b32_e32 v4, v196
	v_mfma_f32_16x16x32_bf16 v[124:127], v[24:27], v[148:151], v[124:127]
	v_and_b32_e32 v0, 64, v4
	v_lshrrev_b32_e32 v3, 1, v4
	v_lshlrev_b32_e32 v0, 1, v0
	v_and_b32_e32 v3, 24, v3
	v_and_b32_e32 v2, 0xfffff8f, v4
	v_add3_u32 v0, 0, v0, v3
	v_mfma_f32_16x16x32_bf16 v[132:135], v[24:27], v[152:155], v[132:135]
	v_mad_u64_u32 v[2:3], s[8:9], v2, s30, v[0:1]
	v_add_u32_e32 v3, 0x1000, v2
	v_mfma_f32_16x16x32_bf16 v[140:143], v[24:27], v[156:159], v[140:143]
	v_add_u32_e32 v5, 0x6000, v2
	v_mfma_f32_16x16x32_bf16 v[6:9], v[24:27], v[160:163], v[6:9]
	v_cvt_pk_bf16_f32 v24, v60, v61
	v_cvt_pk_bf16_f32 v25, v62, v63
	v_mfma_f32_16x16x32_bf16 v[10:13], v[28:31], v[160:163], v[12:15]
	v_mfma_f32_16x16x32_bf16 v[14:17], v[32:35], v[160:163], v[16:19]
	s_nop 3
	v_cvt_pk_bf16_f32 v6, v6, v7
	v_cvt_pk_bf16_f32 v7, v8, v9
	v_cvt_pk_bf16_f32 v18, v56, v57
	v_cvt_pk_bf16_f32 v19, v58, v59
	ds_write2_b64 v2, v[18:19], v[24:25] offset1:4
	v_cvt_pk_bf16_f32 v18, v64, v65
	v_cvt_pk_bf16_f32 v19, v66, v67
	v_cvt_pk_bf16_f32 v24, v36, v37
	v_cvt_pk_bf16_f32 v25, v38, v39
	ds_write2_b64 v2, v[18:19], v[24:25] offset0:8 offset1:12
	v_cvt_pk_bf16_f32 v18, v40, v41
	v_cvt_pk_bf16_f32 v19, v42, v43
	v_cvt_pk_bf16_f32 v24, v68, v69
	v_cvt_pk_bf16_f32 v25, v70, v71
	ds_write2_b64 v3, v[18:19], v[24:25] offset0:32 offset1:36
	v_cvt_pk_bf16_f32 v18, v72, v73
	v_cvt_pk_bf16_f32 v19, v74, v75
	v_cvt_pk_bf16_f32 v24, v44, v45
	v_cvt_pk_bf16_f32 v25, v46, v47
	ds_write2_b64 v3, v[18:19], v[24:25] offset0:40 offset1:44
	v_cvt_pk_bf16_f32 v18, v76, v77
	v_cvt_pk_bf16_f32 v19, v78, v79
	v_cvt_pk_bf16_f32 v24, v80, v81
	v_cvt_pk_bf16_f32 v25, v82, v83
	v_add_u32_e32 v3, 0x2000, v2
	v_mfma_f32_16x16x32_bf16 v[128:131], v[28:31], v[148:151], v[128:131]
	ds_write2_b64 v3, v[18:19], v[24:25] offset0:64 offset1:68
	v_cvt_pk_bf16_f32 v18, v84, v85
	v_cvt_pk_bf16_f32 v19, v86, v87
	v_mfma_f32_16x16x32_bf16 v[100:103], v[32:35], v[148:151], v[100:103]
	v_cvt_pk_bf16_f32 v24, v48, v49
	v_cvt_pk_bf16_f32 v25, v50, v51
	ds_write2_b64 v3, v[18:19], v[24:25] offset0:72 offset1:76
	v_cvt_pk_bf16_f32 v18, v88, v89
	v_cvt_pk_bf16_f32 v19, v90, v91
	v_cvt_pk_bf16_f32 v24, v92, v93
	v_cvt_pk_bf16_f32 v25, v94, v95
	v_add_u32_e32 v3, 0x3000, v2
	v_mfma_f32_16x16x32_bf16 v[136:139], v[28:31], v[152:155], v[136:139]
	ds_write2_b64 v3, v[18:19], v[24:25] offset0:96 offset1:100
	v_cvt_pk_bf16_f32 v18, v96, v97
	v_cvt_pk_bf16_f32 v19, v98, v99
	v_mfma_f32_16x16x32_bf16 v[108:111], v[32:35], v[152:155], v[108:111]
	v_cvt_pk_bf16_f32 v24, v52, v53
	v_cvt_pk_bf16_f32 v25, v54, v55
	ds_write2_b64 v3, v[18:19], v[24:25] offset0:104 offset1:108
	v_cvt_pk_bf16_f32 v18, v120, v121
	v_cvt_pk_bf16_f32 v19, v122, v123
	v_cvt_pk_bf16_f32 v24, v124, v125
	v_cvt_pk_bf16_f32 v25, v126, v127
	v_add_u32_e32 v3, 0x4000, v2
	v_mfma_f32_16x16x32_bf16 v[144:147], v[28:31], v[156:159], v[144:147]
	ds_write2_b64 v3, v[18:19], v[24:25] offset0:128 offset1:132
	v_cvt_pk_bf16_f32 v18, v128, v129
	v_cvt_pk_bf16_f32 v19, v130, v131
	v_mfma_f32_16x16x32_bf16 v[112:115], v[32:35], v[156:159], v[112:115]
	v_cvt_pk_bf16_f32 v24, v100, v101
	v_cvt_pk_bf16_f32 v25, v102, v103
	ds_write2_b64 v3, v[18:19], v[24:25] offset0:136 offset1:140
	v_cvt_pk_bf16_f32 v18, v104, v105
	v_cvt_pk_bf16_f32 v19, v106, v107
	v_cvt_pk_bf16_f32 v24, v132, v133
	v_cvt_pk_bf16_f32 v25, v134, v135
	v_add_u32_e32 v3, 0x5000, v2
	ds_write2_b64 v3, v[18:19], v[24:25] offset0:160 offset1:164
	v_cvt_pk_bf16_f32 v18, v136, v137
	v_cvt_pk_bf16_f32 v19, v138, v139
	v_cvt_pk_bf16_f32 v24, v108, v109
	v_cvt_pk_bf16_f32 v25, v110, v111
	ds_write2_b64 v3, v[18:19], v[24:25] offset0:168 offset1:172
	v_cvt_pk_bf16_f32 v18, v116, v117
	v_cvt_pk_bf16_f32 v19, v118, v119
	v_cvt_pk_bf16_f32 v24, v140, v141
	v_cvt_pk_bf16_f32 v25, v142, v143
	ds_write2_b64 v5, v[18:19], v[24:25] offset0:192 offset1:196
	v_cvt_pk_bf16_f32 v2, v144, v145
	v_cvt_pk_bf16_f32 v3, v146, v147
	v_cvt_pk_bf16_f32 v18, v112, v113
	v_cvt_pk_bf16_f32 v19, v114, v115
	ds_write2_b64 v5, v[2:3], v[18:19] offset0:200 offset1:204
	v_or_b32_e32 v2, 0x70, v4
	v_mad_u64_u32 v[2:3], s[8:9], v2, s30, v[0:1]
	v_cvt_pk_bf16_f32 v18, v20, v21
	v_cvt_pk_bf16_f32 v19, v22, v23
	ds_write2_b64 v2, v[18:19], v[6:7] offset1:4
	v_cvt_pk_bf16_f32 v6, v10, v11
	v_cvt_pk_bf16_f32 v7, v12, v13
	v_cvt_pk_bf16_f32 v8, v14, v15
	v_cvt_pk_bf16_f32 v9, v16, v17
	v_lshlrev_b32_e32 v0, 4, v4
	ds_write2_b64 v2, v[6:7], v[8:9] offset0:8 offset1:12
	v_and_b32_e32 v0, 0xf0, v0
	v_ashrrev_i32_e32 v6, 4, v4
	v_lshl_add_u64 v[2:3], s[0:1], 0, v[0:1]
	v_add_u32_e32 v0, 0, v0
	v_ashrrev_i32_e32 v7, 31, v6
	v_mad_u64_u32 v[8:9], s[0:1], v6, s30, v[0:1]
	v_lshlrev_b64 v[6:7], 11, v[6:7]
	s_waitcnt lgkmcnt(0)
	s_barrier
	v_lshl_add_u64 v[10:11], v[2:3], 0, v[6:7]
	v_mov_b32_e32 v214, 0x8000
	v_mov_b32_e32 v215, 0
	ds_read_b128 v[216:219], v8
	ds_read_b128 v[228:231], v8 offset:4352
	ds_read_b128 v[232:235], v8 offset:8704
	ds_read_b128 v[236:239], v8 offset:13056
	ds_read_b128 v[240:243], v8 offset:17408
	ds_read_b128 v[244:247], v8 offset:21760
	ds_read_b128 v[248:251], v8 offset:26112
	ds_read_b128 v[252:255], v8 offset:30464
	s_waitcnt lgkmcnt(7)
	global_store_dwordx4 v[10:11], v[216:219], off
	v_lshl_add_u64 v[10:11], v[10:11], 0, v[214:215]
	s_waitcnt lgkmcnt(6)
	global_store_dwordx4 v[10:11], v[228:231], off
	v_lshl_add_u64 v[10:11], v[10:11], 0, v[214:215]
	s_waitcnt lgkmcnt(5)
	global_store_dwordx4 v[10:11], v[232:235], off
	v_lshl_add_u64 v[10:11], v[10:11], 0, v[214:215]
	s_waitcnt lgkmcnt(4)
	global_store_dwordx4 v[10:11], v[236:239], off
	v_lshl_add_u64 v[10:11], v[10:11], 0, v[214:215]
	s_waitcnt lgkmcnt(3)
	global_store_dwordx4 v[10:11], v[240:243], off
	v_lshl_add_u64 v[10:11], v[10:11], 0, v[214:215]
	s_waitcnt lgkmcnt(2)
	global_store_dwordx4 v[10:11], v[244:247], off
	v_lshl_add_u64 v[10:11], v[10:11], 0, v[214:215]
	s_waitcnt lgkmcnt(1)
	global_store_dwordx4 v[10:11], v[248:251], off
	v_lshl_add_u64 v[10:11], v[10:11], 0, v[214:215]
	s_waitcnt lgkmcnt(0)
	global_store_dwordx4 v[10:11], v[252:255], off
	v_lshl_add_u64 v[10:11], v[10:11], 0, v[214:215]
	ds_read_b128 v[216:219], v8 offset:34816
	ds_read_b128 v[228:231], v8 offset:39168
	ds_read_b128 v[232:235], v8 offset:43520
	ds_read_b128 v[236:239], v8 offset:47872
	ds_read_b128 v[240:243], v8 offset:52224
	ds_read_b128 v[244:247], v8 offset:56576
	ds_read_b128 v[248:251], v8 offset:60928
	ds_read_b128 v[252:255], v8 offset:65280
	s_waitcnt lgkmcnt(7)
	global_store_dwordx4 v[10:11], v[216:219], off
	v_lshl_add_u64 v[10:11], v[10:11], 0, v[214:215]
	s_waitcnt lgkmcnt(6)
	global_store_dwordx4 v[10:11], v[228:231], off
	v_lshl_add_u64 v[10:11], v[10:11], 0, v[214:215]
	s_waitcnt lgkmcnt(5)
	global_store_dwordx4 v[10:11], v[232:235], off
	v_lshl_add_u64 v[10:11], v[10:11], 0, v[214:215]
	s_waitcnt lgkmcnt(4)
	global_store_dwordx4 v[10:11], v[236:239], off
	v_lshl_add_u64 v[10:11], v[10:11], 0, v[214:215]
	s_waitcnt lgkmcnt(3)
	global_store_dwordx4 v[10:11], v[240:243], off
	v_lshl_add_u64 v[10:11], v[10:11], 0, v[214:215]
	s_waitcnt lgkmcnt(2)
	global_store_dwordx4 v[10:11], v[244:247], off
	v_lshl_add_u64 v[10:11], v[10:11], 0, v[214:215]
	s_waitcnt lgkmcnt(1)
	global_store_dwordx4 v[10:11], v[248:251], off
	v_lshl_add_u64 v[10:11], v[10:11], 0, v[214:215]
	s_waitcnt lgkmcnt(0)
	global_store_dwordx4 v[10:11], v[252:255], off
	s_barrier
	s_branch .LBB0_198
